# rg backward scan writes its outputs to the temp registers so the x-column registers keep zero low halves: high-half LDS reads (no unpack shift) for all tiles after the first
# baseline (speedup 1.0000x reference)
; #define LAS __attribute__((address_space(3)))
; template <bool FINAL>
; __device__ __forceinline__ void rg_item(PREF p, int l, int item, LAS unsigned char* wl, int lane) {
;     ...
;     const int h = item & 7, rest = item >> 3;
;     const int ci = rest < 512 ? 4 + (rest & 255) : ((rest - 512) & 3), b = rest < 512 ? (rest >> 8) : ((rest - 512) >> 2);
;     const int seq_row0 = ci < 4 ? TL + b * 256 : b * 16384;
;     const int t0 = ci < 4 ? ci * 64 : (ci - 4) * 64;
;     const int seqlen = ci < 4 ? 256 : 16384;
;     const int ch = h * 64 + lane;
;     LAS bf16_t* sXc = (LAS bf16_t*)wl;
;     LAS float* stg = (LAS float*)(wl + 9216);
;     {
;         const float cw0 = p.conv_w[(l * 4 + 0) * 512 + ch], cw1 = p.conv_w[(l * 4 + 1) * 512 + ch], cw2 = p.conv_w[(l * 4 + 2) * 512 + ch], cw3 = p.conv_w[(l * 4 + 3) * 512 + ch];
;         const float cb = p.conv_b[l * 512 + ch];
;         float xv[67]; unsigned xr_[67];
; #pragma unroll
;         for (int i = 0; i < 67; ++i) { const int t = t0 - 2 + i; const int tc = t < 0 ? 0 : (t >= seqlen ? seqlen - 1 : t);
;             xr_[i] = P[(size_t)(seq_row0 + tc) * PW + ch]; }
.Lrg7_dec:
	s_add_i32 s15, s11, s10
	s_mul_i32 s36, s9, 0x104
	s_add_i32 s36, s36, s8
	s_lshl_b32 s36, s36, 12
	s_cmp_eq_u32 s10, 0
	s_cselect_b32 s37, 0, -1
	s_add_i32 s38, s10, 64
	s_cmp_eq_u32 s38, s14
	s_cselect_b32 s38, 0, -1
	s_bfe_u32 s44, s44, 0x30006
	s_mul_i32 s44, s44, 0x4800
	v_lshl_or_b32 v234, s7, 6, v233
	v_lshlrev_b32_e32 v235, 2, v234
	v_lshlrev_b32_e32 v234, 1, v234
	v_and_b32_e32 v236, 15, v233
	v_lshrrev_b32_e32 v241, 4, v233
	s_movk_i32 s39, 0x90
	v_mul_u32_u24_e32 v237, 0x90, v236
	v_lshl_add_u32 v237, v241, 4, v237
	v_lshlrev_b32_e32 v238, 7, v236
	v_lshl_add_u32 v238, v241, 4, v238
	v_lshlrev_b32_e32 v239, 10, v241
	v_lshl_add_u32 v239, v236, 2, v239
	v_mov_b32_e32 v241, v238
	v_add_u32_e32 v236, s44, v237
	s_add_i32 s39, s44, 0x2400
	v_add_u32_e32 v237, s39, v239
	v_add_u32_e32 v238, 0x1000, v237
	v_lshl_add_u32 v239, v233, 2, s44
	v_lshl_add_u32 v240, v233, 1, s44
	s_add_i32 s39, s15, -2
	s_mul_hi_i32 s83, s39, 0x1600
	s_mul_i32 s82, s39, 0x1600
	s_waitcnt lgkmcnt(0)
	s_add_u32 s82, s82, s0
	s_addc_u32 s83, s83, s1
	s_add_u32 s82, s82, 0xbc00000
	s_addc_u32 s83, s83, 0
	global_load_ushort v158, v234, s[82:83]
	s_add_u32 s82, s82, 0x1600
	s_addc_u32 s83, s83, 0
	global_load_ushort v159, v234, s[82:83]
	s_add_u32 s82, s82, 0x1600
	s_addc_u32 s83, s83, 0
	global_load_ushort v160, v234, s[82:83]
	s_add_u32 s82, s82, 0x1600
	s_addc_u32 s83, s83, 0
	global_load_ushort v161, v234, s[82:83]
	s_add_u32 s82, s82, 0x1600
	s_addc_u32 s83, s83, 0
	global_load_ushort v162, v234, s[82:83]
	s_add_u32 s82, s82, 0x1600
	s_addc_u32 s83, s83, 0
	global_load_ushort v163, v234, s[82:83]
	s_add_u32 s82, s82, 0x1600
	s_addc_u32 s83, s83, 0
	global_load_ushort v164, v234, s[82:83]
	s_add_u32 s82, s82, 0x1600
	s_addc_u32 s83, s83, 0
	global_load_ushort v165, v234, s[82:83]
	s_add_u32 s82, s82, 0x1600
	s_addc_u32 s83, s83, 0
	global_load_ushort v166, v234, s[82:83]
	s_add_u32 s82, s82, 0x1600
	s_addc_u32 s83, s83, 0
	global_load_ushort v167, v234, s[82:83]
	s_add_u32 s82, s82, 0x1600
	s_addc_u32 s83, s83, 0
	global_load_ushort v168, v234, s[82:83]
	s_add_u32 s82, s82, 0x1600
	s_addc_u32 s83, s83, 0
	global_load_ushort v169, v234, s[82:83]
	s_add_u32 s82, s82, 0x1600
	s_addc_u32 s83, s83, 0
	global_load_ushort v170, v234, s[82:83]
	s_add_u32 s82, s82, 0x1600
	s_addc_u32 s83, s83, 0
	global_load_ushort v171, v234, s[82:83]
	s_add_u32 s82, s82, 0x1600
	s_addc_u32 s83, s83, 0
	global_load_ushort v172, v234, s[82:83]
	s_add_u32 s82, s82, 0x1600
	s_addc_u32 s83, s83, 0
	global_load_ushort v173, v234, s[82:83]
	s_add_u32 s82, s82, 0x1600
	s_addc_u32 s83, s83, 0
	global_load_ushort v174, v234, s[82:83]
	s_add_u32 s82, s82, 0x1600
	s_addc_u32 s83, s83, 0
	global_load_ushort v175, v234, s[82:83]
	s_add_u32 s82, s82, 0x1600
	s_addc_u32 s83, s83, 0
	global_load_ushort v176, v234, s[82:83]
	s_add_u32 s82, s82, 0x1600
	s_addc_u32 s83, s83, 0
	global_load_ushort v177, v234, s[82:83]
	s_add_u32 s82, s82, 0x1600
	s_addc_u32 s83, s83, 0
	global_load_ushort v178, v234, s[82:83]
	s_add_u32 s82, s82, 0x1600
	s_addc_u32 s83, s83, 0
	global_load_ushort v179, v234, s[82:83]
	s_add_u32 s82, s82, 0x1600
	s_addc_u32 s83, s83, 0
	global_load_ushort v180, v234, s[82:83]
	s_add_u32 s82, s82, 0x1600
	s_addc_u32 s83, s83, 0
	global_load_ushort v181, v234, s[82:83]
	s_add_u32 s82, s82, 0x1600
	s_addc_u32 s83, s83, 0
	global_load_ushort v182, v234, s[82:83]
	s_add_u32 s82, s82, 0x1600
	s_addc_u32 s83, s83, 0
	global_load_ushort v183, v234, s[82:83]
	s_add_u32 s82, s82, 0x1600
	s_addc_u32 s83, s83, 0
	global_load_ushort v184, v234, s[82:83]
	s_add_u32 s82, s82, 0x1600
	s_addc_u32 s83, s83, 0
	global_load_ushort v185, v234, s[82:83]
	s_add_u32 s82, s82, 0x1600
	s_addc_u32 s83, s83, 0
	global_load_ushort v186, v234, s[82:83]
	s_add_u32 s82, s82, 0x1600
	s_addc_u32 s83, s83, 0
	global_load_ushort v187, v234, s[82:83]
	s_add_u32 s82, s82, 0x1600
	s_addc_u32 s83, s83, 0
	global_load_ushort v188, v234, s[82:83]
	s_add_u32 s82, s82, 0x1600
	s_addc_u32 s83, s83, 0
	global_load_ushort v189, v234, s[82:83]
	s_add_u32 s82, s82, 0x1600
	s_addc_u32 s83, s83, 0
	global_load_ushort v190, v234, s[82:83]
	s_add_u32 s82, s82, 0x1600
	s_addc_u32 s83, s83, 0
	global_load_ushort v191, v234, s[82:83]
	s_add_u32 s82, s82, 0x1600
	s_addc_u32 s83, s83, 0
	global_load_ushort v192, v234, s[82:83]
	s_add_u32 s82, s82, 0x1600
	s_addc_u32 s83, s83, 0
	global_load_ushort v193, v234, s[82:83]
	s_add_u32 s82, s82, 0x1600
	s_addc_u32 s83, s83, 0
	global_load_ushort v194, v234, s[82:83]
	s_add_u32 s82, s82, 0x1600
	s_addc_u32 s83, s83, 0
	global_load_ushort v195, v234, s[82:83]
	s_add_u32 s82, s82, 0x1600
	s_addc_u32 s83, s83, 0
	global_load_ushort v196, v234, s[82:83]
	s_add_u32 s82, s82, 0x1600
	s_addc_u32 s83, s83, 0
	global_load_ushort v197, v234, s[82:83]
	s_add_u32 s82, s82, 0x1600
	s_addc_u32 s83, s83, 0
	global_load_ushort v198, v234, s[82:83]
	s_add_u32 s82, s82, 0x1600
	s_addc_u32 s83, s83, 0
	global_load_ushort v199, v234, s[82:83]
	s_add_u32 s82, s82, 0x1600
	s_addc_u32 s83, s83, 0
	global_load_ushort v200, v234, s[82:83]
	s_add_u32 s82, s82, 0x1600
	s_addc_u32 s83, s83, 0
	global_load_ushort v201, v234, s[82:83]
	s_add_u32 s82, s82, 0x1600
	s_addc_u32 s83, s83, 0
	global_load_ushort v202, v234, s[82:83]
	s_add_u32 s82, s82, 0x1600
	s_addc_u32 s83, s83, 0
	global_load_ushort v203, v234, s[82:83]
	s_add_u32 s82, s82, 0x1600
	s_addc_u32 s83, s83, 0
	global_load_ushort v204, v234, s[82:83]
	s_add_u32 s82, s82, 0x1600
	s_addc_u32 s83, s83, 0
	global_load_ushort v205, v234, s[82:83]
	s_add_u32 s82, s82, 0x1600
	s_addc_u32 s83, s83, 0
	global_load_ushort v206, v234, s[82:83]
	s_add_u32 s82, s82, 0x1600
; __device__ __forceinline__ float rcpf_(float x) { return __builtin_amdgcn_rcpf(x); }
; template <bool FINAL, int D>
; __device__ __forceinline__ void rg_dir(PREF p, int l, int h, int ch, int sidx, int rowbase  , LAS bf16_t* sXc, LAS float* stg, int lane) {
;     ...
;     const bf16_t* wr_ = WgT + (size_t)(((l * 2 + D) * 2 + 0) * 8 + h) * 4096; const bf16_t* wi_ = WgT + (size_t)(((l * 2 + D) * 2 + 1) * 8 + h) * 4096;
;     const float ba = p.rg_ba[(l * 2 + D) * 512 + ch], bi = p.rg_bi[(l * 2 + D) * 512 + ch], lam = p.rg_lam[(l * 2 + D) * 512 + ch];
;     const float e_ = __expf(-lam), u_ = 1.f + e_;
;     const float l1p = (u_ == 1.f) ? e_ : __logf(u_) * e_ * rcpf_(u_ - 1.f);
;     const float sp8 = -8.f * 1.4426950408889634f * l1p;
;     float hc = FINAL ? RGC[sidx] : 0.f, Ap = 1.f;
;     bf16x8 Br[4][2], Bi[4][2];
; #pragma unroll
;     for (int nt = 0; nt < 4; ++nt) { const int o0 = (nt * 16 + (lane & 15)) * 64 + (lane >> 4) * 8;
;         Br[nt][0] = *(const bf16x8*)(wr_ + o0); Br[nt][1] = *(const bf16x8*)(wr_ + o0 + 32); Bi[nt][0] = *(const bf16x8*)(wi_ + o0); Bi[nt][1] = *(const bf16x8*)(wi_ + o0 + 32); }
; template <bool FINAL>
; __device__ __forceinline__ void rg_item(PREF p, int l, int item, LAS unsigned char* wl, int lane) {
;     ...
;         const float cw0 = p.conv_w[(l * 4 + 0) * 512 + ch], cw1 = p.conv_w[(l * 4 + 1) * 512 + ch], cw2 = p.conv_w[(l * 4 + 2) * 512 + ch], cw3 = p.conv_w[(l * 4 + 3) * 512 + ch];
;         const float cb = p.conv_b[l * 512 + ch];
;         float xv[67]; unsigned xr_[67];
; #pragma unroll
;         for (int i = 0; i < 67; ++i) { const int t = t0 - 2 + i; const int tc = t < 0 ? 0 : (t >= seqlen ? seqlen - 1 : t);
;             xr_[i] = P[(size_t)(seq_row0 + tc) * PW + ch]; }
;         __builtin_amdgcn_sched_barrier(0);
; #pragma unroll
;         for (int i = 0; i < 67; ++i) { const int t = t0 - 2 + i; const int tc = t < 0 ? 0 : (t >= seqlen ? seqlen - 1 : t); xv[i] = (t == tc) ? bf2f(xr_[i]) : 0.f; }
	s_addc_u32 s83, s83, 0
	global_load_ushort v207, v234, s[82:83]
	s_add_u32 s82, s82, 0x1600
	s_addc_u32 s83, s83, 0
	global_load_ushort v208, v234, s[82:83]
	s_add_u32 s82, s82, 0x1600
	s_addc_u32 s83, s83, 0
	global_load_ushort v209, v234, s[82:83]
	s_add_u32 s82, s82, 0x1600
	s_addc_u32 s83, s83, 0
	global_load_ushort v210, v234, s[82:83]
	s_add_u32 s82, s82, 0x1600
	s_addc_u32 s83, s83, 0
	global_load_ushort v211, v234, s[82:83]
	s_add_u32 s82, s82, 0x1600
	s_addc_u32 s83, s83, 0
	global_load_ushort v212, v234, s[82:83]
	s_add_u32 s82, s82, 0x1600
	s_addc_u32 s83, s83, 0
	global_load_ushort v213, v234, s[82:83]
	s_add_u32 s82, s82, 0x1600
	s_addc_u32 s83, s83, 0
	global_load_ushort v214, v234, s[82:83]
	s_add_u32 s82, s82, 0x1600
	s_addc_u32 s83, s83, 0
	global_load_ushort v215, v234, s[82:83]
	s_add_u32 s82, s82, 0x1600
	s_addc_u32 s83, s83, 0
	global_load_ushort v216, v234, s[82:83]
	s_add_u32 s82, s82, 0x1600
	s_addc_u32 s83, s83, 0
	global_load_ushort v217, v234, s[82:83]
	s_add_u32 s82, s82, 0x1600
	s_addc_u32 s83, s83, 0
	global_load_ushort v218, v234, s[82:83]
	s_add_u32 s82, s82, 0x1600
	s_addc_u32 s83, s83, 0
	global_load_ushort v219, v234, s[82:83]
	s_add_u32 s82, s82, 0x1600
	s_addc_u32 s83, s83, 0
	global_load_ushort v222, v234, s[82:83]
	s_add_u32 s82, s82, 0x1600
	s_addc_u32 s83, s83, 0
	global_load_ushort v223, v234, s[82:83]
	s_add_u32 s82, s82, 0x1600
	s_addc_u32 s83, s83, 0
	global_load_ushort v140, v234, s[82:83]
	s_add_u32 s82, s82, 0x1600
	s_addc_u32 s83, s83, 0
	global_load_ushort v141, v234, s[82:83]
	s_add_u32 s82, s82, 0x1600
	s_addc_u32 s83, s83, 0
	global_load_ushort v232, v234, s[82:83]
	s_lshl_b32 s39, s47, 13
	s_add_u32 s72, s72, s39
	s_addc_u32 s73, s73, 0
	global_load_dword v40, v235, s[72:73]
	global_load_dword v41, v235, s[72:73] offset:2048
	s_add_u32 s72, s72, 0x1000
	s_addc_u32 s73, s73, 0
	global_load_dword v42, v235, s[72:73]
	global_load_dword v43, v235, s[72:73] offset:2048
	s_lshl_b32 s39, s47, 11
	s_add_u32 s74, s74, s39
	s_addc_u32 s75, s75, 0
	global_load_dword v44, v235, s[74:75]
	s_lshl_b32 s39, s47, 12
	s_add_u32 s76, s76, s39
	s_addc_u32 s77, s77, 0
	s_add_u32 s78, s78, s39
	s_addc_u32 s79, s79, 0
	s_add_u32 s80, s80, s39
	s_addc_u32 s81, s81, 0
	s_add_u32 s96, s0, 0xa00000
	s_addc_u32 s97, s1, 0
	s_add_u32 s96, s96, s36
	s_addc_u32 s97, s97, 0
	s_lshl_b32 s39, s47, 5
	s_add_i32 s39, s39, s7
	s_lshl_b32 s39, s39, 13
	s_add_u32 s92, s0, 0x300000
	s_addc_u32 s93, s1, 0
	s_add_u32 s92, s92, s39
	s_addc_u32 s93, s93, 0
	global_load_dword v45, v235, s[76:77]
	global_load_dword v46, v235, s[78:79]
	global_load_dword v47, v235, s[80:81]
	global_load_dword v250, v235, s[96:97]
	s_add_u32 s90, s92, 0x0
	s_addc_u32 s91, s93, 0
	global_load_dwordx4 v[80:83], v241, s[90:91]
	global_load_dwordx4 v[84:87], v241, s[90:91] offset:64
	global_load_dwordx4 v[88:91], v241, s[90:91] offset:2048
	global_load_dwordx4 v[92:95], v241, s[90:91] offset:2112
	s_add_u32 s90, s92, 0x1000
	s_addc_u32 s91, s93, 0
	global_load_dwordx4 v[96:99], v241, s[90:91]
	global_load_dwordx4 v[100:103], v241, s[90:91] offset:64
	global_load_dwordx4 v[104:107], v241, s[90:91] offset:2048
	global_load_dwordx4 v[108:111], v241, s[90:91] offset:2112
	s_add_u32 s90, s92, 0x10000
	s_addc_u32 s91, s93, 0
	global_load_dwordx4 v[112:115], v241, s[90:91]
	global_load_dwordx4 v[116:119], v241, s[90:91] offset:64
	global_load_dwordx4 v[120:123], v241, s[90:91] offset:2048
	global_load_dwordx4 v[124:127], v241, s[90:91] offset:2112
	s_add_u32 s90, s92, 0x11000
	s_addc_u32 s91, s93, 0
	global_load_dwordx4 v[128:131], v241, s[90:91]
	global_load_dwordx4 v[132:135], v241, s[90:91] offset:64
	global_load_dwordx4 v[136:139], v241, s[90:91] offset:2048
	global_load_dwordx4 v[228:231], v241, s[90:91] offset:2112
	s_waitcnt vmcnt(20)
	v_lshlrev_b32_e32 v158, 16, v158
	v_lshlrev_b32_e32 v159, 16, v159
	v_lshlrev_b32_e32 v160, 16, v160
	v_lshlrev_b32_e32 v161, 16, v161
	v_lshlrev_b32_e32 v162, 16, v162
	v_lshlrev_b32_e32 v163, 16, v163
	v_lshlrev_b32_e32 v164, 16, v164
	v_lshlrev_b32_e32 v165, 16, v165
	v_lshlrev_b32_e32 v166, 16, v166
	v_lshlrev_b32_e32 v167, 16, v167
	v_lshlrev_b32_e32 v168, 16, v168
	v_lshlrev_b32_e32 v169, 16, v169
	v_lshlrev_b32_e32 v170, 16, v170
	v_lshlrev_b32_e32 v171, 16, v171
	v_lshlrev_b32_e32 v172, 16, v172
	v_lshlrev_b32_e32 v173, 16, v173
	v_lshlrev_b32_e32 v174, 16, v174
	v_lshlrev_b32_e32 v175, 16, v175
	v_lshlrev_b32_e32 v176, 16, v176
	v_lshlrev_b32_e32 v177, 16, v177
	v_lshlrev_b32_e32 v178, 16, v178
	v_lshlrev_b32_e32 v179, 16, v179
	v_lshlrev_b32_e32 v180, 16, v180
	v_lshlrev_b32_e32 v181, 16, v181
	v_lshlrev_b32_e32 v182, 16, v182
	v_lshlrev_b32_e32 v183, 16, v183
	v_lshlrev_b32_e32 v184, 16, v184
	v_lshlrev_b32_e32 v185, 16, v185
	v_lshlrev_b32_e32 v186, 16, v186
	v_lshlrev_b32_e32 v187, 16, v187
	v_lshlrev_b32_e32 v188, 16, v188
	v_lshlrev_b32_e32 v189, 16, v189
	v_lshlrev_b32_e32 v190, 16, v190
	v_lshlrev_b32_e32 v191, 16, v191
	v_lshlrev_b32_e32 v192, 16, v192
	v_lshlrev_b32_e32 v193, 16, v193
	v_lshlrev_b32_e32 v194, 16, v194
	v_lshlrev_b32_e32 v195, 16, v195
	v_lshlrev_b32_e32 v196, 16, v196
	v_lshlrev_b32_e32 v197, 16, v197
	v_lshlrev_b32_e32 v198, 16, v198
	v_lshlrev_b32_e32 v199, 16, v199
	v_lshlrev_b32_e32 v200, 16, v200
	v_lshlrev_b32_e32 v201, 16, v201
	v_lshlrev_b32_e32 v202, 16, v202
	v_lshlrev_b32_e32 v203, 16, v203
	v_lshlrev_b32_e32 v204, 16, v204
	v_lshlrev_b32_e32 v205, 16, v205
	v_lshlrev_b32_e32 v206, 16, v206
	v_lshlrev_b32_e32 v207, 16, v207
	v_lshlrev_b32_e32 v208, 16, v208
	v_lshlrev_b32_e32 v209, 16, v209
	v_lshlrev_b32_e32 v210, 16, v210
	v_lshlrev_b32_e32 v211, 16, v211
; __device__ __forceinline__ unsigned f2bf(float f) { unsigned r; asm("v_cvt_pk_bf16_f32 %0, %1, %1" : "=v"(r) : "v"(f)); return r & 0xffffu; }
; template <bool FINAL>
; __device__ __forceinline__ void rg_item(PREF p, int l, int item, LAS unsigned char* wl, int lane) {
;     ...
;         for (int i = 0; i < 67; ++i) { const int t = t0 - 2 + i; const int tc = t < 0 ? 0 : (t >= seqlen ? seqlen - 1 : t); xv[i] = (t == tc) ? bf2f(xr_[i]) : 0.f; }
; #pragma unroll
;         for (int tt = 0; tt < 64; ++tt) { const float xc = xv[tt] * cw0 + xv[tt + 1] * cw1 + xv[tt + 2] * cw2 + xv[tt + 3] * cw3 + cb; sXc[tt * 72 + lane] = (bf16_t)f2bf(xc); }
	v_lshlrev_b32_e32 v212, 16, v212
	v_lshlrev_b32_e32 v213, 16, v213
	v_lshlrev_b32_e32 v214, 16, v214
	v_lshlrev_b32_e32 v215, 16, v215
	v_lshlrev_b32_e32 v216, 16, v216
	v_lshlrev_b32_e32 v217, 16, v217
	v_lshlrev_b32_e32 v218, 16, v218
	v_lshlrev_b32_e32 v219, 16, v219
	v_lshlrev_b32_e32 v222, 16, v222
	v_lshlrev_b32_e32 v223, 16, v223
	v_lshlrev_b32_e32 v140, 16, v140
	v_lshlrev_b32_e32 v141, 16, v141
	v_lshlrev_b32_e32 v232, 16, v232
	v_and_b32_e32 v158, s37, v158
	v_and_b32_e32 v159, s37, v159
	v_and_b32_e32 v232, s38, v232
	v_mul_f32_e32 v32, v41, v159
	v_mul_f32_e32 v33, v41, v160
	v_mul_f32_e32 v34, v41, v161
	v_mul_f32_e32 v35, v41, v162
	v_mul_f32_e32 v36, v41, v163
	v_mul_f32_e32 v37, v41, v164
	v_mul_f32_e32 v38, v41, v165
	v_mul_f32_e32 v39, v41, v166
	v_fmac_f32_e32 v32, v40, v158
	v_fmac_f32_e32 v33, v40, v159
	v_fmac_f32_e32 v34, v40, v160
	v_fmac_f32_e32 v35, v40, v161
	v_fmac_f32_e32 v36, v40, v162
	v_fmac_f32_e32 v37, v40, v163
	v_fmac_f32_e32 v38, v40, v164
	v_fmac_f32_e32 v39, v40, v165
	v_fmac_f32_e32 v32, v42, v160
	v_fmac_f32_e32 v33, v42, v161
	v_fmac_f32_e32 v34, v42, v162
	v_fmac_f32_e32 v35, v42, v163
	v_fmac_f32_e32 v36, v42, v164
	v_fmac_f32_e32 v37, v42, v165
	v_fmac_f32_e32 v38, v42, v166
	v_fmac_f32_e32 v39, v42, v167
	v_fmac_f32_e32 v32, v43, v161
	v_fmac_f32_e32 v33, v43, v162
	v_fmac_f32_e32 v34, v43, v163
	v_fmac_f32_e32 v35, v43, v164
	v_fmac_f32_e32 v36, v43, v165
	v_fmac_f32_e32 v37, v43, v166
	v_fmac_f32_e32 v38, v43, v167
	v_fmac_f32_e32 v39, v43, v168
	v_add_f32_e32 v32, v44, v32
	v_add_f32_e32 v33, v44, v33
	v_add_f32_e32 v34, v44, v34
	v_add_f32_e32 v35, v44, v35
	v_add_f32_e32 v36, v44, v36
	v_add_f32_e32 v37, v44, v37
	v_add_f32_e32 v38, v44, v38
	v_add_f32_e32 v39, v44, v39
	v_cvt_pk_bf16_f32 v32, v32, v33
	v_cvt_pk_bf16_f32 v34, v34, v35
	v_cvt_pk_bf16_f32 v36, v36, v37
	v_cvt_pk_bf16_f32 v38, v38, v39
	ds_write_b16 v240, v32 offset:0
	ds_write_b16_d16_hi v240, v32 offset:144
	ds_write_b16 v240, v34 offset:288
	ds_write_b16_d16_hi v240, v34 offset:432
	ds_write_b16 v240, v36 offset:576
	ds_write_b16_d16_hi v240, v36 offset:720
	ds_write_b16 v240, v38 offset:864
	ds_write_b16_d16_hi v240, v38 offset:1008
	v_mul_f32_e32 v32, v41, v167
	v_mul_f32_e32 v33, v41, v168
	v_mul_f32_e32 v34, v41, v169
	v_mul_f32_e32 v35, v41, v170
	v_mul_f32_e32 v36, v41, v171
	v_mul_f32_e32 v37, v41, v172
	v_mul_f32_e32 v38, v41, v173
	v_mul_f32_e32 v39, v41, v174
	v_fmac_f32_e32 v32, v40, v166
	v_fmac_f32_e32 v33, v40, v167
	v_fmac_f32_e32 v34, v40, v168
	v_fmac_f32_e32 v35, v40, v169
	v_fmac_f32_e32 v36, v40, v170
	v_fmac_f32_e32 v37, v40, v171
	v_fmac_f32_e32 v38, v40, v172
	v_fmac_f32_e32 v39, v40, v173
	v_fmac_f32_e32 v32, v42, v168
	v_fmac_f32_e32 v33, v42, v169
	v_fmac_f32_e32 v34, v42, v170
	v_fmac_f32_e32 v35, v42, v171
	v_fmac_f32_e32 v36, v42, v172
	v_fmac_f32_e32 v37, v42, v173
	v_fmac_f32_e32 v38, v42, v174
	v_fmac_f32_e32 v39, v42, v175
	v_fmac_f32_e32 v32, v43, v169
	v_fmac_f32_e32 v33, v43, v170
	v_fmac_f32_e32 v34, v43, v171
	v_fmac_f32_e32 v35, v43, v172
	v_fmac_f32_e32 v36, v43, v173
	v_fmac_f32_e32 v37, v43, v174
	v_fmac_f32_e32 v38, v43, v175
	v_fmac_f32_e32 v39, v43, v176
	v_add_f32_e32 v32, v44, v32
	v_add_f32_e32 v33, v44, v33
	v_add_f32_e32 v34, v44, v34
	v_add_f32_e32 v35, v44, v35
	v_add_f32_e32 v36, v44, v36
	v_add_f32_e32 v37, v44, v37
	v_add_f32_e32 v38, v44, v38
	v_add_f32_e32 v39, v44, v39
	v_cvt_pk_bf16_f32 v32, v32, v33
	v_cvt_pk_bf16_f32 v34, v34, v35
	v_cvt_pk_bf16_f32 v36, v36, v37
	v_cvt_pk_bf16_f32 v38, v38, v39
	ds_write_b16 v240, v32 offset:1152
	ds_write_b16_d16_hi v240, v32 offset:1296
	ds_write_b16 v240, v34 offset:1440
	ds_write_b16_d16_hi v240, v34 offset:1584
	ds_write_b16 v240, v36 offset:1728
	ds_write_b16_d16_hi v240, v36 offset:1872
	ds_write_b16 v240, v38 offset:2016
	ds_write_b16_d16_hi v240, v38 offset:2160
	v_mul_f32_e32 v32, v41, v175
	v_mul_f32_e32 v33, v41, v176
	v_mul_f32_e32 v34, v41, v177
	v_mul_f32_e32 v35, v41, v178
	v_mul_f32_e32 v36, v41, v179
	v_mul_f32_e32 v37, v41, v180
	v_mul_f32_e32 v38, v41, v181
	v_mul_f32_e32 v39, v41, v182
	v_fmac_f32_e32 v32, v40, v174
	v_fmac_f32_e32 v33, v40, v175
	v_fmac_f32_e32 v34, v40, v176
	v_fmac_f32_e32 v35, v40, v177
	v_fmac_f32_e32 v36, v40, v178
	v_fmac_f32_e32 v37, v40, v179
	v_fmac_f32_e32 v38, v40, v180
	v_fmac_f32_e32 v39, v40, v181
	v_fmac_f32_e32 v32, v42, v176
	v_fmac_f32_e32 v33, v42, v177
	v_fmac_f32_e32 v34, v42, v178
	v_fmac_f32_e32 v35, v42, v179
	v_fmac_f32_e32 v36, v42, v180
	v_fmac_f32_e32 v37, v42, v181
	v_fmac_f32_e32 v38, v42, v182
	v_fmac_f32_e32 v39, v42, v183
	v_fmac_f32_e32 v32, v43, v177
	v_fmac_f32_e32 v33, v43, v178
	v_fmac_f32_e32 v34, v43, v179
	v_fmac_f32_e32 v35, v43, v180
	v_fmac_f32_e32 v36, v43, v181
	v_fmac_f32_e32 v37, v43, v182
	v_fmac_f32_e32 v38, v43, v183
	v_fmac_f32_e32 v39, v43, v184
	v_add_f32_e32 v32, v44, v32
	v_add_f32_e32 v33, v44, v33
	v_add_f32_e32 v34, v44, v34
	v_add_f32_e32 v35, v44, v35
	v_add_f32_e32 v36, v44, v36
	v_add_f32_e32 v37, v44, v37
	v_add_f32_e32 v38, v44, v38
	v_add_f32_e32 v39, v44, v39
	v_cvt_pk_bf16_f32 v32, v32, v33
	v_cvt_pk_bf16_f32 v34, v34, v35
	v_cvt_pk_bf16_f32 v36, v36, v37
	v_cvt_pk_bf16_f32 v38, v38, v39
	ds_write_b16 v240, v32 offset:2304
	ds_write_b16_d16_hi v240, v32 offset:2448
	ds_write_b16 v240, v34 offset:2592
	ds_write_b16_d16_hi v240, v34 offset:2736
	ds_write_b16 v240, v36 offset:2880
	ds_write_b16_d16_hi v240, v36 offset:3024
	ds_write_b16 v240, v38 offset:3168
	ds_write_b16_d16_hi v240, v38 offset:3312
	v_mul_f32_e32 v32, v41, v183
	v_mul_f32_e32 v33, v41, v184
	v_mul_f32_e32 v34, v41, v185
	v_mul_f32_e32 v35, v41, v186
; __device__ __forceinline__ unsigned f2bf(float f) { unsigned r; asm("v_cvt_pk_bf16_f32 %0, %1, %1" : "=v"(r) : "v"(f)); return r & 0xffffu; }
; template <bool FINAL>
; __device__ __forceinline__ void rg_item(PREF p, int l, int item, LAS unsigned char* wl, int lane) {
;     ...
;         for (int tt = 0; tt < 64; ++tt) { const float xc = xv[tt] * cw0 + xv[tt + 1] * cw1 + xv[tt + 2] * cw2 + xv[tt + 3] * cw3 + cb; sXc[tt * 72 + lane] = (bf16_t)f2bf(xc); }
	v_mul_f32_e32 v36, v41, v187
	v_mul_f32_e32 v37, v41, v188
	v_mul_f32_e32 v38, v41, v189
	v_mul_f32_e32 v39, v41, v190
	v_fmac_f32_e32 v32, v40, v182
	v_fmac_f32_e32 v33, v40, v183
	v_fmac_f32_e32 v34, v40, v184
	v_fmac_f32_e32 v35, v40, v185
	v_fmac_f32_e32 v36, v40, v186
	v_fmac_f32_e32 v37, v40, v187
	v_fmac_f32_e32 v38, v40, v188
	v_fmac_f32_e32 v39, v40, v189
	v_fmac_f32_e32 v32, v42, v184
	v_fmac_f32_e32 v33, v42, v185
	v_fmac_f32_e32 v34, v42, v186
	v_fmac_f32_e32 v35, v42, v187
	v_fmac_f32_e32 v36, v42, v188
	v_fmac_f32_e32 v37, v42, v189
	v_fmac_f32_e32 v38, v42, v190
	v_fmac_f32_e32 v39, v42, v191
	v_fmac_f32_e32 v32, v43, v185
	v_fmac_f32_e32 v33, v43, v186
	v_fmac_f32_e32 v34, v43, v187
	v_fmac_f32_e32 v35, v43, v188
	v_fmac_f32_e32 v36, v43, v189
	v_fmac_f32_e32 v37, v43, v190
	v_fmac_f32_e32 v38, v43, v191
	v_fmac_f32_e32 v39, v43, v192
	v_add_f32_e32 v32, v44, v32
	v_add_f32_e32 v33, v44, v33
	v_add_f32_e32 v34, v44, v34
	v_add_f32_e32 v35, v44, v35
	v_add_f32_e32 v36, v44, v36
	v_add_f32_e32 v37, v44, v37
	v_add_f32_e32 v38, v44, v38
	v_add_f32_e32 v39, v44, v39
	v_cvt_pk_bf16_f32 v32, v32, v33
	v_cvt_pk_bf16_f32 v34, v34, v35
	v_cvt_pk_bf16_f32 v36, v36, v37
	v_cvt_pk_bf16_f32 v38, v38, v39
	ds_write_b16 v240, v32 offset:3456
	ds_write_b16_d16_hi v240, v32 offset:3600
	ds_write_b16 v240, v34 offset:3744
	ds_write_b16_d16_hi v240, v34 offset:3888
	ds_write_b16 v240, v36 offset:4032
	ds_write_b16_d16_hi v240, v36 offset:4176
	ds_write_b16 v240, v38 offset:4320
	ds_write_b16_d16_hi v240, v38 offset:4464
	v_mul_f32_e32 v32, v41, v191
	v_mul_f32_e32 v33, v41, v192
	v_mul_f32_e32 v34, v41, v193
	v_mul_f32_e32 v35, v41, v194
	v_mul_f32_e32 v36, v41, v195
	v_mul_f32_e32 v37, v41, v196
	v_mul_f32_e32 v38, v41, v197
	v_mul_f32_e32 v39, v41, v198
	v_fmac_f32_e32 v32, v40, v190
	v_fmac_f32_e32 v33, v40, v191
	v_fmac_f32_e32 v34, v40, v192
	v_fmac_f32_e32 v35, v40, v193
	v_fmac_f32_e32 v36, v40, v194
	v_fmac_f32_e32 v37, v40, v195
	v_fmac_f32_e32 v38, v40, v196
	v_fmac_f32_e32 v39, v40, v197
	v_fmac_f32_e32 v32, v42, v192
	v_fmac_f32_e32 v33, v42, v193
	v_fmac_f32_e32 v34, v42, v194
	v_fmac_f32_e32 v35, v42, v195
	v_fmac_f32_e32 v36, v42, v196
	v_fmac_f32_e32 v37, v42, v197
	v_fmac_f32_e32 v38, v42, v198
	v_fmac_f32_e32 v39, v42, v199
	v_fmac_f32_e32 v32, v43, v193
	v_fmac_f32_e32 v33, v43, v194
	v_fmac_f32_e32 v34, v43, v195
	v_fmac_f32_e32 v35, v43, v196
	v_fmac_f32_e32 v36, v43, v197
	v_fmac_f32_e32 v37, v43, v198
	v_fmac_f32_e32 v38, v43, v199
	v_fmac_f32_e32 v39, v43, v200
	v_add_f32_e32 v32, v44, v32
	v_add_f32_e32 v33, v44, v33
	v_add_f32_e32 v34, v44, v34
	v_add_f32_e32 v35, v44, v35
	v_add_f32_e32 v36, v44, v36
	v_add_f32_e32 v37, v44, v37
	v_add_f32_e32 v38, v44, v38
	v_add_f32_e32 v39, v44, v39
	v_cvt_pk_bf16_f32 v32, v32, v33
	v_cvt_pk_bf16_f32 v34, v34, v35
	v_cvt_pk_bf16_f32 v36, v36, v37
	v_cvt_pk_bf16_f32 v38, v38, v39
	ds_write_b16 v240, v32 offset:4608
	ds_write_b16_d16_hi v240, v32 offset:4752
	ds_write_b16 v240, v34 offset:4896
	ds_write_b16_d16_hi v240, v34 offset:5040
	ds_write_b16 v240, v36 offset:5184
	ds_write_b16_d16_hi v240, v36 offset:5328
	ds_write_b16 v240, v38 offset:5472
	ds_write_b16_d16_hi v240, v38 offset:5616
	v_mul_f32_e32 v32, v41, v199
	v_mul_f32_e32 v33, v41, v200
	v_mul_f32_e32 v34, v41, v201
	v_mul_f32_e32 v35, v41, v202
	v_mul_f32_e32 v36, v41, v203
	v_mul_f32_e32 v37, v41, v204
	v_mul_f32_e32 v38, v41, v205
	v_mul_f32_e32 v39, v41, v206
	v_fmac_f32_e32 v32, v40, v198
	v_fmac_f32_e32 v33, v40, v199
	v_fmac_f32_e32 v34, v40, v200
	v_fmac_f32_e32 v35, v40, v201
	v_fmac_f32_e32 v36, v40, v202
	v_fmac_f32_e32 v37, v40, v203
	v_fmac_f32_e32 v38, v40, v204
	v_fmac_f32_e32 v39, v40, v205
	v_fmac_f32_e32 v32, v42, v200
	v_fmac_f32_e32 v33, v42, v201
	v_fmac_f32_e32 v34, v42, v202
	v_fmac_f32_e32 v35, v42, v203
	v_fmac_f32_e32 v36, v42, v204
	v_fmac_f32_e32 v37, v42, v205
	v_fmac_f32_e32 v38, v42, v206
	v_fmac_f32_e32 v39, v42, v207
	v_fmac_f32_e32 v32, v43, v201
	v_fmac_f32_e32 v33, v43, v202
	v_fmac_f32_e32 v34, v43, v203
	v_fmac_f32_e32 v35, v43, v204
	v_fmac_f32_e32 v36, v43, v205
	v_fmac_f32_e32 v37, v43, v206
	v_fmac_f32_e32 v38, v43, v207
	v_fmac_f32_e32 v39, v43, v208
	v_add_f32_e32 v32, v44, v32
	v_add_f32_e32 v33, v44, v33
	v_add_f32_e32 v34, v44, v34
	v_add_f32_e32 v35, v44, v35
	v_add_f32_e32 v36, v44, v36
	v_add_f32_e32 v37, v44, v37
	v_add_f32_e32 v38, v44, v38
	v_add_f32_e32 v39, v44, v39
	v_cvt_pk_bf16_f32 v32, v32, v33
	v_cvt_pk_bf16_f32 v34, v34, v35
	v_cvt_pk_bf16_f32 v36, v36, v37
	v_cvt_pk_bf16_f32 v38, v38, v39
	ds_write_b16 v240, v32 offset:5760
	ds_write_b16_d16_hi v240, v32 offset:5904
	ds_write_b16 v240, v34 offset:6048
	ds_write_b16_d16_hi v240, v34 offset:6192
	ds_write_b16 v240, v36 offset:6336
	ds_write_b16_d16_hi v240, v36 offset:6480
	ds_write_b16 v240, v38 offset:6624
	ds_write_b16_d16_hi v240, v38 offset:6768
	v_mul_f32_e32 v32, v41, v207
	v_mul_f32_e32 v33, v41, v208
	v_mul_f32_e32 v34, v41, v209
	v_mul_f32_e32 v35, v41, v210
	v_mul_f32_e32 v36, v41, v211
	v_mul_f32_e32 v37, v41, v212
	v_mul_f32_e32 v38, v41, v213
	v_mul_f32_e32 v39, v41, v214
	v_fmac_f32_e32 v32, v40, v206
	v_fmac_f32_e32 v33, v40, v207
	v_fmac_f32_e32 v34, v40, v208
	v_fmac_f32_e32 v35, v40, v209
	v_fmac_f32_e32 v36, v40, v210
	v_fmac_f32_e32 v37, v40, v211
	v_fmac_f32_e32 v38, v40, v212
	v_fmac_f32_e32 v39, v40, v213
	v_fmac_f32_e32 v32, v42, v208
	v_fmac_f32_e32 v33, v42, v209
	v_fmac_f32_e32 v34, v42, v210
	v_fmac_f32_e32 v35, v42, v211
	v_fmac_f32_e32 v36, v42, v212
	v_fmac_f32_e32 v37, v42, v213
	v_fmac_f32_e32 v38, v42, v214
	v_fmac_f32_e32 v39, v42, v215
	v_fmac_f32_e32 v32, v43, v209
; __device__ __forceinline__ unsigned f2bf(float f) { unsigned r; asm("v_cvt_pk_bf16_f32 %0, %1, %1" : "=v"(r) : "v"(f)); return r & 0xffffu; }
; __device__ __forceinline__ float rcpf_(float x) { return __builtin_amdgcn_rcpf(x); }
; template <bool FINAL, int D>
; __device__ __forceinline__ void rg_dir(PREF p, int l, int h, int ch, int sidx, int rowbase  , LAS bf16_t* sXc, LAS float* stg, int lane) {
;     ...
;     const float ba = p.rg_ba[(l * 2 + D) * 512 + ch], bi = p.rg_bi[(l * 2 + D) * 512 + ch], lam = p.rg_lam[(l * 2 + D) * 512 + ch];
;     const float e_ = __expf(-lam), u_ = 1.f + e_;
;     const float l1p = (u_ == 1.f) ? e_ : __logf(u_) * e_ * rcpf_(u_ - 1.f);
;     const float sp8 = -8.f * 1.4426950408889634f * l1p;
;     float hc = FINAL ? RGC[sidx] : 0.f, Ap = 1.f;
;     bf16x8 Br[4][2], Bi[4][2];
; #pragma unroll
;     for (int nt = 0; nt < 4; ++nt) { const int o0 = (nt * 16 + (lane & 15)) * 64 + (lane >> 4) * 8;
;         Br[nt][0] = *(const bf16x8*)(wr_ + o0); Br[nt][1] = *(const bf16x8*)(wr_ + o0 + 32); Bi[nt][0] = *(const bf16x8*)(wi_ + o0); Bi[nt][1] = *(const bf16x8*)(wi_ + o0 + 32); }
;     if (FINAL && D == 1) asm volatile("s_waitcnt vmcnt(0)" ::: "memory");
; #pragma unroll 1
;     for (int mi = 0; mi < 4; ++mi) { const int mt = D ? 3 - mi : mi;
;         float grv[16], hfv[16];
;         if (FINAL && D == 1) {
; #pragma unroll
;             for (int ti = 0; ti < 16; ++ti) { const size_t row = (size_t)(rowbase + mt * 16 + 15 - ti); grv[ti] = __builtin_bit_cast(float, (unsigned)P[row * PW + 512 + ch]); hfv[ti] = __builtin_bit_cast(float, (unsigned)TMP[row * 512 + ch]); }
; template <bool FINAL>
; __device__ __forceinline__ void rg_item(PREF p, int l, int item, LAS unsigned char* wl, int lane) {
;     ...
;         for (int i = 0; i < 67; ++i) { const int t = t0 - 2 + i; const int tc = t < 0 ? 0 : (t >= seqlen ? seqlen - 1 : t); xv[i] = (t == tc) ? bf2f(xr_[i]) : 0.f; }
; #pragma unroll
;         for (int tt = 0; tt < 64; ++tt) { const float xc = xv[tt] * cw0 + xv[tt + 1] * cw1 + xv[tt + 2] * cw2 + xv[tt + 3] * cw3 + cb; sXc[tt * 72 + lane] = (bf16_t)f2bf(xc); }
	v_fmac_f32_e32 v33, v43, v210
	v_fmac_f32_e32 v34, v43, v211
	v_fmac_f32_e32 v35, v43, v212
	v_fmac_f32_e32 v36, v43, v213
	v_fmac_f32_e32 v37, v43, v214
	v_fmac_f32_e32 v38, v43, v215
	v_fmac_f32_e32 v39, v43, v216
	v_add_f32_e32 v32, v44, v32
	v_add_f32_e32 v33, v44, v33
	v_add_f32_e32 v34, v44, v34
	v_add_f32_e32 v35, v44, v35
	v_add_f32_e32 v36, v44, v36
	v_add_f32_e32 v37, v44, v37
	v_add_f32_e32 v38, v44, v38
	v_add_f32_e32 v39, v44, v39
	v_cvt_pk_bf16_f32 v32, v32, v33
	v_cvt_pk_bf16_f32 v34, v34, v35
	v_cvt_pk_bf16_f32 v36, v36, v37
	v_cvt_pk_bf16_f32 v38, v38, v39
	ds_write_b16 v240, v32 offset:6912
	ds_write_b16_d16_hi v240, v32 offset:7056
	ds_write_b16 v240, v34 offset:7200
	ds_write_b16_d16_hi v240, v34 offset:7344
	ds_write_b16 v240, v36 offset:7488
	ds_write_b16_d16_hi v240, v36 offset:7632
	ds_write_b16 v240, v38 offset:7776
	ds_write_b16_d16_hi v240, v38 offset:7920
	v_mul_f32_e32 v32, v41, v215
	v_mul_f32_e32 v33, v41, v216
	v_mul_f32_e32 v34, v41, v217
	v_mul_f32_e32 v35, v41, v218
	v_mul_f32_e32 v36, v41, v219
	v_mul_f32_e32 v37, v41, v222
	v_mul_f32_e32 v38, v41, v223
	v_mul_f32_e32 v39, v41, v140
	v_fmac_f32_e32 v32, v40, v214
	v_fmac_f32_e32 v33, v40, v215
	v_fmac_f32_e32 v34, v40, v216
	v_fmac_f32_e32 v35, v40, v217
	v_fmac_f32_e32 v36, v40, v218
	v_fmac_f32_e32 v37, v40, v219
	v_fmac_f32_e32 v38, v40, v222
	v_fmac_f32_e32 v39, v40, v223
	v_fmac_f32_e32 v32, v42, v216
	v_fmac_f32_e32 v33, v42, v217
	v_fmac_f32_e32 v34, v42, v218
	v_fmac_f32_e32 v35, v42, v219
	v_fmac_f32_e32 v36, v42, v222
	v_fmac_f32_e32 v37, v42, v223
	v_fmac_f32_e32 v38, v42, v140
	v_fmac_f32_e32 v39, v42, v141
	v_fmac_f32_e32 v32, v43, v217
	v_fmac_f32_e32 v33, v43, v218
	v_fmac_f32_e32 v34, v43, v219
	v_fmac_f32_e32 v35, v43, v222
	v_fmac_f32_e32 v36, v43, v223
	v_fmac_f32_e32 v37, v43, v140
	v_fmac_f32_e32 v38, v43, v141
	v_fmac_f32_e32 v39, v43, v232
	v_add_f32_e32 v32, v44, v32
	v_add_f32_e32 v33, v44, v33
	v_add_f32_e32 v34, v44, v34
	v_add_f32_e32 v35, v44, v35
	v_add_f32_e32 v36, v44, v36
	v_add_f32_e32 v37, v44, v37
	v_add_f32_e32 v38, v44, v38
	v_add_f32_e32 v39, v44, v39
	v_cvt_pk_bf16_f32 v32, v32, v33
	v_cvt_pk_bf16_f32 v34, v34, v35
	v_cvt_pk_bf16_f32 v36, v36, v37
	v_cvt_pk_bf16_f32 v38, v38, v39
	ds_write_b16 v240, v32 offset:8064
	ds_write_b16_d16_hi v240, v32 offset:8208
	ds_write_b16 v240, v34 offset:8352
	ds_write_b16_d16_hi v240, v34 offset:8496
	ds_write_b16 v240, v36 offset:8640
	ds_write_b16_d16_hi v240, v36 offset:8784
	ds_write_b16 v240, v38 offset:8928
	ds_write_b16_d16_hi v240, v38 offset:9072
	v_mov_b32_e32 v248, 0xbfb8aa3b
	v_mov_b32_e32 v249, 0xbfb8aa3b
	v_mov_b32_e32 v140, 0x3d372713
	v_mov_b32_e32 v141, 0x3d372713
	s_waitcnt vmcnt(16)
	s_mov_b32 s8, 0x800000
	s_mov_b32 s9, 0x3f317217
	s_mov_b32 s14, 0x7f800000
	v_mul_f32_e32 v32, 0xbfb8aa3b, v45
	v_exp_f32_e32 v32, v32
	s_nop 0
	v_add_f32_e32 v33, 1.0, v32
	v_cmp_gt_f32_e32 vcc, s8, v33
	s_nop 1
	v_cndmask_b32_e64 v34, 0, 32, vcc
	v_ldexp_f32 v34, v33, v34
	v_log_f32_e32 v34, v34
	v_cndmask_b32_e32 v36, 0, v226, vcc
	v_cmp_eq_f32_e32 vcc, 1.0, v33
	v_mul_f32_e32 v35, 0x3f317217, v34
	v_fma_f32 v35, v34, s9, -v35
	v_fmac_f32_e32 v35, 0x3377d1cf, v34
	v_fmac_f32_e32 v35, 0x3f317217, v34
	v_cmp_lt_f32_e64 s[10:11], |v34|, s14
	s_nop 1
	v_cndmask_b32_e64 v34, v34, v35, s[10:11]
	v_add_f32_e32 v35, -1.0, v33
	v_rcp_f32_e32 v35, v35
	v_sub_f32_e32 v34, v34, v36
	v_mul_f32_e32 v34, v32, v34
	v_mul_f32_e32 v34, v34, v35
	v_cndmask_b32_e32 v32, v34, v32, vcc
	v_mul_f32_e32 v246, 0xc138aa3b, v32
	v_mov_b32_e32 v247, v246
	v_mul_f32_e32 v242, 0xbfb8aa3b, v46
	v_mul_f32_e32 v244, 0xbfb8aa3b, v47
	v_mov_b32_e32 v243, v242
	v_mov_b32_e32 v245, v244
	s_waitcnt vmcnt(0)
	s_add_i32 s39, s15, 48
	s_mul_hi_u32 s83, s39, 0x1600
	s_mul_i32 s82, s39, 0x1600
	s_add_u32 s82, s82, s0
	s_addc_u32 s83, s83, s1
	s_add_u32 s82, s82, 0xbc00400
	s_addc_u32 s83, s83, 0
	global_load_ushort v190, v234, s[82:83]
	s_add_u32 s82, s82, 0x1600
	s_addc_u32 s83, s83, 0
	global_load_ushort v191, v234, s[82:83]
	s_add_u32 s82, s82, 0x1600
	s_addc_u32 s83, s83, 0
	global_load_ushort v192, v234, s[82:83]
	s_add_u32 s82, s82, 0x1600
	s_addc_u32 s83, s83, 0
	global_load_ushort v193, v234, s[82:83]
	s_add_u32 s82, s82, 0x1600
	s_addc_u32 s83, s83, 0
	global_load_ushort v194, v234, s[82:83]
	s_add_u32 s82, s82, 0x1600
	s_addc_u32 s83, s83, 0
	global_load_ushort v195, v234, s[82:83]
	s_add_u32 s82, s82, 0x1600
	s_addc_u32 s83, s83, 0
	global_load_ushort v196, v234, s[82:83]
	s_add_u32 s82, s82, 0x1600
	s_addc_u32 s83, s83, 0
	global_load_ushort v197, v234, s[82:83]
	s_add_u32 s82, s82, 0x1600
	s_addc_u32 s83, s83, 0
	global_load_ushort v198, v234, s[82:83]
	s_add_u32 s82, s82, 0x1600
	s_addc_u32 s83, s83, 0
	global_load_ushort v199, v234, s[82:83]
	s_add_u32 s82, s82, 0x1600
	s_addc_u32 s83, s83, 0
	global_load_ushort v200, v234, s[82:83]
	s_add_u32 s82, s82, 0x1600
	s_addc_u32 s83, s83, 0
	global_load_ushort v201, v234, s[82:83]
	s_add_u32 s82, s82, 0x1600
	s_addc_u32 s83, s83, 0
	global_load_ushort v202, v234, s[82:83]
	s_add_u32 s82, s82, 0x1600
	s_addc_u32 s83, s83, 0
	global_load_ushort v203, v234, s[82:83]
	s_add_u32 s82, s82, 0x1600
	s_addc_u32 s83, s83, 0
	global_load_ushort v204, v234, s[82:83]
	s_add_u32 s82, s82, 0x1600
	s_addc_u32 s83, s83, 0
	global_load_ushort v205, v234, s[82:83]
	ds_read_b128 v[32:35], v236 offset:0
	ds_read_b128 v[36:39], v236 offset:64
	s_waitcnt lgkmcnt(0)
; #define LAS __attribute__((address_space(3)))
; #define WAVE_SYNC() asm volatile("s_waitcnt lgkmcnt(0)" ::: "memory")
; __device__ __forceinline__ float sigmoid_f(float x) { return rcpf_(1.f + __expf(-x)); }
; __device__ __forceinline__ f32x4 mfma16(bf16x8 a, bf16x8 b, f32x4 c) { return __builtin_amdgcn_mfma_f32_16x16x32_bf16(a, b, c, 0, 0, 0); }
; template <bool FINAL, int D>
; __device__ __forceinline__ void rg_dir(PREF p, int l, int h, int ch, int sidx, int rowbase  , LAS bf16_t* sXc, LAS float* stg, int lane) {
;     ...
;         const bf16x8 A0 = *(const LAS bf16x8*)(sXc + (mt * 16 + (lane & 15)) * 72 + (lane >> 4) * 8), A1 = *(const LAS bf16x8*)(sXc + (mt * 16 + (lane & 15)) * 72 + 32 + (lane >> 4) * 8);
;         f32x4 ar[4], ai[4];
; #pragma unroll
;         for (int nt = 0; nt < 4; ++nt) { const f32x4 z = {0.f, 0.f, 0.f, 0.f};
;             ar[nt] = mfma16(A0, Br[nt][0], z); ar[nt] = mfma16(A1, Br[nt][1], ar[nt]); ai[nt] = mfma16(A0, Bi[nt][0], z); ai[nt] = mfma16(A1, Bi[nt][1], ai[nt]); }
;         WAVE_SYNC();
; #pragma unroll
;         for (int nt = 0; nt < 4; ++nt)
; #pragma unroll
;             for (int j = 0; j < 4; ++j) { const int o = ((lane >> 4) * 4 + j) * 64 + nt * 16 + (lane & 15); stg[o] = ar[nt][j]; stg[1024 + o] = ai[nt][j]; }
;         WAVE_SYNC();
;         float av[16], iv[16];
; #pragma unroll
;         for (int ti = 0; ti < 16; ++ti) { const int tk = D ? 15 - ti : ti;
;             const float zr = stg[tk * 64 + lane] + ba, zi = stg[1024 + tk * 64 + lane] + bi;
;             const float r = sigmoid_f(zr), ig = sigmoid_f(zi);
	v_mfma_f32_16x16x32_bf16 v[0:3], v[32:35], v[80:83], 0
	v_mfma_f32_16x16x32_bf16 v[4:7], v[32:35], v[88:91], 0
	v_mfma_f32_16x16x32_bf16 v[8:11], v[32:35], v[96:99], 0
	v_mfma_f32_16x16x32_bf16 v[12:15], v[32:35], v[104:107], 0
	v_mfma_f32_16x16x32_bf16 v[16:19], v[32:35], v[112:115], 0
	v_mfma_f32_16x16x32_bf16 v[20:23], v[32:35], v[120:123], 0
	v_mfma_f32_16x16x32_bf16 v[24:27], v[32:35], v[128:131], 0
	v_mfma_f32_16x16x32_bf16 v[28:31], v[32:35], v[136:139], 0
	v_mfma_f32_16x16x32_bf16 v[0:3], v[36:39], v[84:87], v[0:3]
	v_mfma_f32_16x16x32_bf16 v[4:7], v[36:39], v[92:95], v[4:7]
	v_mfma_f32_16x16x32_bf16 v[8:11], v[36:39], v[100:103], v[8:11]
	v_mfma_f32_16x16x32_bf16 v[12:15], v[36:39], v[108:111], v[12:15]
	v_mfma_f32_16x16x32_bf16 v[16:19], v[36:39], v[116:119], v[16:19]
	v_mfma_f32_16x16x32_bf16 v[20:23], v[36:39], v[124:127], v[20:23]
	v_mfma_f32_16x16x32_bf16 v[24:27], v[36:39], v[132:135], v[24:27]
	v_mfma_f32_16x16x32_bf16 v[28:31], v[36:39], v[228:231], v[28:31]
	s_nop 3
	ds_write2_b32 v237, v0, v4 offset0:0 offset1:16
	ds_write2_b32 v237, v8, v12 offset0:32 offset1:48
	ds_write2_b32 v237, v1, v5 offset0:64 offset1:80
	ds_write2_b32 v237, v9, v13 offset0:96 offset1:112
	ds_write2_b32 v237, v2, v6 offset0:128 offset1:144
	ds_write2_b32 v237, v10, v14 offset0:160 offset1:176
	ds_write2_b32 v237, v3, v7 offset0:192 offset1:208
	ds_write2_b32 v237, v11, v15 offset0:224 offset1:240
	ds_write2_b32 v238, v16, v20 offset0:0 offset1:16
	ds_write2_b32 v238, v24, v28 offset0:32 offset1:48
	ds_write2_b32 v238, v17, v21 offset0:64 offset1:80
	ds_write2_b32 v238, v25, v29 offset0:96 offset1:112
	ds_write2_b32 v238, v18, v22 offset0:128 offset1:144
	ds_write2_b32 v238, v26, v30 offset0:160 offset1:176
	ds_write2_b32 v238, v19, v23 offset0:192 offset1:208
	ds_write2_b32 v238, v27, v31 offset0:224 offset1:240
	s_waitcnt lgkmcnt(0)
	ds_read2st64_b32 v[0:1], v239 offset0:36 offset1:37
	ds_read2st64_b32 v[2:3], v239 offset0:38 offset1:39
	ds_read2st64_b32 v[4:5], v239 offset0:40 offset1:41
	ds_read2st64_b32 v[6:7], v239 offset0:42 offset1:43
	ds_read2st64_b32 v[8:9], v239 offset0:44 offset1:45
	ds_read2st64_b32 v[10:11], v239 offset0:46 offset1:47
	ds_read2st64_b32 v[12:13], v239 offset0:48 offset1:49
	ds_read2st64_b32 v[14:15], v239 offset0:50 offset1:51
	ds_read2st64_b32 v[16:17], v239 offset0:52 offset1:53
	ds_read2st64_b32 v[18:19], v239 offset0:54 offset1:55
	ds_read2st64_b32 v[20:21], v239 offset0:56 offset1:57
	ds_read2st64_b32 v[22:23], v239 offset0:58 offset1:59
	ds_read2st64_b32 v[24:25], v239 offset0:60 offset1:61
	ds_read2st64_b32 v[26:27], v239 offset0:62 offset1:63
	ds_read2st64_b32 v[28:29], v239 offset0:64 offset1:65
	ds_read2st64_b32 v[30:31], v239 offset0:66 offset1:67
	ds_read_u16 v48, v240 offset:0
	ds_read_u16 v49, v240 offset:144
	ds_read_u16 v50, v240 offset:288
	ds_read_u16 v51, v240 offset:432
	ds_read_u16 v52, v240 offset:576
	ds_read_u16 v53, v240 offset:720
	ds_read_u16 v54, v240 offset:864
	ds_read_u16 v55, v240 offset:1008
	ds_read_u16 v56, v240 offset:1152
	ds_read_u16 v57, v240 offset:1296
	ds_read_u16 v58, v240 offset:1440
	ds_read_u16 v59, v240 offset:1584
	ds_read_u16 v60, v240 offset:1728
	ds_read_u16 v61, v240 offset:1872
	ds_read_u16 v62, v240 offset:2016
	ds_read_u16 v63, v240 offset:2160
	s_waitcnt lgkmcnt(0)
	v_pk_fma_f32 v[0:1], v[0:1], v[248:249], v[242:243]
	v_pk_fma_f32 v[2:3], v[2:3], v[248:249], v[242:243]
	v_pk_fma_f32 v[4:5], v[4:5], v[248:249], v[242:243]
	v_pk_fma_f32 v[6:7], v[6:7], v[248:249], v[242:243]
	v_pk_fma_f32 v[8:9], v[8:9], v[248:249], v[242:243]
	v_pk_fma_f32 v[10:11], v[10:11], v[248:249], v[242:243]
	v_pk_fma_f32 v[12:13], v[12:13], v[248:249], v[242:243]
	v_pk_fma_f32 v[14:15], v[14:15], v[248:249], v[242:243]
	v_pk_fma_f32 v[16:17], v[16:17], v[248:249], v[244:245]
	v_pk_fma_f32 v[18:19], v[18:19], v[248:249], v[244:245]
	v_pk_fma_f32 v[20:21], v[20:21], v[248:249], v[244:245]
	v_pk_fma_f32 v[22:23], v[22:23], v[248:249], v[244:245]
	v_pk_fma_f32 v[24:25], v[24:25], v[248:249], v[244:245]
	v_pk_fma_f32 v[26:27], v[26:27], v[248:249], v[244:245]
	v_pk_fma_f32 v[28:29], v[28:29], v[248:249], v[244:245]
	v_pk_fma_f32 v[30:31], v[30:31], v[248:249], v[244:245]
	v_exp_f32_e32 v0, v0
	v_exp_f32_e32 v1, v1
	v_exp_f32_e32 v2, v2
	v_exp_f32_e32 v3, v3
	v_exp_f32_e32 v4, v4
	v_exp_f32_e32 v5, v5
	v_exp_f32_e32 v6, v6
	v_exp_f32_e32 v7, v7
	v_exp_f32_e32 v8, v8
	v_exp_f32_e32 v9, v9
	v_exp_f32_e32 v10, v10
	v_exp_f32_e32 v11, v11
	v_exp_f32_e32 v12, v12
	v_exp_f32_e32 v13, v13
	v_exp_f32_e32 v14, v14
	v_exp_f32_e32 v15, v15
	v_exp_f32_e32 v16, v16
	v_exp_f32_e32 v17, v17
	v_exp_f32_e32 v18, v18
	v_exp_f32_e32 v19, v19
	v_exp_f32_e32 v20, v20
	v_exp_f32_e32 v21, v21
	v_exp_f32_e32 v22, v22
	v_exp_f32_e32 v23, v23
	v_exp_f32_e32 v24, v24
	v_exp_f32_e32 v25, v25
	v_exp_f32_e32 v26, v26
	v_exp_f32_e32 v27, v27
	v_exp_f32_e32 v28, v28
	v_exp_f32_e32 v29, v29
	v_exp_f32_e32 v30, v30
	v_exp_f32_e32 v31, v31
	v_pk_add_f32 v[0:1], v[0:1], 1.0 op_sel_hi:[1,0]
	v_pk_add_f32 v[2:3], v[2:3], 1.0 op_sel_hi:[1,0]
	v_pk_add_f32 v[4:5], v[4:5], 1.0 op_sel_hi:[1,0]
	v_pk_add_f32 v[6:7], v[6:7], 1.0 op_sel_hi:[1,0]
	v_pk_add_f32 v[8:9], v[8:9], 1.0 op_sel_hi:[1,0]
	v_pk_add_f32 v[10:11], v[10:11], 1.0 op_sel_hi:[1,0]
	v_pk_add_f32 v[12:13], v[12:13], 1.0 op_sel_hi:[1,0]
	v_pk_add_f32 v[14:15], v[14:15], 1.0 op_sel_hi:[1,0]
	v_pk_add_f32 v[16:17], v[16:17], 1.0 op_sel_hi:[1,0]
	v_pk_add_f32 v[18:19], v[18:19], 1.0 op_sel_hi:[1,0]
	v_pk_add_f32 v[20:21], v[20:21], 1.0 op_sel_hi:[1,0]
	v_pk_add_f32 v[22:23], v[22:23], 1.0 op_sel_hi:[1,0]
	v_pk_add_f32 v[24:25], v[24:25], 1.0 op_sel_hi:[1,0]
; #define LAS __attribute__((address_space(3)))
; #define WAVE_SYNC() asm volatile("s_waitcnt lgkmcnt(0)" ::: "memory")
; __device__ __forceinline__ unsigned f2bf(float f) { unsigned r; asm("v_cvt_pk_bf16_f32 %0, %1, %1" : "=v"(r) : "v"(f)); return r & 0xffffu; }
; __device__ __forceinline__ float sigmoid_f(float x) { return rcpf_(1.f + __expf(-x)); }
; __device__ __forceinline__ float gelu_tanh_f(float x) { const float y = 0.7978845608028654f * (x + 0.044715f * x * x * x); return x * sigmoid_f(2.f * y); }
; template <bool FINAL, int D>
; __device__ __forceinline__ void rg_dir(PREF p, int l, int h, int ch, int sidx, int rowbase  , LAS bf16_t* sXc, LAS float* stg, int lane) {
;     ...
;         const bf16x8 A0 = *(const LAS bf16x8*)(sXc + (mt * 16 + (lane & 15)) * 72 + (lane >> 4) * 8), A1 = *(const LAS bf16x8*)(sXc + (mt * 16 + (lane & 15)) * 72 + 32 + (lane >> 4) * 8);
;         f32x4 ar[4], ai[4];
; #pragma unroll
;         for (int nt = 0; nt < 4; ++nt) { const f32x4 z = {0.f, 0.f, 0.f, 0.f};
;             ar[nt] = mfma16(A0, Br[nt][0], z); ar[nt] = mfma16(A1, Br[nt][1], ar[nt]); ai[nt] = mfma16(A0, Bi[nt][0], z); ai[nt] = mfma16(A1, Bi[nt][1], ai[nt]); }
;         WAVE_SYNC();
; #pragma unroll
;         for (int nt = 0; nt < 4; ++nt)
; #pragma unroll
;             for (int j = 0; j < 4; ++j) { const int o = ((lane >> 4) * 4 + j) * 64 + nt * 16 + (lane & 15); stg[o] = ar[nt][j]; stg[1024 + o] = ai[nt][j]; }
;         WAVE_SYNC();
;     ...
;         for (int ti = 0; ti < 16; ++ti) { const int tk = D ? 15 - ti : ti;
;             const float zr = stg[tk * 64 + lane] + ba, zi = stg[1024 + tk * 64 + lane] + bi;
;             const float r = sigmoid_f(zr), ig = sigmoid_f(zi);
;             const float a = __builtin_amdgcn_exp2f(r * sp8);
;             const float xc = bf2f(sXc[(mt * 16 + tk) * 72 + lane]);
;             av[ti] = a; iv[ti] = __builtin_amdgcn_sqrtf(fmaxf(1.f - a * a, 0.f)) * ig * xc;
;             if (FINAL && D == 1) grv[ti] = gelu_tanh_f(grv[ti]);
;         }
; #pragma unroll
;         for (int ti = 0; ti < 16; ++ti) { const int tk = D ? 15 - ti : ti;
;             hc = av[ti] * hc + iv[ti]; Ap *= av[ti];
;             if (FINAL) { const size_t row = (size_t)(rowbase + mt * 16 + tk);
;                 if (D == 0) TMP[row * 512 + ch] = (bf16_t)f2bf(hc);
;                 else MIX[row * DM + ch] = (bf16_t)f2bf(grv[ti] * (hfv[ti] + hc)); }
	v_pk_add_f32 v[26:27], v[26:27], 1.0 op_sel_hi:[1,0]
	v_pk_add_f32 v[28:29], v[28:29], 1.0 op_sel_hi:[1,0]
	v_pk_add_f32 v[30:31], v[30:31], 1.0 op_sel_hi:[1,0]
	v_rcp_f32_e32 v0, v0
	v_rcp_f32_e32 v1, v1
	v_rcp_f32_e32 v2, v2
	v_rcp_f32_e32 v3, v3
	v_rcp_f32_e32 v4, v4
	v_rcp_f32_e32 v5, v5
	v_rcp_f32_e32 v6, v6
	v_rcp_f32_e32 v7, v7
	v_rcp_f32_e32 v8, v8
	v_rcp_f32_e32 v9, v9
	v_rcp_f32_e32 v10, v10
	v_rcp_f32_e32 v11, v11
	v_rcp_f32_e32 v12, v12
	v_rcp_f32_e32 v13, v13
	v_rcp_f32_e32 v14, v14
	v_rcp_f32_e32 v15, v15
	v_rcp_f32_e32 v16, v16
	v_rcp_f32_e32 v17, v17
	v_rcp_f32_e32 v18, v18
	v_rcp_f32_e32 v19, v19
	v_rcp_f32_e32 v20, v20
	v_rcp_f32_e32 v21, v21
	v_rcp_f32_e32 v22, v22
	v_rcp_f32_e32 v23, v23
	v_rcp_f32_e32 v24, v24
	v_rcp_f32_e32 v25, v25
	v_rcp_f32_e32 v26, v26
	v_rcp_f32_e32 v27, v27
	v_rcp_f32_e32 v28, v28
	v_rcp_f32_e32 v29, v29
	v_rcp_f32_e32 v30, v30
	v_rcp_f32_e32 v31, v31
	v_pk_mul_f32 v[0:1], v[246:247], v[0:1]
	v_pk_mul_f32 v[2:3], v[246:247], v[2:3]
	v_pk_mul_f32 v[4:5], v[246:247], v[4:5]
	v_pk_mul_f32 v[6:7], v[246:247], v[6:7]
	v_pk_mul_f32 v[8:9], v[246:247], v[8:9]
	v_pk_mul_f32 v[10:11], v[246:247], v[10:11]
	v_pk_mul_f32 v[12:13], v[246:247], v[12:13]
	v_pk_mul_f32 v[14:15], v[246:247], v[14:15]
	v_lshlrev_b32_e32 v48, 16, v48
	v_lshlrev_b32_e32 v49, 16, v49
	v_lshlrev_b32_e32 v50, 16, v50
	v_lshlrev_b32_e32 v51, 16, v51
	v_lshlrev_b32_e32 v52, 16, v52
	v_lshlrev_b32_e32 v53, 16, v53
	v_lshlrev_b32_e32 v54, 16, v54
	v_lshlrev_b32_e32 v55, 16, v55
	v_lshlrev_b32_e32 v56, 16, v56
	v_lshlrev_b32_e32 v57, 16, v57
	v_lshlrev_b32_e32 v58, 16, v58
	v_lshlrev_b32_e32 v59, 16, v59
	v_lshlrev_b32_e32 v60, 16, v60
	v_lshlrev_b32_e32 v61, 16, v61
	v_lshlrev_b32_e32 v62, 16, v62
	v_lshlrev_b32_e32 v63, 16, v63
	v_exp_f32_e32 v0, v0
	v_exp_f32_e32 v1, v1
	v_exp_f32_e32 v2, v2
	v_exp_f32_e32 v3, v3
	v_exp_f32_e32 v4, v4
	v_exp_f32_e32 v5, v5
	v_exp_f32_e32 v6, v6
	v_exp_f32_e32 v7, v7
	v_exp_f32_e32 v8, v8
	v_exp_f32_e32 v9, v9
	v_exp_f32_e32 v10, v10
	v_exp_f32_e32 v11, v11
	v_exp_f32_e32 v12, v12
	v_exp_f32_e32 v13, v13
	v_exp_f32_e32 v14, v14
	v_exp_f32_e32 v15, v15
	v_fma_f32 v32, -v0, v0, 1.0 clamp
	v_fma_f32 v33, -v1, v1, 1.0 clamp
	v_fma_f32 v34, -v2, v2, 1.0 clamp
	v_fma_f32 v35, -v3, v3, 1.0 clamp
	v_fma_f32 v36, -v4, v4, 1.0 clamp
	v_fma_f32 v37, -v5, v5, 1.0 clamp
	v_fma_f32 v38, -v6, v6, 1.0 clamp
	v_fma_f32 v39, -v7, v7, 1.0 clamp
	v_fma_f32 v40, -v8, v8, 1.0 clamp
	v_fma_f32 v41, -v9, v9, 1.0 clamp
	v_fma_f32 v42, -v10, v10, 1.0 clamp
	v_fma_f32 v43, -v11, v11, 1.0 clamp
	v_fma_f32 v44, -v12, v12, 1.0 clamp
	v_fma_f32 v45, -v13, v13, 1.0 clamp
	v_fma_f32 v46, -v14, v14, 1.0 clamp
	v_fma_f32 v47, -v15, v15, 1.0 clamp
	v_sqrt_f32_e32 v32, v32
	v_sqrt_f32_e32 v33, v33
	v_sqrt_f32_e32 v34, v34
	v_sqrt_f32_e32 v35, v35
	v_sqrt_f32_e32 v36, v36
	v_sqrt_f32_e32 v37, v37
	v_sqrt_f32_e32 v38, v38
	v_sqrt_f32_e32 v39, v39
	v_sqrt_f32_e32 v40, v40
	v_sqrt_f32_e32 v41, v41
	v_sqrt_f32_e32 v42, v42
	v_sqrt_f32_e32 v43, v43
	v_sqrt_f32_e32 v44, v44
	v_sqrt_f32_e32 v45, v45
	v_sqrt_f32_e32 v46, v46
	v_sqrt_f32_e32 v47, v47
	s_nop 0
	v_pk_mul_f32 v[16:17], v[16:17], v[32:33]
	v_pk_mul_f32 v[18:19], v[18:19], v[34:35]
	v_pk_mul_f32 v[20:21], v[20:21], v[36:37]
	v_pk_mul_f32 v[22:23], v[22:23], v[38:39]
	v_pk_mul_f32 v[24:25], v[24:25], v[40:41]
	v_pk_mul_f32 v[26:27], v[26:27], v[42:43]
	v_pk_mul_f32 v[28:29], v[28:29], v[44:45]
	v_pk_mul_f32 v[30:31], v[30:31], v[46:47]
	v_pk_mul_f32 v[16:17], v[16:17], v[48:49]
	v_pk_mul_f32 v[18:19], v[18:19], v[50:51]
	v_pk_mul_f32 v[20:21], v[20:21], v[52:53]
	v_pk_mul_f32 v[22:23], v[22:23], v[54:55]
	v_pk_mul_f32 v[24:25], v[24:25], v[56:57]
	v_pk_mul_f32 v[26:27], v[26:27], v[58:59]
	v_pk_mul_f32 v[28:29], v[28:29], v[60:61]
	v_pk_mul_f32 v[30:31], v[30:31], v[62:63]
	v_fma_f32 v32, v0, v250, v16
	v_fma_f32 v250, v1, v32, v17
	v_cvt_pk_bf16_f32 v158, v32, v250
	v_fma_f32 v32, v2, v250, v18
	v_fma_f32 v250, v3, v32, v19
	v_cvt_pk_bf16_f32 v159, v32, v250
	v_fma_f32 v32, v4, v250, v20
	v_fma_f32 v250, v5, v32, v21
	v_cvt_pk_bf16_f32 v160, v32, v250
	v_fma_f32 v32, v6, v250, v22
	v_fma_f32 v250, v7, v32, v23
	v_cvt_pk_bf16_f32 v161, v32, v250
	v_fma_f32 v32, v8, v250, v24
	v_fma_f32 v250, v9, v32, v25
	v_cvt_pk_bf16_f32 v162, v32, v250
	v_fma_f32 v32, v10, v250, v26
	v_fma_f32 v250, v11, v32, v27
	v_cvt_pk_bf16_f32 v163, v32, v250
	v_fma_f32 v32, v12, v250, v28
	v_fma_f32 v250, v13, v32, v29
	v_cvt_pk_bf16_f32 v164, v32, v250
	v_fma_f32 v32, v14, v250, v30
	v_fma_f32 v250, v15, v32, v31
	v_cvt_pk_bf16_f32 v165, v32, v250
	ds_read_b128 v[32:35], v236 offset:2304
	ds_read_b128 v[36:39], v236 offset:2368
	s_waitcnt lgkmcnt(0)
	v_mfma_f32_16x16x32_bf16 v[0:3], v[32:35], v[80:83], 0
	v_mfma_f32_16x16x32_bf16 v[4:7], v[32:35], v[88:91], 0
	v_mfma_f32_16x16x32_bf16 v[8:11], v[32:35], v[96:99], 0
	v_mfma_f32_16x16x32_bf16 v[12:15], v[32:35], v[104:107], 0
	v_mfma_f32_16x16x32_bf16 v[16:19], v[32:35], v[112:115], 0
	v_mfma_f32_16x16x32_bf16 v[20:23], v[32:35], v[120:123], 0
	v_mfma_f32_16x16x32_bf16 v[24:27], v[32:35], v[128:131], 0
	v_mfma_f32_16x16x32_bf16 v[28:31], v[32:35], v[136:139], 0
	v_mfma_f32_16x16x32_bf16 v[0:3], v[36:39], v[84:87], v[0:3]
	v_mfma_f32_16x16x32_bf16 v[4:7], v[36:39], v[92:95], v[4:7]
	v_mfma_f32_16x16x32_bf16 v[8:11], v[36:39], v[100:103], v[8:11]
	v_mfma_f32_16x16x32_bf16 v[12:15], v[36:39], v[108:111], v[12:15]
	v_mfma_f32_16x16x32_bf16 v[16:19], v[36:39], v[116:119], v[16:19]
	v_mfma_f32_16x16x32_bf16 v[20:23], v[36:39], v[124:127], v[20:23]
	v_mfma_f32_16x16x32_bf16 v[24:27], v[36:39], v[132:135], v[24:27]
	v_mfma_f32_16x16x32_bf16 v[28:31], v[36:39], v[228:231], v[28:31]
	s_nop 3
	ds_write2_b32 v237, v0, v4 offset0:0 offset1:16
	ds_write2_b32 v237, v8, v12 offset0:32 offset1:48
	ds_write2_b32 v237, v1, v5 offset0:64 offset1:80
	ds_write2_b32 v237, v9, v13 offset0:96 offset1:112
	ds_write2_b32 v237, v2, v6 offset0:128 offset1:144
	ds_write2_b32 v237, v10, v14 offset0:160 offset1:176
	ds_write2_b32 v237, v3, v7 offset0:192 offset1:208
	ds_write2_b32 v237, v11, v15 offset0:224 offset1:240
	ds_write2_b32 v238, v16, v20 offset0:0 offset1:16
	ds_write2_b32 v238, v24, v28 offset0:32 offset1:48
	ds_write2_b32 v238, v17, v21 offset0:64 offset1:80
	ds_write2_b32 v238, v25, v29 offset0:96 offset1:112
	ds_write2_b32 v238, v18, v22 offset0:128 offset1:144
	ds_write2_b32 v238, v26, v30 offset0:160 offset1:176
	ds_write2_b32 v238, v19, v23 offset0:192 offset1:208
	ds_write2_b32 v238, v27, v31 offset0:224 offset1:240
	s_waitcnt lgkmcnt(0)
; #define WAVE_SYNC() asm volatile("s_waitcnt lgkmcnt(0)" ::: "memory")
; __device__ __forceinline__ float sigmoid_f(float x) { return rcpf_(1.f + __expf(-x)); }
; template <bool FINAL, int D>
; __device__ __forceinline__ void rg_dir(PREF p, int l, int h, int ch, int sidx, int rowbase  , LAS bf16_t* sXc, LAS float* stg, int lane) {
;     ...
;         for (int nt = 0; nt < 4; ++nt)
; #pragma unroll
;             for (int j = 0; j < 4; ++j) { const int o = ((lane >> 4) * 4 + j) * 64 + nt * 16 + (lane & 15); stg[o] = ar[nt][j]; stg[1024 + o] = ai[nt][j]; }
;         WAVE_SYNC();
;         float av[16], iv[16];
; #pragma unroll
;         for (int ti = 0; ti < 16; ++ti) { const int tk = D ? 15 - ti : ti;
;             const float zr = stg[tk * 64 + lane] + ba, zi = stg[1024 + tk * 64 + lane] + bi;
;             const float r = sigmoid_f(zr), ig = sigmoid_f(zi);
	ds_read2st64_b32 v[0:1], v239 offset0:36 offset1:37
	ds_read2st64_b32 v[2:3], v239 offset0:38 offset1:39
	ds_read2st64_b32 v[4:5], v239 offset0:40 offset1:41
	ds_read2st64_b32 v[6:7], v239 offset0:42 offset1:43
	ds_read2st64_b32 v[8:9], v239 offset0:44 offset1:45
	ds_read2st64_b32 v[10:11], v239 offset0:46 offset1:47
	ds_read2st64_b32 v[12:13], v239 offset0:48 offset1:49
	ds_read2st64_b32 v[14:15], v239 offset0:50 offset1:51
	ds_read2st64_b32 v[16:17], v239 offset0:52 offset1:53
	ds_read2st64_b32 v[18:19], v239 offset0:54 offset1:55
	ds_read2st64_b32 v[20:21], v239 offset0:56 offset1:57
	ds_read2st64_b32 v[22:23], v239 offset0:58 offset1:59
	ds_read2st64_b32 v[24:25], v239 offset0:60 offset1:61
	ds_read2st64_b32 v[26:27], v239 offset0:62 offset1:63
	ds_read2st64_b32 v[28:29], v239 offset0:64 offset1:65
	ds_read2st64_b32 v[30:31], v239 offset0:66 offset1:67
	ds_read_u16_d16_hi v48, v240 offset:2304
	ds_read_u16_d16_hi v49, v240 offset:2448
	ds_read_u16_d16_hi v50, v240 offset:2592
	ds_read_u16_d16_hi v51, v240 offset:2736
	ds_read_u16_d16_hi v52, v240 offset:2880
	ds_read_u16_d16_hi v53, v240 offset:3024
	ds_read_u16_d16_hi v54, v240 offset:3168
	ds_read_u16_d16_hi v55, v240 offset:3312
	ds_read_u16_d16_hi v56, v240 offset:3456
	ds_read_u16_d16_hi v57, v240 offset:3600
	ds_read_u16_d16_hi v58, v240 offset:3744
	ds_read_u16_d16_hi v59, v240 offset:3888
	ds_read_u16_d16_hi v60, v240 offset:4032
	ds_read_u16_d16_hi v61, v240 offset:4176
	ds_read_u16_d16_hi v62, v240 offset:4320
	ds_read_u16_d16_hi v63, v240 offset:4464
	s_waitcnt lgkmcnt(0)
	v_pk_fma_f32 v[0:1], v[0:1], v[248:249], v[242:243]
	v_pk_fma_f32 v[2:3], v[2:3], v[248:249], v[242:243]
	v_pk_fma_f32 v[4:5], v[4:5], v[248:249], v[242:243]
	v_pk_fma_f32 v[6:7], v[6:7], v[248:249], v[242:243]
	v_pk_fma_f32 v[8:9], v[8:9], v[248:249], v[242:243]
	v_pk_fma_f32 v[10:11], v[10:11], v[248:249], v[242:243]
	v_pk_fma_f32 v[12:13], v[12:13], v[248:249], v[242:243]
	v_pk_fma_f32 v[14:15], v[14:15], v[248:249], v[242:243]
	v_pk_fma_f32 v[16:17], v[16:17], v[248:249], v[244:245]
	v_pk_fma_f32 v[18:19], v[18:19], v[248:249], v[244:245]
	v_pk_fma_f32 v[20:21], v[20:21], v[248:249], v[244:245]
	v_pk_fma_f32 v[22:23], v[22:23], v[248:249], v[244:245]
	v_pk_fma_f32 v[24:25], v[24:25], v[248:249], v[244:245]
	v_pk_fma_f32 v[26:27], v[26:27], v[248:249], v[244:245]
	v_pk_fma_f32 v[28:29], v[28:29], v[248:249], v[244:245]
	v_pk_fma_f32 v[30:31], v[30:31], v[248:249], v[244:245]
	v_exp_f32_e32 v0, v0
	v_exp_f32_e32 v1, v1
	v_exp_f32_e32 v2, v2
	v_exp_f32_e32 v3, v3
	v_exp_f32_e32 v4, v4
	v_exp_f32_e32 v5, v5
	v_exp_f32_e32 v6, v6
	v_exp_f32_e32 v7, v7
	v_exp_f32_e32 v8, v8
	v_exp_f32_e32 v9, v9
	v_exp_f32_e32 v10, v10
	v_exp_f32_e32 v11, v11
	v_exp_f32_e32 v12, v12
	v_exp_f32_e32 v13, v13
	v_exp_f32_e32 v14, v14
	v_exp_f32_e32 v15, v15
	v_exp_f32_e32 v16, v16
	v_exp_f32_e32 v17, v17
	v_exp_f32_e32 v18, v18
	v_exp_f32_e32 v19, v19
	v_exp_f32_e32 v20, v20
	v_exp_f32_e32 v21, v21
	v_exp_f32_e32 v22, v22
	v_exp_f32_e32 v23, v23
	v_exp_f32_e32 v24, v24
	v_exp_f32_e32 v25, v25
	v_exp_f32_e32 v26, v26
	v_exp_f32_e32 v27, v27
	v_exp_f32_e32 v28, v28
	v_exp_f32_e32 v29, v29
	v_exp_f32_e32 v30, v30
	v_exp_f32_e32 v31, v31
	v_pk_add_f32 v[0:1], v[0:1], 1.0 op_sel_hi:[1,0]
	v_pk_add_f32 v[2:3], v[2:3], 1.0 op_sel_hi:[1,0]
	v_pk_add_f32 v[4:5], v[4:5], 1.0 op_sel_hi:[1,0]
	v_pk_add_f32 v[6:7], v[6:7], 1.0 op_sel_hi:[1,0]
	v_pk_add_f32 v[8:9], v[8:9], 1.0 op_sel_hi:[1,0]
	v_pk_add_f32 v[10:11], v[10:11], 1.0 op_sel_hi:[1,0]
	v_pk_add_f32 v[12:13], v[12:13], 1.0 op_sel_hi:[1,0]
	v_pk_add_f32 v[14:15], v[14:15], 1.0 op_sel_hi:[1,0]
	v_pk_add_f32 v[16:17], v[16:17], 1.0 op_sel_hi:[1,0]
	v_pk_add_f32 v[18:19], v[18:19], 1.0 op_sel_hi:[1,0]
	v_pk_add_f32 v[20:21], v[20:21], 1.0 op_sel_hi:[1,0]
	v_pk_add_f32 v[22:23], v[22:23], 1.0 op_sel_hi:[1,0]
	v_pk_add_f32 v[24:25], v[24:25], 1.0 op_sel_hi:[1,0]
	v_pk_add_f32 v[26:27], v[26:27], 1.0 op_sel_hi:[1,0]
	v_pk_add_f32 v[28:29], v[28:29], 1.0 op_sel_hi:[1,0]
	v_pk_add_f32 v[30:31], v[30:31], 1.0 op_sel_hi:[1,0]
	v_rcp_f32_e32 v0, v0
	v_rcp_f32_e32 v1, v1
	v_rcp_f32_e32 v2, v2
	v_rcp_f32_e32 v3, v3
	v_rcp_f32_e32 v4, v4
	v_rcp_f32_e32 v5, v5
	v_rcp_f32_e32 v6, v6
	v_rcp_f32_e32 v7, v7
	v_rcp_f32_e32 v8, v8
	v_rcp_f32_e32 v9, v9
	v_rcp_f32_e32 v10, v10
	v_rcp_f32_e32 v11, v11
	v_rcp_f32_e32 v12, v12
	v_rcp_f32_e32 v13, v13
	v_rcp_f32_e32 v14, v14
	v_rcp_f32_e32 v15, v15
	v_rcp_f32_e32 v16, v16
	v_rcp_f32_e32 v17, v17
	v_rcp_f32_e32 v18, v18
	v_rcp_f32_e32 v19, v19
	v_rcp_f32_e32 v20, v20
	v_rcp_f32_e32 v21, v21
	v_rcp_f32_e32 v22, v22
	v_rcp_f32_e32 v23, v23
	v_rcp_f32_e32 v24, v24
	v_rcp_f32_e32 v25, v25
	v_rcp_f32_e32 v26, v26
	v_rcp_f32_e32 v27, v27
	v_rcp_f32_e32 v28, v28
	v_rcp_f32_e32 v29, v29
	v_rcp_f32_e32 v30, v30
	v_rcp_f32_e32 v31, v31
	v_pk_mul_f32 v[0:1], v[246:247], v[0:1]
	v_pk_mul_f32 v[2:3], v[246:247], v[2:3]
	v_pk_mul_f32 v[4:5], v[246:247], v[4:5]
	v_pk_mul_f32 v[6:7], v[246:247], v[6:7]
	v_pk_mul_f32 v[8:9], v[246:247], v[8:9]
	v_pk_mul_f32 v[10:11], v[246:247], v[10:11]
	v_pk_mul_f32 v[12:13], v[246:247], v[12:13]
	v_pk_mul_f32 v[14:15], v[246:247], v[14:15]
	v_exp_f32_e32 v0, v0
	v_exp_f32_e32 v1, v1
	v_exp_f32_e32 v2, v2
	v_exp_f32_e32 v3, v3
	v_exp_f32_e32 v4, v4
	v_exp_f32_e32 v5, v5
	v_exp_f32_e32 v6, v6
	v_exp_f32_e32 v7, v7
	v_exp_f32_e32 v8, v8
	v_exp_f32_e32 v9, v9
	v_exp_f32_e32 v10, v10
	v_exp_f32_e32 v11, v11
	v_exp_f32_e32 v12, v12
	v_exp_f32_e32 v13, v13
	v_exp_f32_e32 v14, v14
	v_exp_f32_e32 v15, v15
	v_fma_f32 v32, -v0, v0, 1.0 clamp
	v_fma_f32 v33, -v1, v1, 1.0 clamp
	v_fma_f32 v34, -v2, v2, 1.0 clamp
	v_fma_f32 v35, -v3, v3, 1.0 clamp
; #define LAS __attribute__((address_space(3)))
; #define WAVE_SYNC() asm volatile("s_waitcnt lgkmcnt(0)" ::: "memory")
; __device__ __forceinline__ unsigned f2bf(float f) { unsigned r; asm("v_cvt_pk_bf16_f32 %0, %1, %1" : "=v"(r) : "v"(f)); return r & 0xffffu; }
; __device__ __forceinline__ float sigmoid_f(float x) { return rcpf_(1.f + __expf(-x)); }
; __device__ __forceinline__ float gelu_tanh_f(float x) { const float y = 0.7978845608028654f * (x + 0.044715f * x * x * x); return x * sigmoid_f(2.f * y); }
; __device__ __forceinline__ f32x4 mfma16(bf16x8 a, bf16x8 b, f32x4 c) { return __builtin_amdgcn_mfma_f32_16x16x32_bf16(a, b, c, 0, 0, 0); }
; template <bool FINAL, int D>
; __device__ __forceinline__ void rg_dir(PREF p, int l, int h, int ch, int sidx, int rowbase  , LAS bf16_t* sXc, LAS float* stg, int lane) {
;     ...
;         const bf16x8 A0 = *(const LAS bf16x8*)(sXc + (mt * 16 + (lane & 15)) * 72 + (lane >> 4) * 8), A1 = *(const LAS bf16x8*)(sXc + (mt * 16 + (lane & 15)) * 72 + 32 + (lane >> 4) * 8);
;         f32x4 ar[4], ai[4];
; #pragma unroll
;         for (int nt = 0; nt < 4; ++nt) { const f32x4 z = {0.f, 0.f, 0.f, 0.f};
;             ar[nt] = mfma16(A0, Br[nt][0], z); ar[nt] = mfma16(A1, Br[nt][1], ar[nt]); ai[nt] = mfma16(A0, Bi[nt][0], z); ai[nt] = mfma16(A1, Bi[nt][1], ai[nt]); }
;         WAVE_SYNC();
; #pragma unroll
;         for (int nt = 0; nt < 4; ++nt)
; #pragma unroll
;             for (int j = 0; j < 4; ++j) { const int o = ((lane >> 4) * 4 + j) * 64 + nt * 16 + (lane & 15); stg[o] = ar[nt][j]; stg[1024 + o] = ai[nt][j]; }
;         WAVE_SYNC();
;     ...
;             const float r = sigmoid_f(zr), ig = sigmoid_f(zi);
;             const float a = __builtin_amdgcn_exp2f(r * sp8);
;             const float xc = bf2f(sXc[(mt * 16 + tk) * 72 + lane]);
;             av[ti] = a; iv[ti] = __builtin_amdgcn_sqrtf(fmaxf(1.f - a * a, 0.f)) * ig * xc;
;             if (FINAL && D == 1) grv[ti] = gelu_tanh_f(grv[ti]);
;         }
; #pragma unroll
;         for (int ti = 0; ti < 16; ++ti) { const int tk = D ? 15 - ti : ti;
;             hc = av[ti] * hc + iv[ti]; Ap *= av[ti];
;             if (FINAL) { const size_t row = (size_t)(rowbase + mt * 16 + tk);
;                 if (D == 0) TMP[row * 512 + ch] = (bf16_t)f2bf(hc);
;                 else MIX[row * DM + ch] = (bf16_t)f2bf(grv[ti] * (hfv[ti] + hc)); }
	v_fma_f32 v36, -v4, v4, 1.0 clamp
	v_fma_f32 v37, -v5, v5, 1.0 clamp
	v_fma_f32 v38, -v6, v6, 1.0 clamp
	v_fma_f32 v39, -v7, v7, 1.0 clamp
	v_fma_f32 v40, -v8, v8, 1.0 clamp
	v_fma_f32 v41, -v9, v9, 1.0 clamp
	v_fma_f32 v42, -v10, v10, 1.0 clamp
	v_fma_f32 v43, -v11, v11, 1.0 clamp
	v_fma_f32 v44, -v12, v12, 1.0 clamp
	v_fma_f32 v45, -v13, v13, 1.0 clamp
	v_fma_f32 v46, -v14, v14, 1.0 clamp
	v_fma_f32 v47, -v15, v15, 1.0 clamp
	v_sqrt_f32_e32 v32, v32
	v_sqrt_f32_e32 v33, v33
	v_sqrt_f32_e32 v34, v34
	v_sqrt_f32_e32 v35, v35
	v_sqrt_f32_e32 v36, v36
	v_sqrt_f32_e32 v37, v37
	v_sqrt_f32_e32 v38, v38
	v_sqrt_f32_e32 v39, v39
	v_sqrt_f32_e32 v40, v40
	v_sqrt_f32_e32 v41, v41
	v_sqrt_f32_e32 v42, v42
	v_sqrt_f32_e32 v43, v43
	v_sqrt_f32_e32 v44, v44
	v_sqrt_f32_e32 v45, v45
	v_sqrt_f32_e32 v46, v46
	v_sqrt_f32_e32 v47, v47
	s_nop 0
	v_pk_mul_f32 v[16:17], v[16:17], v[32:33]
	v_pk_mul_f32 v[18:19], v[18:19], v[34:35]
	v_pk_mul_f32 v[20:21], v[20:21], v[36:37]
	v_pk_mul_f32 v[22:23], v[22:23], v[38:39]
	v_pk_mul_f32 v[24:25], v[24:25], v[40:41]
	v_pk_mul_f32 v[26:27], v[26:27], v[42:43]
	v_pk_mul_f32 v[28:29], v[28:29], v[44:45]
	v_pk_mul_f32 v[30:31], v[30:31], v[46:47]
	v_pk_mul_f32 v[16:17], v[16:17], v[48:49]
	v_pk_mul_f32 v[18:19], v[18:19], v[50:51]
	v_pk_mul_f32 v[20:21], v[20:21], v[52:53]
	v_pk_mul_f32 v[22:23], v[22:23], v[54:55]
	v_pk_mul_f32 v[24:25], v[24:25], v[56:57]
	v_pk_mul_f32 v[26:27], v[26:27], v[58:59]
	v_pk_mul_f32 v[28:29], v[28:29], v[60:61]
	v_pk_mul_f32 v[30:31], v[30:31], v[62:63]
	v_fma_f32 v32, v0, v250, v16
	v_fma_f32 v250, v1, v32, v17
	v_cvt_pk_bf16_f32 v166, v32, v250
	v_fma_f32 v32, v2, v250, v18
	v_fma_f32 v250, v3, v32, v19
	v_cvt_pk_bf16_f32 v167, v32, v250
	v_fma_f32 v32, v4, v250, v20
	v_fma_f32 v250, v5, v32, v21
	v_cvt_pk_bf16_f32 v168, v32, v250
	v_fma_f32 v32, v6, v250, v22
	v_fma_f32 v250, v7, v32, v23
	v_cvt_pk_bf16_f32 v169, v32, v250
	v_fma_f32 v32, v8, v250, v24
	v_fma_f32 v250, v9, v32, v25
	v_cvt_pk_bf16_f32 v170, v32, v250
	v_fma_f32 v32, v10, v250, v26
	v_fma_f32 v250, v11, v32, v27
	v_cvt_pk_bf16_f32 v171, v32, v250
	v_fma_f32 v32, v12, v250, v28
	v_fma_f32 v250, v13, v32, v29
	v_cvt_pk_bf16_f32 v172, v32, v250
	v_fma_f32 v32, v14, v250, v30
	v_fma_f32 v250, v15, v32, v31
	v_cvt_pk_bf16_f32 v173, v32, v250
	ds_read_b128 v[32:35], v236 offset:4608
	ds_read_b128 v[36:39], v236 offset:4672
	s_waitcnt lgkmcnt(0)
	v_mfma_f32_16x16x32_bf16 v[0:3], v[32:35], v[80:83], 0
	v_mfma_f32_16x16x32_bf16 v[4:7], v[32:35], v[88:91], 0
	v_mfma_f32_16x16x32_bf16 v[8:11], v[32:35], v[96:99], 0
	v_mfma_f32_16x16x32_bf16 v[12:15], v[32:35], v[104:107], 0
	v_mfma_f32_16x16x32_bf16 v[16:19], v[32:35], v[112:115], 0
	v_mfma_f32_16x16x32_bf16 v[20:23], v[32:35], v[120:123], 0
	v_mfma_f32_16x16x32_bf16 v[24:27], v[32:35], v[128:131], 0
	v_mfma_f32_16x16x32_bf16 v[28:31], v[32:35], v[136:139], 0
	v_mfma_f32_16x16x32_bf16 v[0:3], v[36:39], v[84:87], v[0:3]
	v_mfma_f32_16x16x32_bf16 v[4:7], v[36:39], v[92:95], v[4:7]
	v_mfma_f32_16x16x32_bf16 v[8:11], v[36:39], v[100:103], v[8:11]
	v_mfma_f32_16x16x32_bf16 v[12:15], v[36:39], v[108:111], v[12:15]
	v_mfma_f32_16x16x32_bf16 v[16:19], v[36:39], v[116:119], v[16:19]
	v_mfma_f32_16x16x32_bf16 v[20:23], v[36:39], v[124:127], v[20:23]
	v_mfma_f32_16x16x32_bf16 v[24:27], v[36:39], v[132:135], v[24:27]
	v_mfma_f32_16x16x32_bf16 v[28:31], v[36:39], v[228:231], v[28:31]
	s_nop 3
	ds_write2_b32 v237, v0, v4 offset0:0 offset1:16
	ds_write2_b32 v237, v8, v12 offset0:32 offset1:48
	ds_write2_b32 v237, v1, v5 offset0:64 offset1:80
	ds_write2_b32 v237, v9, v13 offset0:96 offset1:112
	ds_write2_b32 v237, v2, v6 offset0:128 offset1:144
	ds_write2_b32 v237, v10, v14 offset0:160 offset1:176
	ds_write2_b32 v237, v3, v7 offset0:192 offset1:208
	ds_write2_b32 v237, v11, v15 offset0:224 offset1:240
	ds_write2_b32 v238, v16, v20 offset0:0 offset1:16
	ds_write2_b32 v238, v24, v28 offset0:32 offset1:48
	ds_write2_b32 v238, v17, v21 offset0:64 offset1:80
	ds_write2_b32 v238, v25, v29 offset0:96 offset1:112
	ds_write2_b32 v238, v18, v22 offset0:128 offset1:144
	ds_write2_b32 v238, v26, v30 offset0:160 offset1:176
	ds_write2_b32 v238, v19, v23 offset0:192 offset1:208
	ds_write2_b32 v238, v27, v31 offset0:224 offset1:240
	s_waitcnt lgkmcnt(0)
	ds_read2st64_b32 v[0:1], v239 offset0:36 offset1:37
	ds_read2st64_b32 v[2:3], v239 offset0:38 offset1:39
	ds_read2st64_b32 v[4:5], v239 offset0:40 offset1:41
	ds_read2st64_b32 v[6:7], v239 offset0:42 offset1:43
	ds_read2st64_b32 v[8:9], v239 offset0:44 offset1:45
	ds_read2st64_b32 v[10:11], v239 offset0:46 offset1:47
	ds_read2st64_b32 v[12:13], v239 offset0:48 offset1:49
	ds_read2st64_b32 v[14:15], v239 offset0:50 offset1:51
	ds_read2st64_b32 v[16:17], v239 offset0:52 offset1:53
	ds_read2st64_b32 v[18:19], v239 offset0:54 offset1:55
	ds_read2st64_b32 v[20:21], v239 offset0:56 offset1:57
	ds_read2st64_b32 v[22:23], v239 offset0:58 offset1:59
	ds_read2st64_b32 v[24:25], v239 offset0:60 offset1:61
	ds_read2st64_b32 v[26:27], v239 offset0:62 offset1:63
	ds_read2st64_b32 v[28:29], v239 offset0:64 offset1:65
	ds_read2st64_b32 v[30:31], v239 offset0:66 offset1:67
	ds_read_u16_d16_hi v48, v240 offset:4608
	ds_read_u16_d16_hi v49, v240 offset:4752
	ds_read_u16_d16_hi v50, v240 offset:4896
	ds_read_u16_d16_hi v51, v240 offset:5040
	ds_read_u16_d16_hi v52, v240 offset:5184
	ds_read_u16_d16_hi v53, v240 offset:5328
	ds_read_u16_d16_hi v54, v240 offset:5472
	ds_read_u16_d16_hi v55, v240 offset:5616
	ds_read_u16_d16_hi v56, v240 offset:5760
	ds_read_u16_d16_hi v57, v240 offset:5904
	ds_read_u16_d16_hi v58, v240 offset:6048
	ds_read_u16_d16_hi v59, v240 offset:6192
	ds_read_u16_d16_hi v60, v240 offset:6336
	ds_read_u16_d16_hi v61, v240 offset:6480
	ds_read_u16_d16_hi v62, v240 offset:6624
	ds_read_u16_d16_hi v63, v240 offset:6768
	s_waitcnt lgkmcnt(0)
; __device__ __forceinline__ unsigned f2bf(float f) { unsigned r; asm("v_cvt_pk_bf16_f32 %0, %1, %1" : "=v"(r) : "v"(f)); return r & 0xffffu; }
; __device__ __forceinline__ float sigmoid_f(float x) { return rcpf_(1.f + __expf(-x)); }
; __device__ __forceinline__ float gelu_tanh_f(float x) { const float y = 0.7978845608028654f * (x + 0.044715f * x * x * x); return x * sigmoid_f(2.f * y); }
; template <bool FINAL, int D>
; __device__ __forceinline__ void rg_dir(PREF p, int l, int h, int ch, int sidx, int rowbase  , LAS bf16_t* sXc, LAS float* stg, int lane) {
;     ...
;         for (int ti = 0; ti < 16; ++ti) { const int tk = D ? 15 - ti : ti;
;             const float zr = stg[tk * 64 + lane] + ba, zi = stg[1024 + tk * 64 + lane] + bi;
;             const float r = sigmoid_f(zr), ig = sigmoid_f(zi);
;             const float a = __builtin_amdgcn_exp2f(r * sp8);
;             const float xc = bf2f(sXc[(mt * 16 + tk) * 72 + lane]);
;             av[ti] = a; iv[ti] = __builtin_amdgcn_sqrtf(fmaxf(1.f - a * a, 0.f)) * ig * xc;
;             if (FINAL && D == 1) grv[ti] = gelu_tanh_f(grv[ti]);
;         }
; #pragma unroll
;         for (int ti = 0; ti < 16; ++ti) { const int tk = D ? 15 - ti : ti;
;             hc = av[ti] * hc + iv[ti]; Ap *= av[ti];
;             if (FINAL) { const size_t row = (size_t)(rowbase + mt * 16 + tk);
;                 if (D == 0) TMP[row * 512 + ch] = (bf16_t)f2bf(hc);
;                 else MIX[row * DM + ch] = (bf16_t)f2bf(grv[ti] * (hfv[ti] + hc)); }
	v_pk_fma_f32 v[0:1], v[0:1], v[248:249], v[242:243]
	v_pk_fma_f32 v[2:3], v[2:3], v[248:249], v[242:243]
	v_pk_fma_f32 v[4:5], v[4:5], v[248:249], v[242:243]
	v_pk_fma_f32 v[6:7], v[6:7], v[248:249], v[242:243]
	v_pk_fma_f32 v[8:9], v[8:9], v[248:249], v[242:243]
	v_pk_fma_f32 v[10:11], v[10:11], v[248:249], v[242:243]
	v_pk_fma_f32 v[12:13], v[12:13], v[248:249], v[242:243]
	v_pk_fma_f32 v[14:15], v[14:15], v[248:249], v[242:243]
	v_pk_fma_f32 v[16:17], v[16:17], v[248:249], v[244:245]
	v_pk_fma_f32 v[18:19], v[18:19], v[248:249], v[244:245]
	v_pk_fma_f32 v[20:21], v[20:21], v[248:249], v[244:245]
	v_pk_fma_f32 v[22:23], v[22:23], v[248:249], v[244:245]
	v_pk_fma_f32 v[24:25], v[24:25], v[248:249], v[244:245]
	v_pk_fma_f32 v[26:27], v[26:27], v[248:249], v[244:245]
	v_pk_fma_f32 v[28:29], v[28:29], v[248:249], v[244:245]
	v_pk_fma_f32 v[30:31], v[30:31], v[248:249], v[244:245]
	v_exp_f32_e32 v0, v0
	v_exp_f32_e32 v1, v1
	v_exp_f32_e32 v2, v2
	v_exp_f32_e32 v3, v3
	v_exp_f32_e32 v4, v4
	v_exp_f32_e32 v5, v5
	v_exp_f32_e32 v6, v6
	v_exp_f32_e32 v7, v7
	v_exp_f32_e32 v8, v8
	v_exp_f32_e32 v9, v9
	v_exp_f32_e32 v10, v10
	v_exp_f32_e32 v11, v11
	v_exp_f32_e32 v12, v12
	v_exp_f32_e32 v13, v13
	v_exp_f32_e32 v14, v14
	v_exp_f32_e32 v15, v15
	v_exp_f32_e32 v16, v16
	v_exp_f32_e32 v17, v17
	v_exp_f32_e32 v18, v18
	v_exp_f32_e32 v19, v19
	v_exp_f32_e32 v20, v20
	v_exp_f32_e32 v21, v21
	v_exp_f32_e32 v22, v22
	v_exp_f32_e32 v23, v23
	v_exp_f32_e32 v24, v24
	v_exp_f32_e32 v25, v25
	v_exp_f32_e32 v26, v26
	v_exp_f32_e32 v27, v27
	v_exp_f32_e32 v28, v28
	v_exp_f32_e32 v29, v29
	v_exp_f32_e32 v30, v30
	v_exp_f32_e32 v31, v31
	v_pk_add_f32 v[0:1], v[0:1], 1.0 op_sel_hi:[1,0]
	v_pk_add_f32 v[2:3], v[2:3], 1.0 op_sel_hi:[1,0]
	v_pk_add_f32 v[4:5], v[4:5], 1.0 op_sel_hi:[1,0]
	v_pk_add_f32 v[6:7], v[6:7], 1.0 op_sel_hi:[1,0]
	v_pk_add_f32 v[8:9], v[8:9], 1.0 op_sel_hi:[1,0]
	v_pk_add_f32 v[10:11], v[10:11], 1.0 op_sel_hi:[1,0]
	v_pk_add_f32 v[12:13], v[12:13], 1.0 op_sel_hi:[1,0]
	v_pk_add_f32 v[14:15], v[14:15], 1.0 op_sel_hi:[1,0]
	v_pk_add_f32 v[16:17], v[16:17], 1.0 op_sel_hi:[1,0]
	v_pk_add_f32 v[18:19], v[18:19], 1.0 op_sel_hi:[1,0]
	v_pk_add_f32 v[20:21], v[20:21], 1.0 op_sel_hi:[1,0]
	v_pk_add_f32 v[22:23], v[22:23], 1.0 op_sel_hi:[1,0]
	v_pk_add_f32 v[24:25], v[24:25], 1.0 op_sel_hi:[1,0]
	v_pk_add_f32 v[26:27], v[26:27], 1.0 op_sel_hi:[1,0]
	v_pk_add_f32 v[28:29], v[28:29], 1.0 op_sel_hi:[1,0]
	v_pk_add_f32 v[30:31], v[30:31], 1.0 op_sel_hi:[1,0]
	v_rcp_f32_e32 v0, v0
	v_rcp_f32_e32 v1, v1
	v_rcp_f32_e32 v2, v2
	v_rcp_f32_e32 v3, v3
	v_rcp_f32_e32 v4, v4
	v_rcp_f32_e32 v5, v5
	v_rcp_f32_e32 v6, v6
	v_rcp_f32_e32 v7, v7
	v_rcp_f32_e32 v8, v8
	v_rcp_f32_e32 v9, v9
	v_rcp_f32_e32 v10, v10
	v_rcp_f32_e32 v11, v11
	v_rcp_f32_e32 v12, v12
	v_rcp_f32_e32 v13, v13
	v_rcp_f32_e32 v14, v14
	v_rcp_f32_e32 v15, v15
	v_rcp_f32_e32 v16, v16
	v_rcp_f32_e32 v17, v17
	v_rcp_f32_e32 v18, v18
	v_rcp_f32_e32 v19, v19
	v_rcp_f32_e32 v20, v20
	v_rcp_f32_e32 v21, v21
	v_rcp_f32_e32 v22, v22
	v_rcp_f32_e32 v23, v23
	v_rcp_f32_e32 v24, v24
	v_rcp_f32_e32 v25, v25
	v_rcp_f32_e32 v26, v26
	v_rcp_f32_e32 v27, v27
	v_rcp_f32_e32 v28, v28
	v_rcp_f32_e32 v29, v29
	v_rcp_f32_e32 v30, v30
	v_rcp_f32_e32 v31, v31
	v_pk_mul_f32 v[0:1], v[246:247], v[0:1]
	v_pk_mul_f32 v[2:3], v[246:247], v[2:3]
	v_pk_mul_f32 v[4:5], v[246:247], v[4:5]
	v_pk_mul_f32 v[6:7], v[246:247], v[6:7]
	v_pk_mul_f32 v[8:9], v[246:247], v[8:9]
	v_pk_mul_f32 v[10:11], v[246:247], v[10:11]
	v_pk_mul_f32 v[12:13], v[246:247], v[12:13]
	v_pk_mul_f32 v[14:15], v[246:247], v[14:15]
	v_exp_f32_e32 v0, v0
	v_exp_f32_e32 v1, v1
	v_exp_f32_e32 v2, v2
	v_exp_f32_e32 v3, v3
	v_exp_f32_e32 v4, v4
	v_exp_f32_e32 v5, v5
	v_exp_f32_e32 v6, v6
	v_exp_f32_e32 v7, v7
	v_exp_f32_e32 v8, v8
	v_exp_f32_e32 v9, v9
	v_exp_f32_e32 v10, v10
	v_exp_f32_e32 v11, v11
	v_exp_f32_e32 v12, v12
	v_exp_f32_e32 v13, v13
	v_exp_f32_e32 v14, v14
	v_exp_f32_e32 v15, v15
	v_fma_f32 v32, -v0, v0, 1.0 clamp
	v_fma_f32 v33, -v1, v1, 1.0 clamp
	v_fma_f32 v34, -v2, v2, 1.0 clamp
	v_fma_f32 v35, -v3, v3, 1.0 clamp
	v_fma_f32 v36, -v4, v4, 1.0 clamp
	v_fma_f32 v37, -v5, v5, 1.0 clamp
	v_fma_f32 v38, -v6, v6, 1.0 clamp
	v_fma_f32 v39, -v7, v7, 1.0 clamp
	v_fma_f32 v40, -v8, v8, 1.0 clamp
	v_fma_f32 v41, -v9, v9, 1.0 clamp
	v_fma_f32 v42, -v10, v10, 1.0 clamp
	v_fma_f32 v43, -v11, v11, 1.0 clamp
	v_fma_f32 v44, -v12, v12, 1.0 clamp
	v_fma_f32 v45, -v13, v13, 1.0 clamp
	v_fma_f32 v46, -v14, v14, 1.0 clamp
	v_fma_f32 v47, -v15, v15, 1.0 clamp
	v_sqrt_f32_e32 v32, v32
	v_sqrt_f32_e32 v33, v33
	v_sqrt_f32_e32 v34, v34
	v_sqrt_f32_e32 v35, v35
	v_sqrt_f32_e32 v36, v36
	v_sqrt_f32_e32 v37, v37
	v_sqrt_f32_e32 v38, v38
	v_sqrt_f32_e32 v39, v39
	v_sqrt_f32_e32 v40, v40
	v_sqrt_f32_e32 v41, v41
	v_sqrt_f32_e32 v42, v42
	v_sqrt_f32_e32 v43, v43
	v_sqrt_f32_e32 v44, v44
	v_sqrt_f32_e32 v45, v45
	v_sqrt_f32_e32 v46, v46
	v_sqrt_f32_e32 v47, v47
	s_nop 0
	v_pk_mul_f32 v[16:17], v[16:17], v[32:33]
	v_pk_mul_f32 v[18:19], v[18:19], v[34:35]
	v_pk_mul_f32 v[20:21], v[20:21], v[36:37]
	v_pk_mul_f32 v[22:23], v[22:23], v[38:39]
	v_pk_mul_f32 v[24:25], v[24:25], v[40:41]
	v_pk_mul_f32 v[26:27], v[26:27], v[42:43]
	v_pk_mul_f32 v[28:29], v[28:29], v[44:45]
	v_pk_mul_f32 v[30:31], v[30:31], v[46:47]
	v_pk_mul_f32 v[16:17], v[16:17], v[48:49]
	v_pk_mul_f32 v[18:19], v[18:19], v[50:51]
	v_pk_mul_f32 v[20:21], v[20:21], v[52:53]
	v_pk_mul_f32 v[22:23], v[22:23], v[54:55]
	v_pk_mul_f32 v[24:25], v[24:25], v[56:57]
	v_pk_mul_f32 v[26:27], v[26:27], v[58:59]
	v_pk_mul_f32 v[28:29], v[28:29], v[60:61]
	v_pk_mul_f32 v[30:31], v[30:31], v[62:63]
	v_fma_f32 v32, v0, v250, v16
	v_fma_f32 v250, v1, v32, v17
	v_cvt_pk_bf16_f32 v174, v32, v250
	v_fma_f32 v32, v2, v250, v18
	v_fma_f32 v250, v3, v32, v19
	v_cvt_pk_bf16_f32 v175, v32, v250
	v_fma_f32 v32, v4, v250, v20
	v_fma_f32 v250, v5, v32, v21
	v_cvt_pk_bf16_f32 v176, v32, v250
	v_fma_f32 v32, v6, v250, v22
	v_fma_f32 v250, v7, v32, v23
	v_cvt_pk_bf16_f32 v177, v32, v250
	v_fma_f32 v32, v8, v250, v24
	v_fma_f32 v250, v9, v32, v25
	v_cvt_pk_bf16_f32 v178, v32, v250
	v_fma_f32 v32, v10, v250, v26
	v_fma_f32 v250, v11, v32, v27
	v_cvt_pk_bf16_f32 v179, v32, v250
	v_fma_f32 v32, v12, v250, v28
	v_fma_f32 v250, v13, v32, v29
	v_cvt_pk_bf16_f32 v180, v32, v250
	v_fma_f32 v32, v14, v250, v30
	v_fma_f32 v250, v15, v32, v31
	v_cvt_pk_bf16_f32 v181, v32, v250
	ds_read_b128 v[32:35], v236 offset:6912
	ds_read_b128 v[36:39], v236 offset:6976
	s_waitcnt lgkmcnt(0)
; #define LAS __attribute__((address_space(3)))
; #define WAVE_SYNC() asm volatile("s_waitcnt lgkmcnt(0)" ::: "memory")
; __device__ __forceinline__ f32x4 mfma16(bf16x8 a, bf16x8 b, f32x4 c) { return __builtin_amdgcn_mfma_f32_16x16x32_bf16(a, b, c, 0, 0, 0); }
; template <bool FINAL, int D>
; __device__ __forceinline__ void rg_dir(PREF p, int l, int h, int ch, int sidx, int rowbase  , LAS bf16_t* sXc, LAS float* stg, int lane) {
;     ...
;     for (int nt = 0; nt < 4; ++nt) { const int o0 = (nt * 16 + (lane & 15)) * 64 + (lane >> 4) * 8;
;         Br[nt][0] = *(const bf16x8*)(wr_ + o0); Br[nt][1] = *(const bf16x8*)(wr_ + o0 + 32); Bi[nt][0] = *(const bf16x8*)(wi_ + o0); Bi[nt][1] = *(const bf16x8*)(wi_ + o0 + 32); }
;     ...
;         const bf16x8 A0 = *(const LAS bf16x8*)(sXc + (mt * 16 + (lane & 15)) * 72 + (lane >> 4) * 8), A1 = *(const LAS bf16x8*)(sXc + (mt * 16 + (lane & 15)) * 72 + 32 + (lane >> 4) * 8);
;         f32x4 ar[4], ai[4];
; #pragma unroll
;         for (int nt = 0; nt < 4; ++nt) { const f32x4 z = {0.f, 0.f, 0.f, 0.f};
;             ar[nt] = mfma16(A0, Br[nt][0], z); ar[nt] = mfma16(A1, Br[nt][1], ar[nt]); ai[nt] = mfma16(A0, Bi[nt][0], z); ai[nt] = mfma16(A1, Bi[nt][1], ai[nt]); }
;         WAVE_SYNC();
; #pragma unroll
;         for (int nt = 0; nt < 4; ++nt)
; #pragma unroll
;             for (int j = 0; j < 4; ++j) { const int o = ((lane >> 4) * 4 + j) * 64 + nt * 16 + (lane & 15); stg[o] = ar[nt][j]; stg[1024 + o] = ai[nt][j]; }
;         WAVE_SYNC();
	v_mfma_f32_16x16x32_bf16 v[0:3], v[32:35], v[80:83], 0
	v_mfma_f32_16x16x32_bf16 v[4:7], v[32:35], v[88:91], 0
	v_mfma_f32_16x16x32_bf16 v[8:11], v[32:35], v[96:99], 0
	v_mfma_f32_16x16x32_bf16 v[12:15], v[32:35], v[104:107], 0
	v_mfma_f32_16x16x32_bf16 v[16:19], v[32:35], v[112:115], 0
	v_mfma_f32_16x16x32_bf16 v[20:23], v[32:35], v[120:123], 0
	v_mfma_f32_16x16x32_bf16 v[24:27], v[32:35], v[128:131], 0
	v_mfma_f32_16x16x32_bf16 v[28:31], v[32:35], v[136:139], 0
	v_mfma_f32_16x16x32_bf16 v[0:3], v[36:39], v[84:87], v[0:3]
	v_mfma_f32_16x16x32_bf16 v[4:7], v[36:39], v[92:95], v[4:7]
	v_mfma_f32_16x16x32_bf16 v[8:11], v[36:39], v[100:103], v[8:11]
	v_mfma_f32_16x16x32_bf16 v[12:15], v[36:39], v[108:111], v[12:15]
	v_mfma_f32_16x16x32_bf16 v[16:19], v[36:39], v[116:119], v[16:19]
	v_mfma_f32_16x16x32_bf16 v[20:23], v[36:39], v[124:127], v[20:23]
	v_mfma_f32_16x16x32_bf16 v[24:27], v[36:39], v[132:135], v[24:27]
	v_mfma_f32_16x16x32_bf16 v[28:31], v[36:39], v[228:231], v[28:31]
	s_nop 3
	ds_write2_b32 v237, v0, v4 offset0:0 offset1:16
	ds_write2_b32 v237, v8, v12 offset0:32 offset1:48
	ds_write2_b32 v237, v1, v5 offset0:64 offset1:80
	ds_write2_b32 v237, v9, v13 offset0:96 offset1:112
	ds_write2_b32 v237, v2, v6 offset0:128 offset1:144
	ds_write2_b32 v237, v10, v14 offset0:160 offset1:176
	ds_write2_b32 v237, v3, v7 offset0:192 offset1:208
	ds_write2_b32 v237, v11, v15 offset0:224 offset1:240
	ds_write2_b32 v238, v16, v20 offset0:0 offset1:16
	ds_write2_b32 v238, v24, v28 offset0:32 offset1:48
	ds_write2_b32 v238, v17, v21 offset0:64 offset1:80
	ds_write2_b32 v238, v25, v29 offset0:96 offset1:112
	ds_write2_b32 v238, v18, v22 offset0:128 offset1:144
	ds_write2_b32 v238, v26, v30 offset0:160 offset1:176
	ds_write2_b32 v238, v19, v23 offset0:192 offset1:208
	ds_write2_b32 v238, v27, v31 offset0:224 offset1:240
	s_waitcnt lgkmcnt(0)
	ds_read2st64_b32 v[0:1], v239 offset0:36 offset1:37
	ds_read2st64_b32 v[2:3], v239 offset0:38 offset1:39
	ds_read2st64_b32 v[4:5], v239 offset0:40 offset1:41
	ds_read2st64_b32 v[6:7], v239 offset0:42 offset1:43
	ds_read2st64_b32 v[8:9], v239 offset0:44 offset1:45
	ds_read2st64_b32 v[10:11], v239 offset0:46 offset1:47
	ds_read2st64_b32 v[12:13], v239 offset0:48 offset1:49
	ds_read2st64_b32 v[14:15], v239 offset0:50 offset1:51
	ds_read2st64_b32 v[16:17], v239 offset0:52 offset1:53
	ds_read2st64_b32 v[18:19], v239 offset0:54 offset1:55
	ds_read2st64_b32 v[20:21], v239 offset0:56 offset1:57
	ds_read2st64_b32 v[22:23], v239 offset0:58 offset1:59
	ds_read2st64_b32 v[24:25], v239 offset0:60 offset1:61
	ds_read2st64_b32 v[26:27], v239 offset0:62 offset1:63
	ds_read2st64_b32 v[28:29], v239 offset0:64 offset1:65
	ds_read2st64_b32 v[30:31], v239 offset0:66 offset1:67
	ds_read_u16_d16_hi v48, v240 offset:6912
	ds_read_u16_d16_hi v49, v240 offset:7056
	ds_read_u16_d16_hi v50, v240 offset:7200
	ds_read_u16_d16_hi v51, v240 offset:7344
	ds_read_u16_d16_hi v52, v240 offset:7488
	ds_read_u16_d16_hi v53, v240 offset:7632
	ds_read_u16_d16_hi v54, v240 offset:7776
	ds_read_u16_d16_hi v55, v240 offset:7920
	ds_read_u16_d16_hi v56, v240 offset:8064
	ds_read_u16_d16_hi v57, v240 offset:8208
	ds_read_u16_d16_hi v58, v240 offset:8352
	ds_read_u16_d16_hi v59, v240 offset:8496
	ds_read_u16_d16_hi v60, v240 offset:8640
	ds_read_u16_d16_hi v61, v240 offset:8784
	ds_read_u16_d16_hi v62, v240 offset:8928
	ds_read_u16_d16_hi v63, v240 offset:9072
	s_add_u32 s90, s92, 0x20000
	s_addc_u32 s91, s93, 0
	global_load_dwordx4 v[80:83], v241, s[90:91]
	global_load_dwordx4 v[84:87], v241, s[90:91] offset:64
	global_load_dwordx4 v[88:91], v241, s[90:91] offset:2048
	global_load_dwordx4 v[92:95], v241, s[90:91] offset:2112
	s_add_u32 s90, s92, 0x21000
	s_addc_u32 s91, s93, 0
	global_load_dwordx4 v[96:99], v241, s[90:91]
	global_load_dwordx4 v[100:103], v241, s[90:91] offset:64
	global_load_dwordx4 v[104:107], v241, s[90:91] offset:2048
	global_load_dwordx4 v[108:111], v241, s[90:91] offset:2112
	s_add_u32 s90, s92, 0x30000
	s_addc_u32 s91, s93, 0
	global_load_dwordx4 v[112:115], v241, s[90:91]
	global_load_dwordx4 v[116:119], v241, s[90:91] offset:64
	global_load_dwordx4 v[120:123], v241, s[90:91] offset:2048
	global_load_dwordx4 v[124:127], v241, s[90:91] offset:2112
	s_add_u32 s90, s92, 0x31000
	s_addc_u32 s91, s93, 0
	global_load_dwordx4 v[128:131], v241, s[90:91]
	global_load_dwordx4 v[132:135], v241, s[90:91] offset:64
	global_load_dwordx4 v[136:139], v241, s[90:91] offset:2048
	global_load_dwordx4 v[228:231], v241, s[90:91] offset:2112
	s_waitcnt lgkmcnt(0)
; __device__ __forceinline__ unsigned f2bf(float f) { unsigned r; asm("v_cvt_pk_bf16_f32 %0, %1, %1" : "=v"(r) : "v"(f)); return r & 0xffffu; }
; __device__ __forceinline__ float sigmoid_f(float x) { return rcpf_(1.f + __expf(-x)); }
; __device__ __forceinline__ float gelu_tanh_f(float x) { const float y = 0.7978845608028654f * (x + 0.044715f * x * x * x); return x * sigmoid_f(2.f * y); }
; template <bool FINAL, int D>
; __device__ __forceinline__ void rg_dir(PREF p, int l, int h, int ch, int sidx, int rowbase  , LAS bf16_t* sXc, LAS float* stg, int lane) {
;     ...
;     const float ba = p.rg_ba[(l * 2 + D) * 512 + ch], bi = p.rg_bi[(l * 2 + D) * 512 + ch], lam = p.rg_lam[(l * 2 + D) * 512 + ch];
;     ...
;         for (int ti = 0; ti < 16; ++ti) { const int tk = D ? 15 - ti : ti;
;             const float zr = stg[tk * 64 + lane] + ba, zi = stg[1024 + tk * 64 + lane] + bi;
;             const float r = sigmoid_f(zr), ig = sigmoid_f(zi);
;             const float a = __builtin_amdgcn_exp2f(r * sp8);
;             const float xc = bf2f(sXc[(mt * 16 + tk) * 72 + lane]);
;             av[ti] = a; iv[ti] = __builtin_amdgcn_sqrtf(fmaxf(1.f - a * a, 0.f)) * ig * xc;
;             if (FINAL && D == 1) grv[ti] = gelu_tanh_f(grv[ti]);
;         }
; #pragma unroll
;         for (int ti = 0; ti < 16; ++ti) { const int tk = D ? 15 - ti : ti;
;             hc = av[ti] * hc + iv[ti]; Ap *= av[ti];
;             if (FINAL) { const size_t row = (size_t)(rowbase + mt * 16 + tk);
;                 if (D == 0) TMP[row * 512 + ch] = (bf16_t)f2bf(hc);
;                 else MIX[row * DM + ch] = (bf16_t)f2bf(grv[ti] * (hfv[ti] + hc)); }
	v_pk_fma_f32 v[0:1], v[0:1], v[248:249], v[242:243]
	v_pk_fma_f32 v[2:3], v[2:3], v[248:249], v[242:243]
	v_pk_fma_f32 v[4:5], v[4:5], v[248:249], v[242:243]
	v_pk_fma_f32 v[6:7], v[6:7], v[248:249], v[242:243]
	v_pk_fma_f32 v[8:9], v[8:9], v[248:249], v[242:243]
	v_pk_fma_f32 v[10:11], v[10:11], v[248:249], v[242:243]
	v_pk_fma_f32 v[12:13], v[12:13], v[248:249], v[242:243]
	v_pk_fma_f32 v[14:15], v[14:15], v[248:249], v[242:243]
	v_pk_fma_f32 v[16:17], v[16:17], v[248:249], v[244:245]
	v_pk_fma_f32 v[18:19], v[18:19], v[248:249], v[244:245]
	v_pk_fma_f32 v[20:21], v[20:21], v[248:249], v[244:245]
	v_pk_fma_f32 v[22:23], v[22:23], v[248:249], v[244:245]
	v_pk_fma_f32 v[24:25], v[24:25], v[248:249], v[244:245]
	v_pk_fma_f32 v[26:27], v[26:27], v[248:249], v[244:245]
	v_pk_fma_f32 v[28:29], v[28:29], v[248:249], v[244:245]
	v_pk_fma_f32 v[30:31], v[30:31], v[248:249], v[244:245]
	v_exp_f32_e32 v0, v0
	v_exp_f32_e32 v1, v1
	v_exp_f32_e32 v2, v2
	v_exp_f32_e32 v3, v3
	v_exp_f32_e32 v4, v4
	v_exp_f32_e32 v5, v5
	v_exp_f32_e32 v6, v6
	v_exp_f32_e32 v7, v7
	v_exp_f32_e32 v8, v8
	v_exp_f32_e32 v9, v9
	v_exp_f32_e32 v10, v10
	v_exp_f32_e32 v11, v11
	v_exp_f32_e32 v12, v12
	v_exp_f32_e32 v13, v13
	v_exp_f32_e32 v14, v14
	v_exp_f32_e32 v15, v15
	v_exp_f32_e32 v16, v16
	v_exp_f32_e32 v17, v17
	v_exp_f32_e32 v18, v18
	v_exp_f32_e32 v19, v19
	v_exp_f32_e32 v20, v20
	v_exp_f32_e32 v21, v21
	v_exp_f32_e32 v22, v22
	v_exp_f32_e32 v23, v23
	v_exp_f32_e32 v24, v24
	v_exp_f32_e32 v25, v25
	v_exp_f32_e32 v26, v26
	v_exp_f32_e32 v27, v27
	v_exp_f32_e32 v28, v28
	v_exp_f32_e32 v29, v29
	v_exp_f32_e32 v30, v30
	v_exp_f32_e32 v31, v31
	v_pk_add_f32 v[0:1], v[0:1], 1.0 op_sel_hi:[1,0]
	v_pk_add_f32 v[2:3], v[2:3], 1.0 op_sel_hi:[1,0]
	v_pk_add_f32 v[4:5], v[4:5], 1.0 op_sel_hi:[1,0]
	v_pk_add_f32 v[6:7], v[6:7], 1.0 op_sel_hi:[1,0]
	v_pk_add_f32 v[8:9], v[8:9], 1.0 op_sel_hi:[1,0]
	v_pk_add_f32 v[10:11], v[10:11], 1.0 op_sel_hi:[1,0]
	v_pk_add_f32 v[12:13], v[12:13], 1.0 op_sel_hi:[1,0]
	v_pk_add_f32 v[14:15], v[14:15], 1.0 op_sel_hi:[1,0]
	v_pk_add_f32 v[16:17], v[16:17], 1.0 op_sel_hi:[1,0]
	v_pk_add_f32 v[18:19], v[18:19], 1.0 op_sel_hi:[1,0]
	v_pk_add_f32 v[20:21], v[20:21], 1.0 op_sel_hi:[1,0]
	v_pk_add_f32 v[22:23], v[22:23], 1.0 op_sel_hi:[1,0]
	v_pk_add_f32 v[24:25], v[24:25], 1.0 op_sel_hi:[1,0]
	v_pk_add_f32 v[26:27], v[26:27], 1.0 op_sel_hi:[1,0]
	v_pk_add_f32 v[28:29], v[28:29], 1.0 op_sel_hi:[1,0]
	v_pk_add_f32 v[30:31], v[30:31], 1.0 op_sel_hi:[1,0]
	v_rcp_f32_e32 v0, v0
	v_rcp_f32_e32 v1, v1
	v_rcp_f32_e32 v2, v2
	v_rcp_f32_e32 v3, v3
	v_rcp_f32_e32 v4, v4
	v_rcp_f32_e32 v5, v5
	v_rcp_f32_e32 v6, v6
	v_rcp_f32_e32 v7, v7
	v_rcp_f32_e32 v8, v8
	v_rcp_f32_e32 v9, v9
	v_rcp_f32_e32 v10, v10
	v_rcp_f32_e32 v11, v11
	v_rcp_f32_e32 v12, v12
	v_rcp_f32_e32 v13, v13
	v_rcp_f32_e32 v14, v14
	v_rcp_f32_e32 v15, v15
	v_rcp_f32_e32 v16, v16
	v_rcp_f32_e32 v17, v17
	v_rcp_f32_e32 v18, v18
	v_rcp_f32_e32 v19, v19
	v_rcp_f32_e32 v20, v20
	v_rcp_f32_e32 v21, v21
	v_rcp_f32_e32 v22, v22
	v_rcp_f32_e32 v23, v23
	v_rcp_f32_e32 v24, v24
	v_rcp_f32_e32 v25, v25
	v_rcp_f32_e32 v26, v26
	v_rcp_f32_e32 v27, v27
	v_rcp_f32_e32 v28, v28
	v_rcp_f32_e32 v29, v29
	v_rcp_f32_e32 v30, v30
	v_rcp_f32_e32 v31, v31
	v_pk_mul_f32 v[0:1], v[246:247], v[0:1]
	v_pk_mul_f32 v[2:3], v[246:247], v[2:3]
	v_pk_mul_f32 v[4:5], v[246:247], v[4:5]
	v_pk_mul_f32 v[6:7], v[246:247], v[6:7]
	v_pk_mul_f32 v[8:9], v[246:247], v[8:9]
	v_pk_mul_f32 v[10:11], v[246:247], v[10:11]
	v_pk_mul_f32 v[12:13], v[246:247], v[12:13]
	v_pk_mul_f32 v[14:15], v[246:247], v[14:15]
	v_exp_f32_e32 v0, v0
	v_exp_f32_e32 v1, v1
	v_exp_f32_e32 v2, v2
	v_exp_f32_e32 v3, v3
	v_exp_f32_e32 v4, v4
	v_exp_f32_e32 v5, v5
	v_exp_f32_e32 v6, v6
	v_exp_f32_e32 v7, v7
	v_exp_f32_e32 v8, v8
	v_exp_f32_e32 v9, v9
	v_exp_f32_e32 v10, v10
	v_exp_f32_e32 v11, v11
	v_exp_f32_e32 v12, v12
	v_exp_f32_e32 v13, v13
	v_exp_f32_e32 v14, v14
	v_exp_f32_e32 v15, v15
	v_fma_f32 v32, -v0, v0, 1.0 clamp
	v_fma_f32 v33, -v1, v1, 1.0 clamp
	v_fma_f32 v34, -v2, v2, 1.0 clamp
	v_fma_f32 v35, -v3, v3, 1.0 clamp
	v_fma_f32 v36, -v4, v4, 1.0 clamp
	v_fma_f32 v37, -v5, v5, 1.0 clamp
	v_fma_f32 v38, -v6, v6, 1.0 clamp
	v_fma_f32 v39, -v7, v7, 1.0 clamp
	v_fma_f32 v40, -v8, v8, 1.0 clamp
	v_fma_f32 v41, -v9, v9, 1.0 clamp
	v_fma_f32 v42, -v10, v10, 1.0 clamp
	v_fma_f32 v43, -v11, v11, 1.0 clamp
	v_fma_f32 v44, -v12, v12, 1.0 clamp
	v_fma_f32 v45, -v13, v13, 1.0 clamp
	v_fma_f32 v46, -v14, v14, 1.0 clamp
	v_fma_f32 v47, -v15, v15, 1.0 clamp
	v_sqrt_f32_e32 v32, v32
	v_sqrt_f32_e32 v33, v33
	v_sqrt_f32_e32 v34, v34
	v_sqrt_f32_e32 v35, v35
	v_sqrt_f32_e32 v36, v36
	v_sqrt_f32_e32 v37, v37
	v_sqrt_f32_e32 v38, v38
	v_sqrt_f32_e32 v39, v39
	v_sqrt_f32_e32 v40, v40
	v_sqrt_f32_e32 v41, v41
	v_sqrt_f32_e32 v42, v42
	v_sqrt_f32_e32 v43, v43
	v_sqrt_f32_e32 v44, v44
	v_sqrt_f32_e32 v45, v45
	v_sqrt_f32_e32 v46, v46
	v_sqrt_f32_e32 v47, v47
	s_nop 0
	v_pk_mul_f32 v[16:17], v[16:17], v[32:33]
	v_pk_mul_f32 v[18:19], v[18:19], v[34:35]
	v_pk_mul_f32 v[20:21], v[20:21], v[36:37]
	v_pk_mul_f32 v[22:23], v[22:23], v[38:39]
	v_pk_mul_f32 v[24:25], v[24:25], v[40:41]
	v_pk_mul_f32 v[26:27], v[26:27], v[42:43]
	v_pk_mul_f32 v[28:29], v[28:29], v[44:45]
	v_pk_mul_f32 v[30:31], v[30:31], v[46:47]
	v_pk_mul_f32 v[16:17], v[16:17], v[48:49]
	v_pk_mul_f32 v[18:19], v[18:19], v[50:51]
	v_pk_mul_f32 v[20:21], v[20:21], v[52:53]
	v_pk_mul_f32 v[22:23], v[22:23], v[54:55]
	v_pk_mul_f32 v[24:25], v[24:25], v[56:57]
	v_pk_mul_f32 v[26:27], v[26:27], v[58:59]
	v_pk_mul_f32 v[28:29], v[28:29], v[60:61]
	v_pk_mul_f32 v[30:31], v[30:31], v[62:63]
	global_load_dword v45, v235, s[76:77] offset:2048
	global_load_dword v46, v235, s[78:79] offset:2048
	global_load_dword v47, v235, s[80:81] offset:2048
	global_load_dword v251, v235, s[96:97] offset:2048
	v_fma_f32 v32, v0, v250, v16
	v_fma_f32 v250, v1, v32, v17
	v_cvt_pk_bf16_f32 v182, v32, v250
	v_fma_f32 v32, v2, v250, v18
	v_fma_f32 v250, v3, v32, v19
	v_cvt_pk_bf16_f32 v183, v32, v250
	v_fma_f32 v32, v4, v250, v20
	v_fma_f32 v250, v5, v32, v21
	v_cvt_pk_bf16_f32 v184, v32, v250
	v_fma_f32 v32, v6, v250, v22
	v_fma_f32 v250, v7, v32, v23
	v_cvt_pk_bf16_f32 v185, v32, v250
	v_fma_f32 v32, v8, v250, v24
	v_fma_f32 v250, v9, v32, v25
	v_cvt_pk_bf16_f32 v186, v32, v250
	v_fma_f32 v32, v10, v250, v26
	v_fma_f32 v250, v11, v32, v27
	v_cvt_pk_bf16_f32 v187, v32, v250
	v_fma_f32 v32, v12, v250, v28
	v_fma_f32 v250, v13, v32, v29
	v_cvt_pk_bf16_f32 v188, v32, v250
	v_fma_f32 v32, v14, v250, v30
	v_fma_f32 v250, v15, v32, v31
	v_cvt_pk_bf16_f32 v189, v32, v250
	s_waitcnt vmcnt(0)
; template <bool FINAL, int D>
; __device__ __forceinline__ void rg_dir(PREF p, int l, int h, int ch, int sidx, int rowbase  , LAS bf16_t* sXc, LAS float* stg, int lane) {
;     ...
;     const float ba = p.rg_ba[(l * 2 + D) * 512 + ch], bi = p.rg_bi[(l * 2 + D) * 512 + ch], lam = p.rg_lam[(l * 2 + D) * 512 + ch];
;     const float e_ = __expf(-lam), u_ = 1.f + e_;
;     const float l1p = (u_ == 1.f) ? e_ : __logf(u_) * e_ * rcpf_(u_ - 1.f);
;     const float sp8 = -8.f * 1.4426950408889634f * l1p;
;     float hc = FINAL ? RGC[sidx] : 0.f, Ap = 1.f;
;     bf16x8 Br[4][2], Bi[4][2];
; #pragma unroll
;     for (int nt = 0; nt < 4; ++nt) { const int o0 = (nt * 16 + (lane & 15)) * 64 + (lane >> 4) * 8;
;         Br[nt][0] = *(const bf16x8*)(wr_ + o0); Br[nt][1] = *(const bf16x8*)(wr_ + o0 + 32); Bi[nt][0] = *(const bf16x8*)(wi_ + o0); Bi[nt][1] = *(const bf16x8*)(wi_ + o0 + 32); }
;     if (FINAL && D == 1) asm volatile("s_waitcnt vmcnt(0)" ::: "memory");
; #pragma unroll 1
;     for (int mi = 0; mi < 4; ++mi) { const int mt = D ? 3 - mi : mi;
;         float grv[16], hfv[16];
;         if (FINAL && D == 1) {
; #pragma unroll
;             for (int ti = 0; ti < 16; ++ti) { const size_t row = (size_t)(rowbase + mt * 16 + 15 - ti); grv[ti] = __builtin_bit_cast(float, (unsigned)P[row * PW + 512 + ch]); hfv[ti] = __builtin_bit_cast(float, (unsigned)TMP[row * 512 + ch]); }
;             __builtin_amdgcn_sched_barrier(0);
; #pragma unroll
;             for (int ti = 0; ti < 16; ++ti) { grv[ti] = bf2f(__builtin_bit_cast(unsigned, grv[ti])); hfv[ti] = bf2f(__builtin_bit_cast(unsigned, hfv[ti])); }
;         }
;         const bf16x8 A0 = *(const LAS bf16x8*)(sXc + (mt * 16 + (lane & 15)) * 72 + (lane >> 4) * 8), A1 = *(const LAS bf16x8*)(sXc + (mt * 16 + (lane & 15)) * 72 + 32 + (lane >> 4) * 8);
;         f32x4 ar[4], ai[4];
; #pragma unroll
;         for (int nt = 0; nt < 4; ++nt) { const f32x4 z = {0.f, 0.f, 0.f, 0.f};
;             ar[nt] = mfma16(A0, Br[nt][0], z); ar[nt] = mfma16(A1, Br[nt][1], ar[nt]); ai[nt] = mfma16(A0, Bi[nt][0], z); ai[nt] = mfma16(A1, Bi[nt][1], ai[nt]); }
;         WAVE_SYNC();
; #pragma unroll
;         for (int nt = 0; nt < 4; ++nt)
; #pragma unroll
;             for (int j = 0; j < 4; ++j) { const int o = ((lane >> 4) * 4 + j) * 64 + nt * 16 + (lane & 15); stg[o] = ar[nt][j]; stg[1024 + o] = ai[nt][j]; }
;         WAVE_SYNC();
	s_mov_b32 s8, 0x800000
	s_mov_b32 s9, 0x3f317217
	s_mov_b32 s14, 0x7f800000
	v_mul_f32_e32 v32, 0xbfb8aa3b, v45
	v_exp_f32_e32 v32, v32
	s_nop 0
	v_add_f32_e32 v33, 1.0, v32
	v_cmp_gt_f32_e32 vcc, s8, v33
	s_nop 1
	v_cndmask_b32_e64 v34, 0, 32, vcc
	v_ldexp_f32 v34, v33, v34
	v_log_f32_e32 v34, v34
	v_cndmask_b32_e32 v36, 0, v226, vcc
	v_cmp_eq_f32_e32 vcc, 1.0, v33
	v_mul_f32_e32 v35, 0x3f317217, v34
	v_fma_f32 v35, v34, s9, -v35
	v_fmac_f32_e32 v35, 0x3377d1cf, v34
	v_fmac_f32_e32 v35, 0x3f317217, v34
	v_cmp_lt_f32_e64 s[10:11], |v34|, s14
	s_nop 1
	v_cndmask_b32_e64 v34, v34, v35, s[10:11]
	v_add_f32_e32 v35, -1.0, v33
	v_rcp_f32_e32 v35, v35
	v_sub_f32_e32 v34, v34, v36
	v_mul_f32_e32 v34, v32, v34
	v_mul_f32_e32 v34, v34, v35
	v_cndmask_b32_e32 v32, v34, v32, vcc
	v_mul_f32_e32 v246, 0xc138aa3b, v32
	v_mov_b32_e32 v247, v246
	v_mul_f32_e32 v242, 0xbfb8aa3b, v46
	v_mul_f32_e32 v244, 0xbfb8aa3b, v47
	v_mov_b32_e32 v243, v242
	v_mov_b32_e32 v245, v244
	v_mov_b32_e32 v250, v251
	ds_read_b128 v[32:35], v236 offset:6912
	ds_read_b128 v[36:39], v236 offset:6976
	s_waitcnt lgkmcnt(0)
	v_mfma_f32_16x16x32_bf16 v[0:3], v[32:35], v[80:83], 0
	v_mfma_f32_16x16x32_bf16 v[4:7], v[32:35], v[88:91], 0
	v_mfma_f32_16x16x32_bf16 v[8:11], v[32:35], v[96:99], 0
	v_mfma_f32_16x16x32_bf16 v[12:15], v[32:35], v[104:107], 0
	v_mfma_f32_16x16x32_bf16 v[16:19], v[32:35], v[112:115], 0
	v_mfma_f32_16x16x32_bf16 v[20:23], v[32:35], v[120:123], 0
	v_mfma_f32_16x16x32_bf16 v[24:27], v[32:35], v[128:131], 0
	v_mfma_f32_16x16x32_bf16 v[28:31], v[32:35], v[136:139], 0
	v_mfma_f32_16x16x32_bf16 v[0:3], v[36:39], v[84:87], v[0:3]
	v_mfma_f32_16x16x32_bf16 v[4:7], v[36:39], v[92:95], v[4:7]
	v_mfma_f32_16x16x32_bf16 v[8:11], v[36:39], v[100:103], v[8:11]
	v_mfma_f32_16x16x32_bf16 v[12:15], v[36:39], v[108:111], v[12:15]
	v_mfma_f32_16x16x32_bf16 v[16:19], v[36:39], v[116:119], v[16:19]
	v_mfma_f32_16x16x32_bf16 v[20:23], v[36:39], v[124:127], v[20:23]
	v_mfma_f32_16x16x32_bf16 v[24:27], v[36:39], v[132:135], v[24:27]
	v_mfma_f32_16x16x32_bf16 v[28:31], v[36:39], v[228:231], v[28:31]
	s_nop 3
	ds_write2_b32 v237, v0, v4 offset0:0 offset1:16
	ds_write2_b32 v237, v8, v12 offset0:32 offset1:48
	ds_write2_b32 v237, v1, v5 offset0:64 offset1:80
	ds_write2_b32 v237, v9, v13 offset0:96 offset1:112
	ds_write2_b32 v237, v2, v6 offset0:128 offset1:144
	ds_write2_b32 v237, v10, v14 offset0:160 offset1:176
	ds_write2_b32 v237, v3, v7 offset0:192 offset1:208
	ds_write2_b32 v237, v11, v15 offset0:224 offset1:240
	ds_write2_b32 v238, v16, v20 offset0:0 offset1:16
	ds_write2_b32 v238, v24, v28 offset0:32 offset1:48
	ds_write2_b32 v238, v17, v21 offset0:64 offset1:80
	ds_write2_b32 v238, v25, v29 offset0:96 offset1:112
	ds_write2_b32 v238, v18, v22 offset0:128 offset1:144
	ds_write2_b32 v238, v26, v30 offset0:160 offset1:176
	ds_write2_b32 v238, v19, v23 offset0:192 offset1:208
	ds_write2_b32 v238, v27, v31 offset0:224 offset1:240
	s_waitcnt lgkmcnt(0)
	ds_read2st64_b32 v[0:1], v239 offset0:36 offset1:37
	ds_read2st64_b32 v[2:3], v239 offset0:38 offset1:39
	ds_read2st64_b32 v[4:5], v239 offset0:40 offset1:41
	ds_read2st64_b32 v[6:7], v239 offset0:42 offset1:43
	ds_read2st64_b32 v[8:9], v239 offset0:44 offset1:45
	ds_read2st64_b32 v[10:11], v239 offset0:46 offset1:47
	ds_read2st64_b32 v[12:13], v239 offset0:48 offset1:49
	ds_read2st64_b32 v[14:15], v239 offset0:50 offset1:51
	ds_read2st64_b32 v[16:17], v239 offset0:52 offset1:53
	ds_read2st64_b32 v[18:19], v239 offset0:54 offset1:55
	ds_read2st64_b32 v[20:21], v239 offset0:56 offset1:57
	ds_read2st64_b32 v[22:23], v239 offset0:58 offset1:59
	ds_read2st64_b32 v[24:25], v239 offset0:60 offset1:61
	ds_read2st64_b32 v[26:27], v239 offset0:62 offset1:63
	ds_read2st64_b32 v[28:29], v239 offset0:64 offset1:65
	ds_read2st64_b32 v[30:31], v239 offset0:66 offset1:67
	ds_read_u16_d16_hi v48, v240 offset:6912
	ds_read_u16_d16_hi v49, v240 offset:7056
	ds_read_u16_d16_hi v50, v240 offset:7200
	ds_read_u16_d16_hi v51, v240 offset:7344
	ds_read_u16_d16_hi v52, v240 offset:7488
	ds_read_u16_d16_hi v53, v240 offset:7632
	ds_read_u16_d16_hi v54, v240 offset:7776
	ds_read_u16_d16_hi v55, v240 offset:7920
	ds_read_u16_d16_hi v56, v240 offset:8064
	ds_read_u16_d16_hi v57, v240 offset:8208
	ds_read_u16_d16_hi v58, v240 offset:8352
	ds_read_u16_d16_hi v59, v240 offset:8496
	ds_read_u16_d16_hi v60, v240 offset:8640
	ds_read_u16_d16_hi v61, v240 offset:8784
	ds_read_u16_d16_hi v62, v240 offset:8928
	ds_read_u16_d16_hi v63, v240 offset:9072
	v_lshlrev_b32_e32 v206, 16, v190
	v_lshlrev_b32_e32 v207, 16, v191
	v_lshlrev_b32_e32 v208, 16, v192
	v_lshlrev_b32_e32 v209, 16, v193
	v_lshlrev_b32_e32 v210, 16, v194
	v_lshlrev_b32_e32 v211, 16, v195
	v_lshlrev_b32_e32 v212, 16, v196
	v_lshlrev_b32_e32 v213, 16, v197
	v_lshlrev_b32_e32 v214, 16, v198
	v_lshlrev_b32_e32 v215, 16, v199
	v_lshlrev_b32_e32 v216, 16, v200
	v_lshlrev_b32_e32 v217, 16, v201
	v_lshlrev_b32_e32 v218, 16, v202
	v_lshlrev_b32_e32 v219, 16, v203
	v_lshlrev_b32_e32 v222, 16, v204
	v_lshlrev_b32_e32 v223, 16, v205
	v_pk_mul_f32 v[32:33], v[140:141], v[206:207]
	v_pk_mul_f32 v[34:35], v[140:141], v[208:209]
	v_pk_mul_f32 v[36:37], v[140:141], v[210:211]
	v_pk_mul_f32 v[38:39], v[140:141], v[212:213]
	v_pk_mul_f32 v[40:41], v[140:141], v[214:215]
	v_pk_mul_f32 v[42:43], v[140:141], v[216:217]
	v_pk_mul_f32 v[44:45], v[140:141], v[218:219]
	v_pk_mul_f32 v[46:47], v[140:141], v[222:223]
	v_pk_mul_f32 v[32:33], v[32:33], v[206:207]
	v_pk_mul_f32 v[34:35], v[34:35], v[208:209]
	v_pk_mul_f32 v[36:37], v[36:37], v[210:211]
	v_pk_mul_f32 v[38:39], v[38:39], v[212:213]
	v_pk_mul_f32 v[40:41], v[40:41], v[214:215]
; #define LAS __attribute__((address_space(3)))
; #define WAVE_SYNC() asm volatile("s_waitcnt lgkmcnt(0)" ::: "memory")
; __device__ __forceinline__ float sigmoid_f(float x) { return rcpf_(1.f + __expf(-x)); }
; __device__ __forceinline__ float gelu_tanh_f(float x) { const float y = 0.7978845608028654f * (x + 0.044715f * x * x * x); return x * sigmoid_f(2.f * y); }
; template <bool FINAL, int D>
; __device__ __forceinline__ void rg_dir(PREF p, int l, int h, int ch, int sidx, int rowbase  , LAS bf16_t* sXc, LAS float* stg, int lane) {
;     ...
;             for (int ti = 0; ti < 16; ++ti) { const size_t row = (size_t)(rowbase + mt * 16 + 15 - ti); grv[ti] = __builtin_bit_cast(float, (unsigned)P[row * PW + 512 + ch]); hfv[ti] = __builtin_bit_cast(float, (unsigned)TMP[row * 512 + ch]); }
;             __builtin_amdgcn_sched_barrier(0);
; #pragma unroll
;             for (int ti = 0; ti < 16; ++ti) { grv[ti] = bf2f(__builtin_bit_cast(unsigned, grv[ti])); hfv[ti] = bf2f(__builtin_bit_cast(unsigned, hfv[ti])); }
;         }
;         const bf16x8 A0 = *(const LAS bf16x8*)(sXc + (mt * 16 + (lane & 15)) * 72 + (lane >> 4) * 8), A1 = *(const LAS bf16x8*)(sXc + (mt * 16 + (lane & 15)) * 72 + 32 + (lane >> 4) * 8);
;         f32x4 ar[4], ai[4];
; #pragma unroll
;         for (int nt = 0; nt < 4; ++nt) { const f32x4 z = {0.f, 0.f, 0.f, 0.f};
;             ar[nt] = mfma16(A0, Br[nt][0], z); ar[nt] = mfma16(A1, Br[nt][1], ar[nt]); ai[nt] = mfma16(A0, Bi[nt][0], z); ai[nt] = mfma16(A1, Bi[nt][1], ai[nt]); }
;         WAVE_SYNC();
; #pragma unroll
;         for (int nt = 0; nt < 4; ++nt)
; #pragma unroll
;             for (int j = 0; j < 4; ++j) { const int o = ((lane >> 4) * 4 + j) * 64 + nt * 16 + (lane & 15); stg[o] = ar[nt][j]; stg[1024 + o] = ai[nt][j]; }
;         WAVE_SYNC();
;         float av[16], iv[16];
; #pragma unroll
;         for (int ti = 0; ti < 16; ++ti) { const int tk = D ? 15 - ti : ti;
;             const float zr = stg[tk * 64 + lane] + ba, zi = stg[1024 + tk * 64 + lane] + bi;
;             const float r = sigmoid_f(zr), ig = sigmoid_f(zi);
;             const float a = __builtin_amdgcn_exp2f(r * sp8);
;             const float xc = bf2f(sXc[(mt * 16 + tk) * 72 + lane]);
;             av[ti] = a; iv[ti] = __builtin_amdgcn_sqrtf(fmaxf(1.f - a * a, 0.f)) * ig * xc;
;             if (FINAL && D == 1) grv[ti] = gelu_tanh_f(grv[ti]);
	v_pk_mul_f32 v[42:43], v[42:43], v[216:217]
	v_pk_mul_f32 v[44:45], v[44:45], v[218:219]
	v_pk_mul_f32 v[46:47], v[46:47], v[222:223]
	v_fma_f32 v32, v32, v206, v206
	v_fma_f32 v33, v33, v207, v207
	v_fma_f32 v34, v34, v208, v208
	v_fma_f32 v35, v35, v209, v209
	v_fma_f32 v36, v36, v210, v210
	v_fma_f32 v37, v37, v211, v211
	v_fma_f32 v38, v38, v212, v212
	v_fma_f32 v39, v39, v213, v213
	v_fma_f32 v40, v40, v214, v214
	v_fma_f32 v41, v41, v215, v215
	v_fma_f32 v42, v42, v216, v216
	v_fma_f32 v43, v43, v217, v217
	v_fma_f32 v44, v44, v218, v218
	v_fma_f32 v45, v45, v219, v219
	v_fma_f32 v46, v46, v222, v222
	v_fma_f32 v47, v47, v223, v223
	s_mov_b32 s98, 0xc0135761
	v_pk_mul_f32 v[32:33], v[32:33], s[98:99] op_sel_hi:[1,0]
	v_pk_mul_f32 v[34:35], v[34:35], s[98:99] op_sel_hi:[1,0]
	v_pk_mul_f32 v[36:37], v[36:37], s[98:99] op_sel_hi:[1,0]
	v_pk_mul_f32 v[38:39], v[38:39], s[98:99] op_sel_hi:[1,0]
	v_pk_mul_f32 v[40:41], v[40:41], s[98:99] op_sel_hi:[1,0]
	v_pk_mul_f32 v[42:43], v[42:43], s[98:99] op_sel_hi:[1,0]
	v_pk_mul_f32 v[44:45], v[44:45], s[98:99] op_sel_hi:[1,0]
	v_pk_mul_f32 v[46:47], v[46:47], s[98:99] op_sel_hi:[1,0]
	v_exp_f32_e32 v32, v32
	v_exp_f32_e32 v33, v33
	v_exp_f32_e32 v34, v34
	v_exp_f32_e32 v35, v35
	v_exp_f32_e32 v36, v36
	v_exp_f32_e32 v37, v37
	v_exp_f32_e32 v38, v38
	v_exp_f32_e32 v39, v39
	v_exp_f32_e32 v40, v40
	v_exp_f32_e32 v41, v41
	v_exp_f32_e32 v42, v42
	v_exp_f32_e32 v43, v43
	v_exp_f32_e32 v44, v44
	v_exp_f32_e32 v45, v45
	v_exp_f32_e32 v46, v46
	v_exp_f32_e32 v47, v47
	v_pk_add_f32 v[32:33], v[32:33], 1.0 op_sel_hi:[1,0]
	v_pk_add_f32 v[34:35], v[34:35], 1.0 op_sel_hi:[1,0]
	v_pk_add_f32 v[36:37], v[36:37], 1.0 op_sel_hi:[1,0]
	v_pk_add_f32 v[38:39], v[38:39], 1.0 op_sel_hi:[1,0]
	v_pk_add_f32 v[40:41], v[40:41], 1.0 op_sel_hi:[1,0]
	v_pk_add_f32 v[42:43], v[42:43], 1.0 op_sel_hi:[1,0]
	v_pk_add_f32 v[44:45], v[44:45], 1.0 op_sel_hi:[1,0]
	v_pk_add_f32 v[46:47], v[46:47], 1.0 op_sel_hi:[1,0]
	v_rcp_f32_e32 v32, v32
	v_rcp_f32_e32 v33, v33
	v_rcp_f32_e32 v34, v34
	v_rcp_f32_e32 v35, v35
	v_rcp_f32_e32 v36, v36
	v_rcp_f32_e32 v37, v37
	v_rcp_f32_e32 v38, v38
	v_rcp_f32_e32 v39, v39
	v_rcp_f32_e32 v40, v40
	v_rcp_f32_e32 v41, v41
	v_rcp_f32_e32 v42, v42
	v_rcp_f32_e32 v43, v43
	v_rcp_f32_e32 v44, v44
	v_rcp_f32_e32 v45, v45
	v_rcp_f32_e32 v46, v46
	v_rcp_f32_e32 v47, v47
	s_nop 0
	v_pk_mul_f32 v[206:207], v[32:33], v[206:207]
	v_pk_mul_f32 v[208:209], v[34:35], v[208:209]
	v_pk_mul_f32 v[210:211], v[36:37], v[210:211]
	v_pk_mul_f32 v[212:213], v[38:39], v[212:213]
	v_pk_mul_f32 v[214:215], v[40:41], v[214:215]
	v_pk_mul_f32 v[216:217], v[42:43], v[216:217]
	v_pk_mul_f32 v[218:219], v[44:45], v[218:219]
	v_pk_mul_f32 v[222:223], v[46:47], v[222:223]
	s_add_i32 s39, s15, 32
	s_mul_hi_u32 s83, s39, 0x1600
	s_mul_i32 s82, s39, 0x1600
	s_add_u32 s82, s82, s0
	s_addc_u32 s83, s83, s1
	s_add_u32 s82, s82, 0xbc00400
	s_addc_u32 s83, s83, 0
	global_load_ushort v190, v234, s[82:83]
	s_add_u32 s82, s82, 0x1600
	s_addc_u32 s83, s83, 0
	global_load_ushort v191, v234, s[82:83]
	s_add_u32 s82, s82, 0x1600
	s_addc_u32 s83, s83, 0
	global_load_ushort v192, v234, s[82:83]
	s_add_u32 s82, s82, 0x1600
	s_addc_u32 s83, s83, 0
	global_load_ushort v193, v234, s[82:83]
	s_add_u32 s82, s82, 0x1600
	s_addc_u32 s83, s83, 0
	global_load_ushort v194, v234, s[82:83]
	s_add_u32 s82, s82, 0x1600
	s_addc_u32 s83, s83, 0
	global_load_ushort v195, v234, s[82:83]
	s_add_u32 s82, s82, 0x1600
	s_addc_u32 s83, s83, 0
	global_load_ushort v196, v234, s[82:83]
	s_add_u32 s82, s82, 0x1600
	s_addc_u32 s83, s83, 0
	global_load_ushort v197, v234, s[82:83]
	s_add_u32 s82, s82, 0x1600
	s_addc_u32 s83, s83, 0
	global_load_ushort v198, v234, s[82:83]
	s_add_u32 s82, s82, 0x1600
	s_addc_u32 s83, s83, 0
	global_load_ushort v199, v234, s[82:83]
	s_add_u32 s82, s82, 0x1600
	s_addc_u32 s83, s83, 0
	global_load_ushort v200, v234, s[82:83]
	s_add_u32 s82, s82, 0x1600
	s_addc_u32 s83, s83, 0
	global_load_ushort v201, v234, s[82:83]
	s_add_u32 s82, s82, 0x1600
	s_addc_u32 s83, s83, 0
	global_load_ushort v202, v234, s[82:83]
	s_add_u32 s82, s82, 0x1600
	s_addc_u32 s83, s83, 0
	global_load_ushort v203, v234, s[82:83]
	s_add_u32 s82, s82, 0x1600
	s_addc_u32 s83, s83, 0
	global_load_ushort v204, v234, s[82:83]
	s_add_u32 s82, s82, 0x1600
	s_addc_u32 s83, s83, 0
	global_load_ushort v205, v234, s[82:83]
	s_waitcnt lgkmcnt(0)
; __device__ __forceinline__ float sigmoid_f(float x) { return rcpf_(1.f + __expf(-x)); }
; template <bool FINAL, int D>
; __device__ __forceinline__ void rg_dir(PREF p, int l, int h, int ch, int sidx, int rowbase  , LAS bf16_t* sXc, LAS float* stg, int lane) {
;     ...
;         for (int ti = 0; ti < 16; ++ti) { const int tk = D ? 15 - ti : ti;
;             const float zr = stg[tk * 64 + lane] + ba, zi = stg[1024 + tk * 64 + lane] + bi;
;             const float r = sigmoid_f(zr), ig = sigmoid_f(zi);
;             const float a = __builtin_amdgcn_exp2f(r * sp8);
;             const float xc = bf2f(sXc[(mt * 16 + tk) * 72 + lane]);
;             av[ti] = a; iv[ti] = __builtin_amdgcn_sqrtf(fmaxf(1.f - a * a, 0.f)) * ig * xc;
	v_pk_fma_f32 v[0:1], v[0:1], v[248:249], v[242:243]
	v_pk_fma_f32 v[2:3], v[2:3], v[248:249], v[242:243]
	v_pk_fma_f32 v[4:5], v[4:5], v[248:249], v[242:243]
	v_pk_fma_f32 v[6:7], v[6:7], v[248:249], v[242:243]
	v_pk_fma_f32 v[8:9], v[8:9], v[248:249], v[242:243]
	v_pk_fma_f32 v[10:11], v[10:11], v[248:249], v[242:243]
	v_pk_fma_f32 v[12:13], v[12:13], v[248:249], v[242:243]
	v_pk_fma_f32 v[14:15], v[14:15], v[248:249], v[242:243]
	v_pk_fma_f32 v[16:17], v[16:17], v[248:249], v[244:245]
	v_pk_fma_f32 v[18:19], v[18:19], v[248:249], v[244:245]
	v_pk_fma_f32 v[20:21], v[20:21], v[248:249], v[244:245]
	v_pk_fma_f32 v[22:23], v[22:23], v[248:249], v[244:245]
	v_pk_fma_f32 v[24:25], v[24:25], v[248:249], v[244:245]
	v_pk_fma_f32 v[26:27], v[26:27], v[248:249], v[244:245]
	v_pk_fma_f32 v[28:29], v[28:29], v[248:249], v[244:245]
	v_pk_fma_f32 v[30:31], v[30:31], v[248:249], v[244:245]
	v_exp_f32_e32 v0, v0
	v_exp_f32_e32 v1, v1
	v_exp_f32_e32 v2, v2
	v_exp_f32_e32 v3, v3
	v_exp_f32_e32 v4, v4
	v_exp_f32_e32 v5, v5
	v_exp_f32_e32 v6, v6
	v_exp_f32_e32 v7, v7
	v_exp_f32_e32 v8, v8
	v_exp_f32_e32 v9, v9
	v_exp_f32_e32 v10, v10
	v_exp_f32_e32 v11, v11
	v_exp_f32_e32 v12, v12
	v_exp_f32_e32 v13, v13
	v_exp_f32_e32 v14, v14
	v_exp_f32_e32 v15, v15
	v_exp_f32_e32 v16, v16
	v_exp_f32_e32 v17, v17
	v_exp_f32_e32 v18, v18
	v_exp_f32_e32 v19, v19
	v_exp_f32_e32 v20, v20
	v_exp_f32_e32 v21, v21
	v_exp_f32_e32 v22, v22
	v_exp_f32_e32 v23, v23
	v_exp_f32_e32 v24, v24
	v_exp_f32_e32 v25, v25
	v_exp_f32_e32 v26, v26
	v_exp_f32_e32 v27, v27
	v_exp_f32_e32 v28, v28
	v_exp_f32_e32 v29, v29
	v_exp_f32_e32 v30, v30
	v_exp_f32_e32 v31, v31
	v_pk_add_f32 v[0:1], v[0:1], 1.0 op_sel_hi:[1,0]
	v_pk_add_f32 v[2:3], v[2:3], 1.0 op_sel_hi:[1,0]
	v_pk_add_f32 v[4:5], v[4:5], 1.0 op_sel_hi:[1,0]
	v_pk_add_f32 v[6:7], v[6:7], 1.0 op_sel_hi:[1,0]
	v_pk_add_f32 v[8:9], v[8:9], 1.0 op_sel_hi:[1,0]
	v_pk_add_f32 v[10:11], v[10:11], 1.0 op_sel_hi:[1,0]
	v_pk_add_f32 v[12:13], v[12:13], 1.0 op_sel_hi:[1,0]
	v_pk_add_f32 v[14:15], v[14:15], 1.0 op_sel_hi:[1,0]
	v_pk_add_f32 v[16:17], v[16:17], 1.0 op_sel_hi:[1,0]
	v_pk_add_f32 v[18:19], v[18:19], 1.0 op_sel_hi:[1,0]
	v_pk_add_f32 v[20:21], v[20:21], 1.0 op_sel_hi:[1,0]
	v_pk_add_f32 v[22:23], v[22:23], 1.0 op_sel_hi:[1,0]
	v_pk_add_f32 v[24:25], v[24:25], 1.0 op_sel_hi:[1,0]
	v_pk_add_f32 v[26:27], v[26:27], 1.0 op_sel_hi:[1,0]
	v_pk_add_f32 v[28:29], v[28:29], 1.0 op_sel_hi:[1,0]
	v_pk_add_f32 v[30:31], v[30:31], 1.0 op_sel_hi:[1,0]
	v_rcp_f32_e32 v0, v0
	v_rcp_f32_e32 v1, v1
	v_rcp_f32_e32 v2, v2
	v_rcp_f32_e32 v3, v3
	v_rcp_f32_e32 v4, v4
	v_rcp_f32_e32 v5, v5
	v_rcp_f32_e32 v6, v6
	v_rcp_f32_e32 v7, v7
	v_rcp_f32_e32 v8, v8
	v_rcp_f32_e32 v9, v9
	v_rcp_f32_e32 v10, v10
	v_rcp_f32_e32 v11, v11
	v_rcp_f32_e32 v12, v12
	v_rcp_f32_e32 v13, v13
	v_rcp_f32_e32 v14, v14
	v_rcp_f32_e32 v15, v15
	v_rcp_f32_e32 v16, v16
	v_rcp_f32_e32 v17, v17
	v_rcp_f32_e32 v18, v18
	v_rcp_f32_e32 v19, v19
	v_rcp_f32_e32 v20, v20
	v_rcp_f32_e32 v21, v21
	v_rcp_f32_e32 v22, v22
	v_rcp_f32_e32 v23, v23
	v_rcp_f32_e32 v24, v24
	v_rcp_f32_e32 v25, v25
	v_rcp_f32_e32 v26, v26
	v_rcp_f32_e32 v27, v27
	v_rcp_f32_e32 v28, v28
	v_rcp_f32_e32 v29, v29
	v_rcp_f32_e32 v30, v30
	v_rcp_f32_e32 v31, v31
	v_pk_mul_f32 v[0:1], v[246:247], v[0:1]
	v_pk_mul_f32 v[2:3], v[246:247], v[2:3]
	v_pk_mul_f32 v[4:5], v[246:247], v[4:5]
	v_pk_mul_f32 v[6:7], v[246:247], v[6:7]
	v_pk_mul_f32 v[8:9], v[246:247], v[8:9]
	v_pk_mul_f32 v[10:11], v[246:247], v[10:11]
	v_pk_mul_f32 v[12:13], v[246:247], v[12:13]
	v_pk_mul_f32 v[14:15], v[246:247], v[14:15]
	v_exp_f32_e32 v0, v0
	v_exp_f32_e32 v1, v1
	v_exp_f32_e32 v2, v2
	v_exp_f32_e32 v3, v3
	v_exp_f32_e32 v4, v4
	v_exp_f32_e32 v5, v5
	v_exp_f32_e32 v6, v6
	v_exp_f32_e32 v7, v7
	v_exp_f32_e32 v8, v8
	v_exp_f32_e32 v9, v9
	v_exp_f32_e32 v10, v10
	v_exp_f32_e32 v11, v11
	v_exp_f32_e32 v12, v12
	v_exp_f32_e32 v13, v13
	v_exp_f32_e32 v14, v14
	v_exp_f32_e32 v15, v15
	v_fma_f32 v32, -v0, v0, 1.0 clamp
	v_fma_f32 v33, -v1, v1, 1.0 clamp
	v_fma_f32 v34, -v2, v2, 1.0 clamp
	v_fma_f32 v35, -v3, v3, 1.0 clamp
	v_fma_f32 v36, -v4, v4, 1.0 clamp
	v_fma_f32 v37, -v5, v5, 1.0 clamp
	v_fma_f32 v38, -v6, v6, 1.0 clamp
	v_fma_f32 v39, -v7, v7, 1.0 clamp
	v_fma_f32 v40, -v8, v8, 1.0 clamp
	v_fma_f32 v41, -v9, v9, 1.0 clamp
	v_fma_f32 v42, -v10, v10, 1.0 clamp
	v_fma_f32 v43, -v11, v11, 1.0 clamp
	v_fma_f32 v44, -v12, v12, 1.0 clamp
	v_fma_f32 v45, -v13, v13, 1.0 clamp
	v_fma_f32 v46, -v14, v14, 1.0 clamp
	v_fma_f32 v47, -v15, v15, 1.0 clamp
	v_sqrt_f32_e32 v32, v32
	v_sqrt_f32_e32 v33, v33
	v_sqrt_f32_e32 v34, v34
	v_sqrt_f32_e32 v35, v35
	v_sqrt_f32_e32 v36, v36
	v_sqrt_f32_e32 v37, v37
	v_sqrt_f32_e32 v38, v38
	v_sqrt_f32_e32 v39, v39
	v_sqrt_f32_e32 v40, v40
	v_sqrt_f32_e32 v41, v41
	v_sqrt_f32_e32 v42, v42
	v_sqrt_f32_e32 v43, v43
	v_sqrt_f32_e32 v44, v44
	v_sqrt_f32_e32 v45, v45
	v_sqrt_f32_e32 v46, v46
	v_sqrt_f32_e32 v47, v47
	s_nop 0
	v_pk_mul_f32 v[16:17], v[16:17], v[32:33]
	v_pk_mul_f32 v[18:19], v[18:19], v[34:35]
	v_pk_mul_f32 v[20:21], v[20:21], v[36:37]
	v_pk_mul_f32 v[22:23], v[22:23], v[38:39]
	v_pk_mul_f32 v[24:25], v[24:25], v[40:41]
	v_pk_mul_f32 v[26:27], v[26:27], v[42:43]
	v_pk_mul_f32 v[28:29], v[28:29], v[44:45]
	v_pk_mul_f32 v[30:31], v[30:31], v[46:47]
	v_pk_mul_f32 v[16:17], v[16:17], v[48:49]
	v_pk_mul_f32 v[18:19], v[18:19], v[50:51]
	v_pk_mul_f32 v[20:21], v[20:21], v[52:53]
	v_pk_mul_f32 v[22:23], v[22:23], v[54:55]
	v_pk_mul_f32 v[24:25], v[24:25], v[56:57]
	v_pk_mul_f32 v[26:27], v[26:27], v[58:59]
	v_pk_mul_f32 v[28:29], v[28:29], v[60:61]
	v_pk_mul_f32 v[30:31], v[30:31], v[62:63]
	s_add_i32 s39, s15, 62
; #define LAS __attribute__((address_space(3)))
; #define WAVE_SYNC() asm volatile("s_waitcnt lgkmcnt(0)" ::: "memory")
; __device__ __forceinline__ unsigned f2bf(float f) { unsigned r; asm("v_cvt_pk_bf16_f32 %0, %1, %1" : "=v"(r) : "v"(f)); return r & 0xffffu; }
; __device__ __forceinline__ float sigmoid_f(float x) { return rcpf_(1.f + __expf(-x)); }
; template <bool FINAL, int D>
; __device__ __forceinline__ void rg_dir(PREF p, int l, int h, int ch, int sidx, int rowbase  , LAS bf16_t* sXc, LAS float* stg, int lane) {
;     ...
;         const bf16x8 A0 = *(const LAS bf16x8*)(sXc + (mt * 16 + (lane & 15)) * 72 + (lane >> 4) * 8), A1 = *(const LAS bf16x8*)(sXc + (mt * 16 + (lane & 15)) * 72 + 32 + (lane >> 4) * 8);
;         f32x4 ar[4], ai[4];
; #pragma unroll
;         for (int nt = 0; nt < 4; ++nt) { const f32x4 z = {0.f, 0.f, 0.f, 0.f};
;             ar[nt] = mfma16(A0, Br[nt][0], z); ar[nt] = mfma16(A1, Br[nt][1], ar[nt]); ai[nt] = mfma16(A0, Bi[nt][0], z); ai[nt] = mfma16(A1, Bi[nt][1], ai[nt]); }
;         WAVE_SYNC();
; #pragma unroll
;         for (int nt = 0; nt < 4; ++nt)
; #pragma unroll
;             for (int j = 0; j < 4; ++j) { const int o = ((lane >> 4) * 4 + j) * 64 + nt * 16 + (lane & 15); stg[o] = ar[nt][j]; stg[1024 + o] = ai[nt][j]; }
;         WAVE_SYNC();
;         float av[16], iv[16];
; #pragma unroll
;         for (int ti = 0; ti < 16; ++ti) { const int tk = D ? 15 - ti : ti;
;             const float zr = stg[tk * 64 + lane] + ba, zi = stg[1024 + tk * 64 + lane] + bi;
;             const float r = sigmoid_f(zr), ig = sigmoid_f(zi);
;             const float a = __builtin_amdgcn_exp2f(r * sp8);
;             const float xc = bf2f(sXc[(mt * 16 + tk) * 72 + lane]);
;             av[ti] = a; iv[ti] = __builtin_amdgcn_sqrtf(fmaxf(1.f - a * a, 0.f)) * ig * xc;
;             if (FINAL && D == 1) grv[ti] = gelu_tanh_f(grv[ti]);
;         }
; #pragma unroll
;         for (int ti = 0; ti < 16; ++ti) { const int tk = D ? 15 - ti : ti;
;             hc = av[ti] * hc + iv[ti]; Ap *= av[ti];
;             if (FINAL) { const size_t row = (size_t)(rowbase + mt * 16 + tk);
;                 if (D == 0) TMP[row * 512 + ch] = (bf16_t)f2bf(hc);
;                 else MIX[row * DM + ch] = (bf16_t)f2bf(grv[ti] * (hfv[ti] + hc)); }
	s_lshl_b32 s39, s39, 11
	s_add_u32 s90, s0, 0x7b00000
	s_addc_u32 s91, s1, 0
	s_add_u32 s90, s90, s39
	s_addc_u32 s91, s91, 0
	v_lshlrev_b32_e32 v48, 16, v182
	v_and_b32_e32 v49, 0xffff0000, v182
	v_lshlrev_b32_e32 v50, 16, v183
	v_and_b32_e32 v51, 0xffff0000, v183
	v_lshlrev_b32_e32 v52, 16, v184
	v_and_b32_e32 v53, 0xffff0000, v184
	v_lshlrev_b32_e32 v54, 16, v185
	v_and_b32_e32 v55, 0xffff0000, v185
	v_lshlrev_b32_e32 v56, 16, v186
	v_and_b32_e32 v57, 0xffff0000, v186
	v_lshlrev_b32_e32 v58, 16, v187
	v_and_b32_e32 v59, 0xffff0000, v187
	v_lshlrev_b32_e32 v60, 16, v188
	v_and_b32_e32 v61, 0xffff0000, v188
	v_lshlrev_b32_e32 v62, 16, v189
	v_and_b32_e32 v63, 0xffff0000, v189
	v_fma_f32 v47, v15, v250, v31
	v_fma_f32 v46, v14, v47, v30
	v_fma_f32 v45, v13, v46, v29
	v_fma_f32 v44, v12, v45, v28
	v_fma_f32 v43, v11, v44, v27
	v_fma_f32 v42, v10, v43, v26
	v_fma_f32 v41, v9, v42, v25
	v_fma_f32 v40, v8, v41, v24
	v_fma_f32 v39, v7, v40, v23
	v_fma_f32 v38, v6, v39, v22
	v_fma_f32 v37, v5, v38, v21
	v_fma_f32 v36, v4, v37, v20
	v_fma_f32 v35, v3, v36, v19
	v_fma_f32 v34, v2, v35, v18
	v_fma_f32 v33, v1, v34, v17
	v_fma_f32 v32, v0, v33, v16
	v_mov_b32_e32 v250, v32
	v_pk_add_f32 v[32:33], v[48:49], v[32:33]
	v_pk_add_f32 v[34:35], v[50:51], v[34:35]
	v_pk_add_f32 v[36:37], v[52:53], v[36:37]
	v_pk_add_f32 v[38:39], v[54:55], v[38:39]
	v_pk_add_f32 v[40:41], v[56:57], v[40:41]
	v_pk_add_f32 v[42:43], v[58:59], v[42:43]
	v_pk_add_f32 v[44:45], v[60:61], v[44:45]
	v_pk_add_f32 v[46:47], v[62:63], v[46:47]
	v_pk_mul_f32 v[32:33], v[206:207], v[32:33]
	v_pk_mul_f32 v[34:35], v[208:209], v[34:35]
	v_pk_mul_f32 v[36:37], v[210:211], v[36:37]
	v_pk_mul_f32 v[38:39], v[212:213], v[38:39]
	v_pk_mul_f32 v[40:41], v[214:215], v[40:41]
	v_pk_mul_f32 v[42:43], v[216:217], v[42:43]
	v_pk_mul_f32 v[44:45], v[218:219], v[44:45]
	v_pk_mul_f32 v[46:47], v[222:223], v[46:47]
	v_cvt_pk_bf16_f32 v32, v32, v33
	v_cvt_pk_bf16_f32 v34, v34, v35
	v_cvt_pk_bf16_f32 v36, v36, v37
	v_cvt_pk_bf16_f32 v38, v38, v39
	v_cvt_pk_bf16_f32 v40, v40, v41
	v_cvt_pk_bf16_f32 v42, v42, v43
	v_cvt_pk_bf16_f32 v44, v44, v45
	v_cvt_pk_bf16_f32 v46, v46, v47
	global_store_short_d16_hi v234, v46, s[90:91] offset:2048
	global_store_short v234, v46, s[90:91]
	s_sub_u32 s90, s90, 0x1000
	s_subb_u32 s91, s91, 0
	global_store_short_d16_hi v234, v44, s[90:91] offset:2048
	global_store_short v234, v44, s[90:91]
	s_sub_u32 s90, s90, 0x1000
	s_subb_u32 s91, s91, 0
	global_store_short_d16_hi v234, v42, s[90:91] offset:2048
	global_store_short v234, v42, s[90:91]
	s_sub_u32 s90, s90, 0x1000
	s_subb_u32 s91, s91, 0
	global_store_short_d16_hi v234, v40, s[90:91] offset:2048
	global_store_short v234, v40, s[90:91]
	s_sub_u32 s90, s90, 0x1000
	s_subb_u32 s91, s91, 0
	global_store_short_d16_hi v234, v38, s[90:91] offset:2048
	global_store_short v234, v38, s[90:91]
	s_sub_u32 s90, s90, 0x1000
	s_subb_u32 s91, s91, 0
	global_store_short_d16_hi v234, v36, s[90:91] offset:2048
	global_store_short v234, v36, s[90:91]
	s_sub_u32 s90, s90, 0x1000
	s_subb_u32 s91, s91, 0
	global_store_short_d16_hi v234, v34, s[90:91] offset:2048
	global_store_short v234, v34, s[90:91]
	s_sub_u32 s90, s90, 0x1000
	s_subb_u32 s91, s91, 0
	global_store_short_d16_hi v234, v32, s[90:91] offset:2048
	global_store_short v234, v32, s[90:91]
	ds_read_b128 v[32:35], v236 offset:4608
	ds_read_b128 v[36:39], v236 offset:4672
	s_waitcnt lgkmcnt(0)
	v_mfma_f32_16x16x32_bf16 v[0:3], v[32:35], v[80:83], 0
	v_mfma_f32_16x16x32_bf16 v[4:7], v[32:35], v[88:91], 0
	v_mfma_f32_16x16x32_bf16 v[8:11], v[32:35], v[96:99], 0
	v_mfma_f32_16x16x32_bf16 v[12:15], v[32:35], v[104:107], 0
	v_mfma_f32_16x16x32_bf16 v[16:19], v[32:35], v[112:115], 0
	v_mfma_f32_16x16x32_bf16 v[20:23], v[32:35], v[120:123], 0
	v_mfma_f32_16x16x32_bf16 v[24:27], v[32:35], v[128:131], 0
	v_mfma_f32_16x16x32_bf16 v[28:31], v[32:35], v[136:139], 0
	v_mfma_f32_16x16x32_bf16 v[0:3], v[36:39], v[84:87], v[0:3]
	v_mfma_f32_16x16x32_bf16 v[4:7], v[36:39], v[92:95], v[4:7]
	v_mfma_f32_16x16x32_bf16 v[8:11], v[36:39], v[100:103], v[8:11]
	v_mfma_f32_16x16x32_bf16 v[12:15], v[36:39], v[108:111], v[12:15]
	v_mfma_f32_16x16x32_bf16 v[16:19], v[36:39], v[116:119], v[16:19]
	v_mfma_f32_16x16x32_bf16 v[20:23], v[36:39], v[124:127], v[20:23]
	v_mfma_f32_16x16x32_bf16 v[24:27], v[36:39], v[132:135], v[24:27]
	v_mfma_f32_16x16x32_bf16 v[28:31], v[36:39], v[228:231], v[28:31]
	s_nop 3
	ds_write2_b32 v237, v0, v4 offset0:0 offset1:16
	ds_write2_b32 v237, v8, v12 offset0:32 offset1:48
	ds_write2_b32 v237, v1, v5 offset0:64 offset1:80
	ds_write2_b32 v237, v9, v13 offset0:96 offset1:112
	ds_write2_b32 v237, v2, v6 offset0:128 offset1:144
	ds_write2_b32 v237, v10, v14 offset0:160 offset1:176
	ds_write2_b32 v237, v3, v7 offset0:192 offset1:208
	ds_write2_b32 v237, v11, v15 offset0:224 offset1:240
	ds_write2_b32 v238, v16, v20 offset0:0 offset1:16
	ds_write2_b32 v238, v24, v28 offset0:32 offset1:48
	ds_write2_b32 v238, v17, v21 offset0:64 offset1:80
	ds_write2_b32 v238, v25, v29 offset0:96 offset1:112
	ds_write2_b32 v238, v18, v22 offset0:128 offset1:144
	ds_write2_b32 v238, v26, v30 offset0:160 offset1:176
	ds_write2_b32 v238, v19, v23 offset0:192 offset1:208
	ds_write2_b32 v238, v27, v31 offset0:224 offset1:240
	s_waitcnt lgkmcnt(0)
; #define LAS __attribute__((address_space(3)))
; #define WAVE_SYNC() asm volatile("s_waitcnt lgkmcnt(0)" ::: "memory")
; __device__ __forceinline__ float sigmoid_f(float x) { return rcpf_(1.f + __expf(-x)); }
; __device__ __forceinline__ float gelu_tanh_f(float x) { const float y = 0.7978845608028654f * (x + 0.044715f * x * x * x); return x * sigmoid_f(2.f * y); }
; template <bool FINAL, int D>
; __device__ __forceinline__ void rg_dir(PREF p, int l, int h, int ch, int sidx, int rowbase  , LAS bf16_t* sXc, LAS float* stg, int lane) {
;     ...
;             for (int ti = 0; ti < 16; ++ti) { const size_t row = (size_t)(rowbase + mt * 16 + 15 - ti); grv[ti] = __builtin_bit_cast(float, (unsigned)P[row * PW + 512 + ch]); hfv[ti] = __builtin_bit_cast(float, (unsigned)TMP[row * 512 + ch]); }
;             __builtin_amdgcn_sched_barrier(0);
; #pragma unroll
;             for (int ti = 0; ti < 16; ++ti) { grv[ti] = bf2f(__builtin_bit_cast(unsigned, grv[ti])); hfv[ti] = bf2f(__builtin_bit_cast(unsigned, hfv[ti])); }
;         }
;         const bf16x8 A0 = *(const LAS bf16x8*)(sXc + (mt * 16 + (lane & 15)) * 72 + (lane >> 4) * 8), A1 = *(const LAS bf16x8*)(sXc + (mt * 16 + (lane & 15)) * 72 + 32 + (lane >> 4) * 8);
;         f32x4 ar[4], ai[4];
; #pragma unroll
;         for (int nt = 0; nt < 4; ++nt) { const f32x4 z = {0.f, 0.f, 0.f, 0.f};
;             ar[nt] = mfma16(A0, Br[nt][0], z); ar[nt] = mfma16(A1, Br[nt][1], ar[nt]); ai[nt] = mfma16(A0, Bi[nt][0], z); ai[nt] = mfma16(A1, Bi[nt][1], ai[nt]); }
;         WAVE_SYNC();
; #pragma unroll
;         for (int nt = 0; nt < 4; ++nt)
; #pragma unroll
;             for (int j = 0; j < 4; ++j) { const int o = ((lane >> 4) * 4 + j) * 64 + nt * 16 + (lane & 15); stg[o] = ar[nt][j]; stg[1024 + o] = ai[nt][j]; }
;         WAVE_SYNC();
;         float av[16], iv[16];
; #pragma unroll
;         for (int ti = 0; ti < 16; ++ti) { const int tk = D ? 15 - ti : ti;
;             const float zr = stg[tk * 64 + lane] + ba, zi = stg[1024 + tk * 64 + lane] + bi;
;             const float r = sigmoid_f(zr), ig = sigmoid_f(zi);
;             const float a = __builtin_amdgcn_exp2f(r * sp8);
;             const float xc = bf2f(sXc[(mt * 16 + tk) * 72 + lane]);
;             av[ti] = a; iv[ti] = __builtin_amdgcn_sqrtf(fmaxf(1.f - a * a, 0.f)) * ig * xc;
;             if (FINAL && D == 1) grv[ti] = gelu_tanh_f(grv[ti]);
	ds_read2st64_b32 v[0:1], v239 offset0:36 offset1:37
	ds_read2st64_b32 v[2:3], v239 offset0:38 offset1:39
	ds_read2st64_b32 v[4:5], v239 offset0:40 offset1:41
	ds_read2st64_b32 v[6:7], v239 offset0:42 offset1:43
	ds_read2st64_b32 v[8:9], v239 offset0:44 offset1:45
	ds_read2st64_b32 v[10:11], v239 offset0:46 offset1:47
	ds_read2st64_b32 v[12:13], v239 offset0:48 offset1:49
	ds_read2st64_b32 v[14:15], v239 offset0:50 offset1:51
	ds_read2st64_b32 v[16:17], v239 offset0:52 offset1:53
	ds_read2st64_b32 v[18:19], v239 offset0:54 offset1:55
	ds_read2st64_b32 v[20:21], v239 offset0:56 offset1:57
	ds_read2st64_b32 v[22:23], v239 offset0:58 offset1:59
	ds_read2st64_b32 v[24:25], v239 offset0:60 offset1:61
	ds_read2st64_b32 v[26:27], v239 offset0:62 offset1:63
	ds_read2st64_b32 v[28:29], v239 offset0:64 offset1:65
	ds_read2st64_b32 v[30:31], v239 offset0:66 offset1:67
	ds_read_u16_d16_hi v48, v240 offset:4608
	ds_read_u16_d16_hi v49, v240 offset:4752
	ds_read_u16_d16_hi v50, v240 offset:4896
	ds_read_u16_d16_hi v51, v240 offset:5040
	ds_read_u16_d16_hi v52, v240 offset:5184
	ds_read_u16_d16_hi v53, v240 offset:5328
	ds_read_u16_d16_hi v54, v240 offset:5472
	ds_read_u16_d16_hi v55, v240 offset:5616
	ds_read_u16_d16_hi v56, v240 offset:5760
	ds_read_u16_d16_hi v57, v240 offset:5904
	ds_read_u16_d16_hi v58, v240 offset:6048
	ds_read_u16_d16_hi v59, v240 offset:6192
	ds_read_u16_d16_hi v60, v240 offset:6336
	ds_read_u16_d16_hi v61, v240 offset:6480
	ds_read_u16_d16_hi v62, v240 offset:6624
	ds_read_u16_d16_hi v63, v240 offset:6768
	s_waitcnt vmcnt(16)
	v_lshlrev_b32_e32 v206, 16, v190
	v_lshlrev_b32_e32 v207, 16, v191
	v_lshlrev_b32_e32 v208, 16, v192
	v_lshlrev_b32_e32 v209, 16, v193
	v_lshlrev_b32_e32 v210, 16, v194
	v_lshlrev_b32_e32 v211, 16, v195
	v_lshlrev_b32_e32 v212, 16, v196
	v_lshlrev_b32_e32 v213, 16, v197
	v_lshlrev_b32_e32 v214, 16, v198
	v_lshlrev_b32_e32 v215, 16, v199
	v_lshlrev_b32_e32 v216, 16, v200
	v_lshlrev_b32_e32 v217, 16, v201
	v_lshlrev_b32_e32 v218, 16, v202
	v_lshlrev_b32_e32 v219, 16, v203
	v_lshlrev_b32_e32 v222, 16, v204
	v_lshlrev_b32_e32 v223, 16, v205
	v_pk_mul_f32 v[32:33], v[140:141], v[206:207]
	v_pk_mul_f32 v[34:35], v[140:141], v[208:209]
	v_pk_mul_f32 v[36:37], v[140:141], v[210:211]
	v_pk_mul_f32 v[38:39], v[140:141], v[212:213]
	v_pk_mul_f32 v[40:41], v[140:141], v[214:215]
	v_pk_mul_f32 v[42:43], v[140:141], v[216:217]
	v_pk_mul_f32 v[44:45], v[140:141], v[218:219]
	v_pk_mul_f32 v[46:47], v[140:141], v[222:223]
	v_pk_mul_f32 v[32:33], v[32:33], v[206:207]
	v_pk_mul_f32 v[34:35], v[34:35], v[208:209]
	v_pk_mul_f32 v[36:37], v[36:37], v[210:211]
	v_pk_mul_f32 v[38:39], v[38:39], v[212:213]
	v_pk_mul_f32 v[40:41], v[40:41], v[214:215]
	v_pk_mul_f32 v[42:43], v[42:43], v[216:217]
	v_pk_mul_f32 v[44:45], v[44:45], v[218:219]
	v_pk_mul_f32 v[46:47], v[46:47], v[222:223]
	v_fma_f32 v32, v32, v206, v206
	v_fma_f32 v33, v33, v207, v207
	v_fma_f32 v34, v34, v208, v208
	v_fma_f32 v35, v35, v209, v209
	v_fma_f32 v36, v36, v210, v210
	v_fma_f32 v37, v37, v211, v211
	v_fma_f32 v38, v38, v212, v212
	v_fma_f32 v39, v39, v213, v213
	v_fma_f32 v40, v40, v214, v214
	v_fma_f32 v41, v41, v215, v215
	v_fma_f32 v42, v42, v216, v216
	v_fma_f32 v43, v43, v217, v217
	v_fma_f32 v44, v44, v218, v218
	v_fma_f32 v45, v45, v219, v219
	v_fma_f32 v46, v46, v222, v222
	v_fma_f32 v47, v47, v223, v223
	s_mov_b32 s98, 0xc0135761
	v_pk_mul_f32 v[32:33], v[32:33], s[98:99] op_sel_hi:[1,0]
	v_pk_mul_f32 v[34:35], v[34:35], s[98:99] op_sel_hi:[1,0]
	v_pk_mul_f32 v[36:37], v[36:37], s[98:99] op_sel_hi:[1,0]
	v_pk_mul_f32 v[38:39], v[38:39], s[98:99] op_sel_hi:[1,0]
	v_pk_mul_f32 v[40:41], v[40:41], s[98:99] op_sel_hi:[1,0]
	v_pk_mul_f32 v[42:43], v[42:43], s[98:99] op_sel_hi:[1,0]
	v_pk_mul_f32 v[44:45], v[44:45], s[98:99] op_sel_hi:[1,0]
	v_pk_mul_f32 v[46:47], v[46:47], s[98:99] op_sel_hi:[1,0]
	v_exp_f32_e32 v32, v32
	v_exp_f32_e32 v33, v33
	v_exp_f32_e32 v34, v34
	v_exp_f32_e32 v35, v35
	v_exp_f32_e32 v36, v36
	v_exp_f32_e32 v37, v37
	v_exp_f32_e32 v38, v38
	v_exp_f32_e32 v39, v39
	v_exp_f32_e32 v40, v40
	v_exp_f32_e32 v41, v41
	v_exp_f32_e32 v42, v42
	v_exp_f32_e32 v43, v43
	v_exp_f32_e32 v44, v44
	v_exp_f32_e32 v45, v45
	v_exp_f32_e32 v46, v46
	v_exp_f32_e32 v47, v47
	v_pk_add_f32 v[32:33], v[32:33], 1.0 op_sel_hi:[1,0]
	v_pk_add_f32 v[34:35], v[34:35], 1.0 op_sel_hi:[1,0]
	v_pk_add_f32 v[36:37], v[36:37], 1.0 op_sel_hi:[1,0]
	v_pk_add_f32 v[38:39], v[38:39], 1.0 op_sel_hi:[1,0]
	v_pk_add_f32 v[40:41], v[40:41], 1.0 op_sel_hi:[1,0]
	v_pk_add_f32 v[42:43], v[42:43], 1.0 op_sel_hi:[1,0]
	v_pk_add_f32 v[44:45], v[44:45], 1.0 op_sel_hi:[1,0]
	v_pk_add_f32 v[46:47], v[46:47], 1.0 op_sel_hi:[1,0]
	v_rcp_f32_e32 v32, v32
	v_rcp_f32_e32 v33, v33
	v_rcp_f32_e32 v34, v34
	v_rcp_f32_e32 v35, v35
	v_rcp_f32_e32 v36, v36
	v_rcp_f32_e32 v37, v37
	v_rcp_f32_e32 v38, v38
	v_rcp_f32_e32 v39, v39
	v_rcp_f32_e32 v40, v40
	v_rcp_f32_e32 v41, v41
	v_rcp_f32_e32 v42, v42
	v_rcp_f32_e32 v43, v43
	v_rcp_f32_e32 v44, v44
	v_rcp_f32_e32 v45, v45
	v_rcp_f32_e32 v46, v46
	v_rcp_f32_e32 v47, v47
	s_nop 0
	v_pk_mul_f32 v[206:207], v[32:33], v[206:207]
	v_pk_mul_f32 v[208:209], v[34:35], v[208:209]
	v_pk_mul_f32 v[210:211], v[36:37], v[210:211]
	v_pk_mul_f32 v[212:213], v[38:39], v[212:213]
	v_pk_mul_f32 v[214:215], v[40:41], v[214:215]
	v_pk_mul_f32 v[216:217], v[42:43], v[216:217]
	v_pk_mul_f32 v[218:219], v[44:45], v[218:219]
	v_pk_mul_f32 v[222:223], v[46:47], v[222:223]
	s_add_i32 s39, s15, 16
	s_mul_hi_u32 s83, s39, 0x1600
	s_mul_i32 s82, s39, 0x1600
	s_add_u32 s82, s82, s0
	s_addc_u32 s83, s83, s1
	s_add_u32 s82, s82, 0xbc00400
	s_addc_u32 s83, s83, 0
; __device__ __forceinline__ float sigmoid_f(float x) { return rcpf_(1.f + __expf(-x)); }
; template <bool FINAL, int D>
; __device__ __forceinline__ void rg_dir(PREF p, int l, int h, int ch, int sidx, int rowbase  , LAS bf16_t* sXc, LAS float* stg, int lane) {
;     ...
;             for (int ti = 0; ti < 16; ++ti) { const size_t row = (size_t)(rowbase + mt * 16 + 15 - ti); grv[ti] = __builtin_bit_cast(float, (unsigned)P[row * PW + 512 + ch]); hfv[ti] = __builtin_bit_cast(float, (unsigned)TMP[row * 512 + ch]); }
;     ...
;         for (int ti = 0; ti < 16; ++ti) { const int tk = D ? 15 - ti : ti;
;             const float zr = stg[tk * 64 + lane] + ba, zi = stg[1024 + tk * 64 + lane] + bi;
;             const float r = sigmoid_f(zr), ig = sigmoid_f(zi);
;             const float a = __builtin_amdgcn_exp2f(r * sp8);
;             const float xc = bf2f(sXc[(mt * 16 + tk) * 72 + lane]);
;             av[ti] = a; iv[ti] = __builtin_amdgcn_sqrtf(fmaxf(1.f - a * a, 0.f)) * ig * xc;
	global_load_ushort v190, v234, s[82:83]
	s_add_u32 s82, s82, 0x1600
	s_addc_u32 s83, s83, 0
	global_load_ushort v191, v234, s[82:83]
	s_add_u32 s82, s82, 0x1600
	s_addc_u32 s83, s83, 0
	global_load_ushort v192, v234, s[82:83]
	s_add_u32 s82, s82, 0x1600
	s_addc_u32 s83, s83, 0
	global_load_ushort v193, v234, s[82:83]
	s_add_u32 s82, s82, 0x1600
	s_addc_u32 s83, s83, 0
	global_load_ushort v194, v234, s[82:83]
	s_add_u32 s82, s82, 0x1600
	s_addc_u32 s83, s83, 0
	global_load_ushort v195, v234, s[82:83]
	s_add_u32 s82, s82, 0x1600
	s_addc_u32 s83, s83, 0
	global_load_ushort v196, v234, s[82:83]
	s_add_u32 s82, s82, 0x1600
	s_addc_u32 s83, s83, 0
	global_load_ushort v197, v234, s[82:83]
	s_add_u32 s82, s82, 0x1600
	s_addc_u32 s83, s83, 0
	global_load_ushort v198, v234, s[82:83]
	s_add_u32 s82, s82, 0x1600
	s_addc_u32 s83, s83, 0
	global_load_ushort v199, v234, s[82:83]
	s_add_u32 s82, s82, 0x1600
	s_addc_u32 s83, s83, 0
	global_load_ushort v200, v234, s[82:83]
	s_add_u32 s82, s82, 0x1600
	s_addc_u32 s83, s83, 0
	global_load_ushort v201, v234, s[82:83]
	s_add_u32 s82, s82, 0x1600
	s_addc_u32 s83, s83, 0
	global_load_ushort v202, v234, s[82:83]
	s_add_u32 s82, s82, 0x1600
	s_addc_u32 s83, s83, 0
	global_load_ushort v203, v234, s[82:83]
	s_add_u32 s82, s82, 0x1600
	s_addc_u32 s83, s83, 0
	global_load_ushort v204, v234, s[82:83]
	s_add_u32 s82, s82, 0x1600
	s_addc_u32 s83, s83, 0
	global_load_ushort v205, v234, s[82:83]
	s_waitcnt lgkmcnt(0)
	v_pk_fma_f32 v[0:1], v[0:1], v[248:249], v[242:243]
	v_pk_fma_f32 v[2:3], v[2:3], v[248:249], v[242:243]
	v_pk_fma_f32 v[4:5], v[4:5], v[248:249], v[242:243]
	v_pk_fma_f32 v[6:7], v[6:7], v[248:249], v[242:243]
	v_pk_fma_f32 v[8:9], v[8:9], v[248:249], v[242:243]
	v_pk_fma_f32 v[10:11], v[10:11], v[248:249], v[242:243]
	v_pk_fma_f32 v[12:13], v[12:13], v[248:249], v[242:243]
	v_pk_fma_f32 v[14:15], v[14:15], v[248:249], v[242:243]
	v_pk_fma_f32 v[16:17], v[16:17], v[248:249], v[244:245]
	v_pk_fma_f32 v[18:19], v[18:19], v[248:249], v[244:245]
	v_pk_fma_f32 v[20:21], v[20:21], v[248:249], v[244:245]
	v_pk_fma_f32 v[22:23], v[22:23], v[248:249], v[244:245]
	v_pk_fma_f32 v[24:25], v[24:25], v[248:249], v[244:245]
	v_pk_fma_f32 v[26:27], v[26:27], v[248:249], v[244:245]
	v_pk_fma_f32 v[28:29], v[28:29], v[248:249], v[244:245]
	v_pk_fma_f32 v[30:31], v[30:31], v[248:249], v[244:245]
	v_exp_f32_e32 v0, v0
	v_exp_f32_e32 v1, v1
	v_exp_f32_e32 v2, v2
	v_exp_f32_e32 v3, v3
	v_exp_f32_e32 v4, v4
	v_exp_f32_e32 v5, v5
	v_exp_f32_e32 v6, v6
	v_exp_f32_e32 v7, v7
	v_exp_f32_e32 v8, v8
	v_exp_f32_e32 v9, v9
	v_exp_f32_e32 v10, v10
	v_exp_f32_e32 v11, v11
	v_exp_f32_e32 v12, v12
	v_exp_f32_e32 v13, v13
	v_exp_f32_e32 v14, v14
	v_exp_f32_e32 v15, v15
	v_exp_f32_e32 v16, v16
	v_exp_f32_e32 v17, v17
	v_exp_f32_e32 v18, v18
	v_exp_f32_e32 v19, v19
	v_exp_f32_e32 v20, v20
	v_exp_f32_e32 v21, v21
	v_exp_f32_e32 v22, v22
	v_exp_f32_e32 v23, v23
	v_exp_f32_e32 v24, v24
	v_exp_f32_e32 v25, v25
	v_exp_f32_e32 v26, v26
	v_exp_f32_e32 v27, v27
	v_exp_f32_e32 v28, v28
	v_exp_f32_e32 v29, v29
	v_exp_f32_e32 v30, v30
	v_exp_f32_e32 v31, v31
	v_pk_add_f32 v[0:1], v[0:1], 1.0 op_sel_hi:[1,0]
	v_pk_add_f32 v[2:3], v[2:3], 1.0 op_sel_hi:[1,0]
	v_pk_add_f32 v[4:5], v[4:5], 1.0 op_sel_hi:[1,0]
	v_pk_add_f32 v[6:7], v[6:7], 1.0 op_sel_hi:[1,0]
	v_pk_add_f32 v[8:9], v[8:9], 1.0 op_sel_hi:[1,0]
	v_pk_add_f32 v[10:11], v[10:11], 1.0 op_sel_hi:[1,0]
	v_pk_add_f32 v[12:13], v[12:13], 1.0 op_sel_hi:[1,0]
	v_pk_add_f32 v[14:15], v[14:15], 1.0 op_sel_hi:[1,0]
	v_pk_add_f32 v[16:17], v[16:17], 1.0 op_sel_hi:[1,0]
	v_pk_add_f32 v[18:19], v[18:19], 1.0 op_sel_hi:[1,0]
	v_pk_add_f32 v[20:21], v[20:21], 1.0 op_sel_hi:[1,0]
	v_pk_add_f32 v[22:23], v[22:23], 1.0 op_sel_hi:[1,0]
	v_pk_add_f32 v[24:25], v[24:25], 1.0 op_sel_hi:[1,0]
	v_pk_add_f32 v[26:27], v[26:27], 1.0 op_sel_hi:[1,0]
	v_pk_add_f32 v[28:29], v[28:29], 1.0 op_sel_hi:[1,0]
	v_pk_add_f32 v[30:31], v[30:31], 1.0 op_sel_hi:[1,0]
	v_rcp_f32_e32 v0, v0
	v_rcp_f32_e32 v1, v1
	v_rcp_f32_e32 v2, v2
	v_rcp_f32_e32 v3, v3
	v_rcp_f32_e32 v4, v4
	v_rcp_f32_e32 v5, v5
	v_rcp_f32_e32 v6, v6
	v_rcp_f32_e32 v7, v7
	v_rcp_f32_e32 v8, v8
	v_rcp_f32_e32 v9, v9
	v_rcp_f32_e32 v10, v10
	v_rcp_f32_e32 v11, v11
	v_rcp_f32_e32 v12, v12
	v_rcp_f32_e32 v13, v13
	v_rcp_f32_e32 v14, v14
	v_rcp_f32_e32 v15, v15
	v_rcp_f32_e32 v16, v16
	v_rcp_f32_e32 v17, v17
	v_rcp_f32_e32 v18, v18
	v_rcp_f32_e32 v19, v19
	v_rcp_f32_e32 v20, v20
	v_rcp_f32_e32 v21, v21
	v_rcp_f32_e32 v22, v22
	v_rcp_f32_e32 v23, v23
	v_rcp_f32_e32 v24, v24
	v_rcp_f32_e32 v25, v25
	v_rcp_f32_e32 v26, v26
	v_rcp_f32_e32 v27, v27
	v_rcp_f32_e32 v28, v28
	v_rcp_f32_e32 v29, v29
	v_rcp_f32_e32 v30, v30
	v_rcp_f32_e32 v31, v31
	v_pk_mul_f32 v[0:1], v[246:247], v[0:1]
	v_pk_mul_f32 v[2:3], v[246:247], v[2:3]
	v_pk_mul_f32 v[4:5], v[246:247], v[4:5]
	v_pk_mul_f32 v[6:7], v[246:247], v[6:7]
	v_pk_mul_f32 v[8:9], v[246:247], v[8:9]
	v_pk_mul_f32 v[10:11], v[246:247], v[10:11]
	v_pk_mul_f32 v[12:13], v[246:247], v[12:13]
	v_pk_mul_f32 v[14:15], v[246:247], v[14:15]
	v_exp_f32_e32 v0, v0
	v_exp_f32_e32 v1, v1
	v_exp_f32_e32 v2, v2
	v_exp_f32_e32 v3, v3
	v_exp_f32_e32 v4, v4
	v_exp_f32_e32 v5, v5
	v_exp_f32_e32 v6, v6
	v_exp_f32_e32 v7, v7
	v_exp_f32_e32 v8, v8
	v_exp_f32_e32 v9, v9
	v_exp_f32_e32 v10, v10
	v_exp_f32_e32 v11, v11
	v_exp_f32_e32 v12, v12
	v_exp_f32_e32 v13, v13
	v_exp_f32_e32 v14, v14
	v_exp_f32_e32 v15, v15
	v_fma_f32 v32, -v0, v0, 1.0 clamp
	v_fma_f32 v33, -v1, v1, 1.0 clamp
	v_fma_f32 v34, -v2, v2, 1.0 clamp
	v_fma_f32 v35, -v3, v3, 1.0 clamp
	v_fma_f32 v36, -v4, v4, 1.0 clamp
	v_fma_f32 v37, -v5, v5, 1.0 clamp
	v_fma_f32 v38, -v6, v6, 1.0 clamp
; __device__ __forceinline__ unsigned f2bf(float f) { unsigned r; asm("v_cvt_pk_bf16_f32 %0, %1, %1" : "=v"(r) : "v"(f)); return r & 0xffffu; }
; __device__ __forceinline__ float gelu_tanh_f(float x) { const float y = 0.7978845608028654f * (x + 0.044715f * x * x * x); return x * sigmoid_f(2.f * y); }
; template <bool FINAL, int D>
; __device__ __forceinline__ void rg_dir(PREF p, int l, int h, int ch, int sidx, int rowbase  , LAS bf16_t* sXc, LAS float* stg, int lane) {
;     ...
;             av[ti] = a; iv[ti] = __builtin_amdgcn_sqrtf(fmaxf(1.f - a * a, 0.f)) * ig * xc;
;             if (FINAL && D == 1) grv[ti] = gelu_tanh_f(grv[ti]);
;         }
; #pragma unroll
;         for (int ti = 0; ti < 16; ++ti) { const int tk = D ? 15 - ti : ti;
;             hc = av[ti] * hc + iv[ti]; Ap *= av[ti];
;             if (FINAL) { const size_t row = (size_t)(rowbase + mt * 16 + tk);
;                 if (D == 0) TMP[row * 512 + ch] = (bf16_t)f2bf(hc);
;                 else MIX[row * DM + ch] = (bf16_t)f2bf(grv[ti] * (hfv[ti] + hc)); }
	v_fma_f32 v39, -v7, v7, 1.0 clamp
	v_fma_f32 v40, -v8, v8, 1.0 clamp
	v_fma_f32 v41, -v9, v9, 1.0 clamp
	v_fma_f32 v42, -v10, v10, 1.0 clamp
	v_fma_f32 v43, -v11, v11, 1.0 clamp
	v_fma_f32 v44, -v12, v12, 1.0 clamp
	v_fma_f32 v45, -v13, v13, 1.0 clamp
	v_fma_f32 v46, -v14, v14, 1.0 clamp
	v_fma_f32 v47, -v15, v15, 1.0 clamp
	v_sqrt_f32_e32 v32, v32
	v_sqrt_f32_e32 v33, v33
	v_sqrt_f32_e32 v34, v34
	v_sqrt_f32_e32 v35, v35
	v_sqrt_f32_e32 v36, v36
	v_sqrt_f32_e32 v37, v37
	v_sqrt_f32_e32 v38, v38
	v_sqrt_f32_e32 v39, v39
	v_sqrt_f32_e32 v40, v40
	v_sqrt_f32_e32 v41, v41
	v_sqrt_f32_e32 v42, v42
	v_sqrt_f32_e32 v43, v43
	v_sqrt_f32_e32 v44, v44
	v_sqrt_f32_e32 v45, v45
	v_sqrt_f32_e32 v46, v46
	v_sqrt_f32_e32 v47, v47
	s_nop 0
	v_pk_mul_f32 v[16:17], v[16:17], v[32:33]
	v_pk_mul_f32 v[18:19], v[18:19], v[34:35]
	v_pk_mul_f32 v[20:21], v[20:21], v[36:37]
	v_pk_mul_f32 v[22:23], v[22:23], v[38:39]
	v_pk_mul_f32 v[24:25], v[24:25], v[40:41]
	v_pk_mul_f32 v[26:27], v[26:27], v[42:43]
	v_pk_mul_f32 v[28:29], v[28:29], v[44:45]
	v_pk_mul_f32 v[30:31], v[30:31], v[46:47]
	v_pk_mul_f32 v[16:17], v[16:17], v[48:49]
	v_pk_mul_f32 v[18:19], v[18:19], v[50:51]
	v_pk_mul_f32 v[20:21], v[20:21], v[52:53]
	v_pk_mul_f32 v[22:23], v[22:23], v[54:55]
	v_pk_mul_f32 v[24:25], v[24:25], v[56:57]
	v_pk_mul_f32 v[26:27], v[26:27], v[58:59]
	v_pk_mul_f32 v[28:29], v[28:29], v[60:61]
	v_pk_mul_f32 v[30:31], v[30:31], v[62:63]
	s_add_i32 s39, s15, 46
	s_lshl_b32 s39, s39, 11
	s_add_u32 s90, s0, 0x7b00000
	s_addc_u32 s91, s1, 0
	s_add_u32 s90, s90, s39
	s_addc_u32 s91, s91, 0
	v_lshlrev_b32_e32 v48, 16, v174
	v_and_b32_e32 v49, 0xffff0000, v174
	v_lshlrev_b32_e32 v50, 16, v175
	v_and_b32_e32 v51, 0xffff0000, v175
	v_lshlrev_b32_e32 v52, 16, v176
	v_and_b32_e32 v53, 0xffff0000, v176
	v_lshlrev_b32_e32 v54, 16, v177
	v_and_b32_e32 v55, 0xffff0000, v177
	v_lshlrev_b32_e32 v56, 16, v178
	v_and_b32_e32 v57, 0xffff0000, v178
	v_lshlrev_b32_e32 v58, 16, v179
	v_and_b32_e32 v59, 0xffff0000, v179
	v_lshlrev_b32_e32 v60, 16, v180
	v_and_b32_e32 v61, 0xffff0000, v180
	v_lshlrev_b32_e32 v62, 16, v181
	v_and_b32_e32 v63, 0xffff0000, v181
	v_fma_f32 v47, v15, v250, v31
	v_fma_f32 v46, v14, v47, v30
	v_fma_f32 v45, v13, v46, v29
	v_fma_f32 v44, v12, v45, v28
	v_fma_f32 v43, v11, v44, v27
	v_fma_f32 v42, v10, v43, v26
	v_fma_f32 v41, v9, v42, v25
	v_fma_f32 v40, v8, v41, v24
	v_fma_f32 v39, v7, v40, v23
	v_fma_f32 v38, v6, v39, v22
	v_fma_f32 v37, v5, v38, v21
	v_fma_f32 v36, v4, v37, v20
	v_fma_f32 v35, v3, v36, v19
	v_fma_f32 v34, v2, v35, v18
	v_fma_f32 v33, v1, v34, v17
	v_fma_f32 v32, v0, v33, v16
	v_mov_b32_e32 v250, v32
	v_pk_add_f32 v[32:33], v[48:49], v[32:33]
	v_pk_add_f32 v[34:35], v[50:51], v[34:35]
	v_pk_add_f32 v[36:37], v[52:53], v[36:37]
	v_pk_add_f32 v[38:39], v[54:55], v[38:39]
	v_pk_add_f32 v[40:41], v[56:57], v[40:41]
	v_pk_add_f32 v[42:43], v[58:59], v[42:43]
	v_pk_add_f32 v[44:45], v[60:61], v[44:45]
	v_pk_add_f32 v[46:47], v[62:63], v[46:47]
	v_pk_mul_f32 v[32:33], v[206:207], v[32:33]
	v_pk_mul_f32 v[34:35], v[208:209], v[34:35]
	v_pk_mul_f32 v[36:37], v[210:211], v[36:37]
	v_pk_mul_f32 v[38:39], v[212:213], v[38:39]
	v_pk_mul_f32 v[40:41], v[214:215], v[40:41]
	v_pk_mul_f32 v[42:43], v[216:217], v[42:43]
	v_pk_mul_f32 v[44:45], v[218:219], v[44:45]
	v_pk_mul_f32 v[46:47], v[222:223], v[46:47]
	v_cvt_pk_bf16_f32 v32, v32, v33
	v_cvt_pk_bf16_f32 v34, v34, v35
	v_cvt_pk_bf16_f32 v36, v36, v37
	v_cvt_pk_bf16_f32 v38, v38, v39
	v_cvt_pk_bf16_f32 v40, v40, v41
	v_cvt_pk_bf16_f32 v42, v42, v43
	v_cvt_pk_bf16_f32 v44, v44, v45
	v_cvt_pk_bf16_f32 v46, v46, v47
	global_store_short_d16_hi v234, v46, s[90:91] offset:2048
	global_store_short v234, v46, s[90:91]
	s_sub_u32 s90, s90, 0x1000
	s_subb_u32 s91, s91, 0
	global_store_short_d16_hi v234, v44, s[90:91] offset:2048
	global_store_short v234, v44, s[90:91]
	s_sub_u32 s90, s90, 0x1000
	s_subb_u32 s91, s91, 0
	global_store_short_d16_hi v234, v42, s[90:91] offset:2048
	global_store_short v234, v42, s[90:91]
	s_sub_u32 s90, s90, 0x1000
	s_subb_u32 s91, s91, 0
	global_store_short_d16_hi v234, v40, s[90:91] offset:2048
	global_store_short v234, v40, s[90:91]
	s_sub_u32 s90, s90, 0x1000
	s_subb_u32 s91, s91, 0
	global_store_short_d16_hi v234, v38, s[90:91] offset:2048
	global_store_short v234, v38, s[90:91]
	s_sub_u32 s90, s90, 0x1000
	s_subb_u32 s91, s91, 0
	global_store_short_d16_hi v234, v36, s[90:91] offset:2048
	global_store_short v234, v36, s[90:91]
	s_sub_u32 s90, s90, 0x1000
	s_subb_u32 s91, s91, 0
	global_store_short_d16_hi v234, v34, s[90:91] offset:2048
	global_store_short v234, v34, s[90:91]
	s_sub_u32 s90, s90, 0x1000
	s_subb_u32 s91, s91, 0
	global_store_short_d16_hi v234, v32, s[90:91] offset:2048
	global_store_short v234, v32, s[90:91]
	ds_read_b128 v[32:35], v236 offset:2304
	ds_read_b128 v[36:39], v236 offset:2368
	s_waitcnt lgkmcnt(0)
; #define LAS __attribute__((address_space(3)))
; #define WAVE_SYNC() asm volatile("s_waitcnt lgkmcnt(0)" ::: "memory")
; __device__ __forceinline__ float sigmoid_f(float x) { return rcpf_(1.f + __expf(-x)); }
; __device__ __forceinline__ float gelu_tanh_f(float x) { const float y = 0.7978845608028654f * (x + 0.044715f * x * x * x); return x * sigmoid_f(2.f * y); }
; __device__ __forceinline__ f32x4 mfma16(bf16x8 a, bf16x8 b, f32x4 c) { return __builtin_amdgcn_mfma_f32_16x16x32_bf16(a, b, c, 0, 0, 0); }
; template <bool FINAL, int D>
; __device__ __forceinline__ void rg_dir(PREF p, int l, int h, int ch, int sidx, int rowbase  , LAS bf16_t* sXc, LAS float* stg, int lane) {
;     ...
;         const bf16x8 A0 = *(const LAS bf16x8*)(sXc + (mt * 16 + (lane & 15)) * 72 + (lane >> 4) * 8), A1 = *(const LAS bf16x8*)(sXc + (mt * 16 + (lane & 15)) * 72 + 32 + (lane >> 4) * 8);
;         f32x4 ar[4], ai[4];
; #pragma unroll
;         for (int nt = 0; nt < 4; ++nt) { const f32x4 z = {0.f, 0.f, 0.f, 0.f};
;             ar[nt] = mfma16(A0, Br[nt][0], z); ar[nt] = mfma16(A1, Br[nt][1], ar[nt]); ai[nt] = mfma16(A0, Bi[nt][0], z); ai[nt] = mfma16(A1, Bi[nt][1], ai[nt]); }
;         WAVE_SYNC();
; #pragma unroll
;         for (int nt = 0; nt < 4; ++nt)
; #pragma unroll
;             for (int j = 0; j < 4; ++j) { const int o = ((lane >> 4) * 4 + j) * 64 + nt * 16 + (lane & 15); stg[o] = ar[nt][j]; stg[1024 + o] = ai[nt][j]; }
;         WAVE_SYNC();
;         float av[16], iv[16];
; #pragma unroll
;         for (int ti = 0; ti < 16; ++ti) { const int tk = D ? 15 - ti : ti;
;             const float zr = stg[tk * 64 + lane] + ba, zi = stg[1024 + tk * 64 + lane] + bi;
;             const float r = sigmoid_f(zr), ig = sigmoid_f(zi);
;             const float a = __builtin_amdgcn_exp2f(r * sp8);
;             const float xc = bf2f(sXc[(mt * 16 + tk) * 72 + lane]);
;             av[ti] = a; iv[ti] = __builtin_amdgcn_sqrtf(fmaxf(1.f - a * a, 0.f)) * ig * xc;
;             if (FINAL && D == 1) grv[ti] = gelu_tanh_f(grv[ti]);
	v_mfma_f32_16x16x32_bf16 v[0:3], v[32:35], v[80:83], 0
	v_mfma_f32_16x16x32_bf16 v[4:7], v[32:35], v[88:91], 0
	v_mfma_f32_16x16x32_bf16 v[8:11], v[32:35], v[96:99], 0
	v_mfma_f32_16x16x32_bf16 v[12:15], v[32:35], v[104:107], 0
	v_mfma_f32_16x16x32_bf16 v[16:19], v[32:35], v[112:115], 0
	v_mfma_f32_16x16x32_bf16 v[20:23], v[32:35], v[120:123], 0
	v_mfma_f32_16x16x32_bf16 v[24:27], v[32:35], v[128:131], 0
	v_mfma_f32_16x16x32_bf16 v[28:31], v[32:35], v[136:139], 0
	v_mfma_f32_16x16x32_bf16 v[0:3], v[36:39], v[84:87], v[0:3]
	v_mfma_f32_16x16x32_bf16 v[4:7], v[36:39], v[92:95], v[4:7]
	v_mfma_f32_16x16x32_bf16 v[8:11], v[36:39], v[100:103], v[8:11]
	v_mfma_f32_16x16x32_bf16 v[12:15], v[36:39], v[108:111], v[12:15]
	v_mfma_f32_16x16x32_bf16 v[16:19], v[36:39], v[116:119], v[16:19]
	v_mfma_f32_16x16x32_bf16 v[20:23], v[36:39], v[124:127], v[20:23]
	v_mfma_f32_16x16x32_bf16 v[24:27], v[36:39], v[132:135], v[24:27]
	v_mfma_f32_16x16x32_bf16 v[28:31], v[36:39], v[228:231], v[28:31]
	s_nop 3
	ds_write2_b32 v237, v0, v4 offset0:0 offset1:16
	ds_write2_b32 v237, v8, v12 offset0:32 offset1:48
	ds_write2_b32 v237, v1, v5 offset0:64 offset1:80
	ds_write2_b32 v237, v9, v13 offset0:96 offset1:112
	ds_write2_b32 v237, v2, v6 offset0:128 offset1:144
	ds_write2_b32 v237, v10, v14 offset0:160 offset1:176
	ds_write2_b32 v237, v3, v7 offset0:192 offset1:208
	ds_write2_b32 v237, v11, v15 offset0:224 offset1:240
	ds_write2_b32 v238, v16, v20 offset0:0 offset1:16
	ds_write2_b32 v238, v24, v28 offset0:32 offset1:48
	ds_write2_b32 v238, v17, v21 offset0:64 offset1:80
	ds_write2_b32 v238, v25, v29 offset0:96 offset1:112
	ds_write2_b32 v238, v18, v22 offset0:128 offset1:144
	ds_write2_b32 v238, v26, v30 offset0:160 offset1:176
	ds_write2_b32 v238, v19, v23 offset0:192 offset1:208
	ds_write2_b32 v238, v27, v31 offset0:224 offset1:240
	s_waitcnt lgkmcnt(0)
	ds_read2st64_b32 v[0:1], v239 offset0:36 offset1:37
	ds_read2st64_b32 v[2:3], v239 offset0:38 offset1:39
	ds_read2st64_b32 v[4:5], v239 offset0:40 offset1:41
	ds_read2st64_b32 v[6:7], v239 offset0:42 offset1:43
	ds_read2st64_b32 v[8:9], v239 offset0:44 offset1:45
	ds_read2st64_b32 v[10:11], v239 offset0:46 offset1:47
	ds_read2st64_b32 v[12:13], v239 offset0:48 offset1:49
	ds_read2st64_b32 v[14:15], v239 offset0:50 offset1:51
	ds_read2st64_b32 v[16:17], v239 offset0:52 offset1:53
	ds_read2st64_b32 v[18:19], v239 offset0:54 offset1:55
	ds_read2st64_b32 v[20:21], v239 offset0:56 offset1:57
	ds_read2st64_b32 v[22:23], v239 offset0:58 offset1:59
	ds_read2st64_b32 v[24:25], v239 offset0:60 offset1:61
	ds_read2st64_b32 v[26:27], v239 offset0:62 offset1:63
	ds_read2st64_b32 v[28:29], v239 offset0:64 offset1:65
	ds_read2st64_b32 v[30:31], v239 offset0:66 offset1:67
	ds_read_u16_d16_hi v48, v240 offset:2304
	ds_read_u16_d16_hi v49, v240 offset:2448
	ds_read_u16_d16_hi v50, v240 offset:2592
	ds_read_u16_d16_hi v51, v240 offset:2736
	ds_read_u16_d16_hi v52, v240 offset:2880
	ds_read_u16_d16_hi v53, v240 offset:3024
	ds_read_u16_d16_hi v54, v240 offset:3168
	ds_read_u16_d16_hi v55, v240 offset:3312
	ds_read_u16_d16_hi v56, v240 offset:3456
	ds_read_u16_d16_hi v57, v240 offset:3600
	ds_read_u16_d16_hi v58, v240 offset:3744
	ds_read_u16_d16_hi v59, v240 offset:3888
	ds_read_u16_d16_hi v60, v240 offset:4032
	ds_read_u16_d16_hi v61, v240 offset:4176
	ds_read_u16_d16_hi v62, v240 offset:4320
	ds_read_u16_d16_hi v63, v240 offset:4464
	s_waitcnt vmcnt(16)
	v_lshlrev_b32_e32 v206, 16, v190
	v_lshlrev_b32_e32 v207, 16, v191
	v_lshlrev_b32_e32 v208, 16, v192
	v_lshlrev_b32_e32 v209, 16, v193
	v_lshlrev_b32_e32 v210, 16, v194
	v_lshlrev_b32_e32 v211, 16, v195
	v_lshlrev_b32_e32 v212, 16, v196
	v_lshlrev_b32_e32 v213, 16, v197
	v_lshlrev_b32_e32 v214, 16, v198
	v_lshlrev_b32_e32 v215, 16, v199
	v_lshlrev_b32_e32 v216, 16, v200
	v_lshlrev_b32_e32 v217, 16, v201
	v_lshlrev_b32_e32 v218, 16, v202
	v_lshlrev_b32_e32 v219, 16, v203
	v_lshlrev_b32_e32 v222, 16, v204
	v_lshlrev_b32_e32 v223, 16, v205
	v_pk_mul_f32 v[32:33], v[140:141], v[206:207]
	v_pk_mul_f32 v[34:35], v[140:141], v[208:209]
	v_pk_mul_f32 v[36:37], v[140:141], v[210:211]
	v_pk_mul_f32 v[38:39], v[140:141], v[212:213]
	v_pk_mul_f32 v[40:41], v[140:141], v[214:215]
	v_pk_mul_f32 v[42:43], v[140:141], v[216:217]
	v_pk_mul_f32 v[44:45], v[140:141], v[218:219]
	v_pk_mul_f32 v[46:47], v[140:141], v[222:223]
	v_pk_mul_f32 v[32:33], v[32:33], v[206:207]
	v_pk_mul_f32 v[34:35], v[34:35], v[208:209]
	v_pk_mul_f32 v[36:37], v[36:37], v[210:211]
	v_pk_mul_f32 v[38:39], v[38:39], v[212:213]
	v_pk_mul_f32 v[40:41], v[40:41], v[214:215]
	v_pk_mul_f32 v[42:43], v[42:43], v[216:217]
	v_pk_mul_f32 v[44:45], v[44:45], v[218:219]
	v_pk_mul_f32 v[46:47], v[46:47], v[222:223]
	v_fma_f32 v32, v32, v206, v206
	v_fma_f32 v33, v33, v207, v207
	v_fma_f32 v34, v34, v208, v208
	v_fma_f32 v35, v35, v209, v209
	v_fma_f32 v36, v36, v210, v210
	v_fma_f32 v37, v37, v211, v211
	v_fma_f32 v38, v38, v212, v212
	v_fma_f32 v39, v39, v213, v213
	v_fma_f32 v40, v40, v214, v214
	v_fma_f32 v41, v41, v215, v215
	v_fma_f32 v42, v42, v216, v216
	v_fma_f32 v43, v43, v217, v217
	v_fma_f32 v44, v44, v218, v218
	v_fma_f32 v45, v45, v219, v219
	v_fma_f32 v46, v46, v222, v222
	v_fma_f32 v47, v47, v223, v223
	s_mov_b32 s98, 0xc0135761
	v_pk_mul_f32 v[32:33], v[32:33], s[98:99] op_sel_hi:[1,0]
	v_pk_mul_f32 v[34:35], v[34:35], s[98:99] op_sel_hi:[1,0]
	v_pk_mul_f32 v[36:37], v[36:37], s[98:99] op_sel_hi:[1,0]
	v_pk_mul_f32 v[38:39], v[38:39], s[98:99] op_sel_hi:[1,0]
	v_pk_mul_f32 v[40:41], v[40:41], s[98:99] op_sel_hi:[1,0]
	v_pk_mul_f32 v[42:43], v[42:43], s[98:99] op_sel_hi:[1,0]
	v_pk_mul_f32 v[44:45], v[44:45], s[98:99] op_sel_hi:[1,0]
; #define LAS __attribute__((address_space(3)))
; #define WAVE_SYNC() asm volatile("s_waitcnt lgkmcnt(0)" ::: "memory")
; __device__ __forceinline__ float sigmoid_f(float x) { return rcpf_(1.f + __expf(-x)); }
; template <bool FINAL, int D>
; __device__ __forceinline__ void rg_dir(PREF p, int l, int h, int ch, int sidx, int rowbase  , LAS bf16_t* sXc, LAS float* stg, int lane) {
;     ...
;         if (FINAL && D == 1) {
; #pragma unroll
;             for (int ti = 0; ti < 16; ++ti) { const size_t row = (size_t)(rowbase + mt * 16 + 15 - ti); grv[ti] = __builtin_bit_cast(float, (unsigned)P[row * PW + 512 + ch]); hfv[ti] = __builtin_bit_cast(float, (unsigned)TMP[row * 512 + ch]); }
;             __builtin_amdgcn_sched_barrier(0);
; #pragma unroll
;             for (int ti = 0; ti < 16; ++ti) { grv[ti] = bf2f(__builtin_bit_cast(unsigned, grv[ti])); hfv[ti] = bf2f(__builtin_bit_cast(unsigned, hfv[ti])); }
;         }
;         const bf16x8 A0 = *(const LAS bf16x8*)(sXc + (mt * 16 + (lane & 15)) * 72 + (lane >> 4) * 8), A1 = *(const LAS bf16x8*)(sXc + (mt * 16 + (lane & 15)) * 72 + 32 + (lane >> 4) * 8);
;         f32x4 ar[4], ai[4];
; #pragma unroll
;         for (int nt = 0; nt < 4; ++nt) { const f32x4 z = {0.f, 0.f, 0.f, 0.f};
;             ar[nt] = mfma16(A0, Br[nt][0], z); ar[nt] = mfma16(A1, Br[nt][1], ar[nt]); ai[nt] = mfma16(A0, Bi[nt][0], z); ai[nt] = mfma16(A1, Bi[nt][1], ai[nt]); }
;         WAVE_SYNC();
; #pragma unroll
;         for (int nt = 0; nt < 4; ++nt)
; #pragma unroll
;             for (int j = 0; j < 4; ++j) { const int o = ((lane >> 4) * 4 + j) * 64 + nt * 16 + (lane & 15); stg[o] = ar[nt][j]; stg[1024 + o] = ai[nt][j]; }
;         WAVE_SYNC();
;         float av[16], iv[16];
; #pragma unroll
;         for (int ti = 0; ti < 16; ++ti) { const int tk = D ? 15 - ti : ti;
;             const float zr = stg[tk * 64 + lane] + ba, zi = stg[1024 + tk * 64 + lane] + bi;
;             const float r = sigmoid_f(zr), ig = sigmoid_f(zi);
;             const float a = __builtin_amdgcn_exp2f(r * sp8);
;             const float xc = bf2f(sXc[(mt * 16 + tk) * 72 + lane]);
;             av[ti] = a; iv[ti] = __builtin_amdgcn_sqrtf(fmaxf(1.f - a * a, 0.f)) * ig * xc;
;             if (FINAL && D == 1) grv[ti] = gelu_tanh_f(grv[ti]);
	v_pk_mul_f32 v[46:47], v[46:47], s[98:99] op_sel_hi:[1,0]
	v_exp_f32_e32 v32, v32
	v_exp_f32_e32 v33, v33
	v_exp_f32_e32 v34, v34
	v_exp_f32_e32 v35, v35
	v_exp_f32_e32 v36, v36
	v_exp_f32_e32 v37, v37
	v_exp_f32_e32 v38, v38
	v_exp_f32_e32 v39, v39
	v_exp_f32_e32 v40, v40
	v_exp_f32_e32 v41, v41
	v_exp_f32_e32 v42, v42
	v_exp_f32_e32 v43, v43
	v_exp_f32_e32 v44, v44
	v_exp_f32_e32 v45, v45
	v_exp_f32_e32 v46, v46
	v_exp_f32_e32 v47, v47
	v_pk_add_f32 v[32:33], v[32:33], 1.0 op_sel_hi:[1,0]
	v_pk_add_f32 v[34:35], v[34:35], 1.0 op_sel_hi:[1,0]
	v_pk_add_f32 v[36:37], v[36:37], 1.0 op_sel_hi:[1,0]
	v_pk_add_f32 v[38:39], v[38:39], 1.0 op_sel_hi:[1,0]
	v_pk_add_f32 v[40:41], v[40:41], 1.0 op_sel_hi:[1,0]
	v_pk_add_f32 v[42:43], v[42:43], 1.0 op_sel_hi:[1,0]
	v_pk_add_f32 v[44:45], v[44:45], 1.0 op_sel_hi:[1,0]
	v_pk_add_f32 v[46:47], v[46:47], 1.0 op_sel_hi:[1,0]
	v_rcp_f32_e32 v32, v32
	v_rcp_f32_e32 v33, v33
	v_rcp_f32_e32 v34, v34
	v_rcp_f32_e32 v35, v35
	v_rcp_f32_e32 v36, v36
	v_rcp_f32_e32 v37, v37
	v_rcp_f32_e32 v38, v38
	v_rcp_f32_e32 v39, v39
	v_rcp_f32_e32 v40, v40
	v_rcp_f32_e32 v41, v41
	v_rcp_f32_e32 v42, v42
	v_rcp_f32_e32 v43, v43
	v_rcp_f32_e32 v44, v44
	v_rcp_f32_e32 v45, v45
	v_rcp_f32_e32 v46, v46
	v_rcp_f32_e32 v47, v47
	s_nop 0
	v_pk_mul_f32 v[206:207], v[32:33], v[206:207]
	v_pk_mul_f32 v[208:209], v[34:35], v[208:209]
	v_pk_mul_f32 v[210:211], v[36:37], v[210:211]
	v_pk_mul_f32 v[212:213], v[38:39], v[212:213]
	v_pk_mul_f32 v[214:215], v[40:41], v[214:215]
	v_pk_mul_f32 v[216:217], v[42:43], v[216:217]
	v_pk_mul_f32 v[218:219], v[44:45], v[218:219]
	v_pk_mul_f32 v[222:223], v[46:47], v[222:223]
	s_add_i32 s39, s15, 0
	s_mul_hi_u32 s83, s39, 0x1600
	s_mul_i32 s82, s39, 0x1600
	s_add_u32 s82, s82, s0
	s_addc_u32 s83, s83, s1
	s_add_u32 s82, s82, 0xbc00400
	s_addc_u32 s83, s83, 0
	global_load_ushort v190, v234, s[82:83]
	s_add_u32 s82, s82, 0x1600
	s_addc_u32 s83, s83, 0
	global_load_ushort v191, v234, s[82:83]
	s_add_u32 s82, s82, 0x1600
	s_addc_u32 s83, s83, 0
	global_load_ushort v192, v234, s[82:83]
	s_add_u32 s82, s82, 0x1600
	s_addc_u32 s83, s83, 0
	global_load_ushort v193, v234, s[82:83]
	s_add_u32 s82, s82, 0x1600
	s_addc_u32 s83, s83, 0
	global_load_ushort v194, v234, s[82:83]
	s_add_u32 s82, s82, 0x1600
	s_addc_u32 s83, s83, 0
	global_load_ushort v195, v234, s[82:83]
	s_add_u32 s82, s82, 0x1600
	s_addc_u32 s83, s83, 0
	global_load_ushort v196, v234, s[82:83]
	s_add_u32 s82, s82, 0x1600
	s_addc_u32 s83, s83, 0
	global_load_ushort v197, v234, s[82:83]
	s_add_u32 s82, s82, 0x1600
	s_addc_u32 s83, s83, 0
	global_load_ushort v198, v234, s[82:83]
	s_add_u32 s82, s82, 0x1600
	s_addc_u32 s83, s83, 0
	global_load_ushort v199, v234, s[82:83]
	s_add_u32 s82, s82, 0x1600
	s_addc_u32 s83, s83, 0
	global_load_ushort v200, v234, s[82:83]
	s_add_u32 s82, s82, 0x1600
	s_addc_u32 s83, s83, 0
	global_load_ushort v201, v234, s[82:83]
	s_add_u32 s82, s82, 0x1600
	s_addc_u32 s83, s83, 0
	global_load_ushort v202, v234, s[82:83]
	s_add_u32 s82, s82, 0x1600
	s_addc_u32 s83, s83, 0
	global_load_ushort v203, v234, s[82:83]
	s_add_u32 s82, s82, 0x1600
	s_addc_u32 s83, s83, 0
	global_load_ushort v204, v234, s[82:83]
	s_add_u32 s82, s82, 0x1600
	s_addc_u32 s83, s83, 0
	global_load_ushort v205, v234, s[82:83]
	s_waitcnt lgkmcnt(0)
	v_pk_fma_f32 v[0:1], v[0:1], v[248:249], v[242:243]
	v_pk_fma_f32 v[2:3], v[2:3], v[248:249], v[242:243]
	v_pk_fma_f32 v[4:5], v[4:5], v[248:249], v[242:243]
	v_pk_fma_f32 v[6:7], v[6:7], v[248:249], v[242:243]
	v_pk_fma_f32 v[8:9], v[8:9], v[248:249], v[242:243]
	v_pk_fma_f32 v[10:11], v[10:11], v[248:249], v[242:243]
	v_pk_fma_f32 v[12:13], v[12:13], v[248:249], v[242:243]
	v_pk_fma_f32 v[14:15], v[14:15], v[248:249], v[242:243]
	v_pk_fma_f32 v[16:17], v[16:17], v[248:249], v[244:245]
	v_pk_fma_f32 v[18:19], v[18:19], v[248:249], v[244:245]
	v_pk_fma_f32 v[20:21], v[20:21], v[248:249], v[244:245]
	v_pk_fma_f32 v[22:23], v[22:23], v[248:249], v[244:245]
	v_pk_fma_f32 v[24:25], v[24:25], v[248:249], v[244:245]
	v_pk_fma_f32 v[26:27], v[26:27], v[248:249], v[244:245]
	v_pk_fma_f32 v[28:29], v[28:29], v[248:249], v[244:245]
	v_pk_fma_f32 v[30:31], v[30:31], v[248:249], v[244:245]
	v_exp_f32_e32 v0, v0
	v_exp_f32_e32 v1, v1
	v_exp_f32_e32 v2, v2
	v_exp_f32_e32 v3, v3
	v_exp_f32_e32 v4, v4
	v_exp_f32_e32 v5, v5
	v_exp_f32_e32 v6, v6
	v_exp_f32_e32 v7, v7
	v_exp_f32_e32 v8, v8
	v_exp_f32_e32 v9, v9
	v_exp_f32_e32 v10, v10
	v_exp_f32_e32 v11, v11
	v_exp_f32_e32 v12, v12
	v_exp_f32_e32 v13, v13
	v_exp_f32_e32 v14, v14
	v_exp_f32_e32 v15, v15
	v_exp_f32_e32 v16, v16
	v_exp_f32_e32 v17, v17
	v_exp_f32_e32 v18, v18
	v_exp_f32_e32 v19, v19
	v_exp_f32_e32 v20, v20
	v_exp_f32_e32 v21, v21
	v_exp_f32_e32 v22, v22
	v_exp_f32_e32 v23, v23
	v_exp_f32_e32 v24, v24
	v_exp_f32_e32 v25, v25
	v_exp_f32_e32 v26, v26
	v_exp_f32_e32 v27, v27
	v_exp_f32_e32 v28, v28
	v_exp_f32_e32 v29, v29
	v_exp_f32_e32 v30, v30
	v_exp_f32_e32 v31, v31
	v_pk_add_f32 v[0:1], v[0:1], 1.0 op_sel_hi:[1,0]
	v_pk_add_f32 v[2:3], v[2:3], 1.0 op_sel_hi:[1,0]
	v_pk_add_f32 v[4:5], v[4:5], 1.0 op_sel_hi:[1,0]
	v_pk_add_f32 v[6:7], v[6:7], 1.0 op_sel_hi:[1,0]
	v_pk_add_f32 v[8:9], v[8:9], 1.0 op_sel_hi:[1,0]
	v_pk_add_f32 v[10:11], v[10:11], 1.0 op_sel_hi:[1,0]
	v_pk_add_f32 v[12:13], v[12:13], 1.0 op_sel_hi:[1,0]
	v_pk_add_f32 v[14:15], v[14:15], 1.0 op_sel_hi:[1,0]
	v_pk_add_f32 v[16:17], v[16:17], 1.0 op_sel_hi:[1,0]
	v_pk_add_f32 v[18:19], v[18:19], 1.0 op_sel_hi:[1,0]
	v_pk_add_f32 v[20:21], v[20:21], 1.0 op_sel_hi:[1,0]
	v_pk_add_f32 v[22:23], v[22:23], 1.0 op_sel_hi:[1,0]
	v_pk_add_f32 v[24:25], v[24:25], 1.0 op_sel_hi:[1,0]
	v_pk_add_f32 v[26:27], v[26:27], 1.0 op_sel_hi:[1,0]
; __device__ __forceinline__ unsigned f2bf(float f) { unsigned r; asm("v_cvt_pk_bf16_f32 %0, %1, %1" : "=v"(r) : "v"(f)); return r & 0xffffu; }
; __device__ __forceinline__ float sigmoid_f(float x) { return rcpf_(1.f + __expf(-x)); }
; __device__ __forceinline__ float gelu_tanh_f(float x) { const float y = 0.7978845608028654f * (x + 0.044715f * x * x * x); return x * sigmoid_f(2.f * y); }
; template <bool FINAL, int D>
; __device__ __forceinline__ void rg_dir(PREF p, int l, int h, int ch, int sidx, int rowbase  , LAS bf16_t* sXc, LAS float* stg, int lane) {
;     ...
;             const float r = sigmoid_f(zr), ig = sigmoid_f(zi);
;             const float a = __builtin_amdgcn_exp2f(r * sp8);
;             const float xc = bf2f(sXc[(mt * 16 + tk) * 72 + lane]);
;             av[ti] = a; iv[ti] = __builtin_amdgcn_sqrtf(fmaxf(1.f - a * a, 0.f)) * ig * xc;
;             if (FINAL && D == 1) grv[ti] = gelu_tanh_f(grv[ti]);
;         }
; #pragma unroll
;         for (int ti = 0; ti < 16; ++ti) { const int tk = D ? 15 - ti : ti;
;             hc = av[ti] * hc + iv[ti]; Ap *= av[ti];
;             if (FINAL) { const size_t row = (size_t)(rowbase + mt * 16 + tk);
;                 if (D == 0) TMP[row * 512 + ch] = (bf16_t)f2bf(hc);
;                 else MIX[row * DM + ch] = (bf16_t)f2bf(grv[ti] * (hfv[ti] + hc)); }
	v_pk_add_f32 v[28:29], v[28:29], 1.0 op_sel_hi:[1,0]
	v_pk_add_f32 v[30:31], v[30:31], 1.0 op_sel_hi:[1,0]
	v_rcp_f32_e32 v0, v0
	v_rcp_f32_e32 v1, v1
	v_rcp_f32_e32 v2, v2
	v_rcp_f32_e32 v3, v3
	v_rcp_f32_e32 v4, v4
	v_rcp_f32_e32 v5, v5
	v_rcp_f32_e32 v6, v6
	v_rcp_f32_e32 v7, v7
	v_rcp_f32_e32 v8, v8
	v_rcp_f32_e32 v9, v9
	v_rcp_f32_e32 v10, v10
	v_rcp_f32_e32 v11, v11
	v_rcp_f32_e32 v12, v12
	v_rcp_f32_e32 v13, v13
	v_rcp_f32_e32 v14, v14
	v_rcp_f32_e32 v15, v15
	v_rcp_f32_e32 v16, v16
	v_rcp_f32_e32 v17, v17
	v_rcp_f32_e32 v18, v18
	v_rcp_f32_e32 v19, v19
	v_rcp_f32_e32 v20, v20
	v_rcp_f32_e32 v21, v21
	v_rcp_f32_e32 v22, v22
	v_rcp_f32_e32 v23, v23
	v_rcp_f32_e32 v24, v24
	v_rcp_f32_e32 v25, v25
	v_rcp_f32_e32 v26, v26
	v_rcp_f32_e32 v27, v27
	v_rcp_f32_e32 v28, v28
	v_rcp_f32_e32 v29, v29
	v_rcp_f32_e32 v30, v30
	v_rcp_f32_e32 v31, v31
	v_pk_mul_f32 v[0:1], v[246:247], v[0:1]
	v_pk_mul_f32 v[2:3], v[246:247], v[2:3]
	v_pk_mul_f32 v[4:5], v[246:247], v[4:5]
	v_pk_mul_f32 v[6:7], v[246:247], v[6:7]
	v_pk_mul_f32 v[8:9], v[246:247], v[8:9]
	v_pk_mul_f32 v[10:11], v[246:247], v[10:11]
	v_pk_mul_f32 v[12:13], v[246:247], v[12:13]
	v_pk_mul_f32 v[14:15], v[246:247], v[14:15]
	v_exp_f32_e32 v0, v0
	v_exp_f32_e32 v1, v1
	v_exp_f32_e32 v2, v2
	v_exp_f32_e32 v3, v3
	v_exp_f32_e32 v4, v4
	v_exp_f32_e32 v5, v5
	v_exp_f32_e32 v6, v6
	v_exp_f32_e32 v7, v7
	v_exp_f32_e32 v8, v8
	v_exp_f32_e32 v9, v9
	v_exp_f32_e32 v10, v10
	v_exp_f32_e32 v11, v11
	v_exp_f32_e32 v12, v12
	v_exp_f32_e32 v13, v13
	v_exp_f32_e32 v14, v14
	v_exp_f32_e32 v15, v15
	v_fma_f32 v32, -v0, v0, 1.0 clamp
	v_fma_f32 v33, -v1, v1, 1.0 clamp
	v_fma_f32 v34, -v2, v2, 1.0 clamp
	v_fma_f32 v35, -v3, v3, 1.0 clamp
	v_fma_f32 v36, -v4, v4, 1.0 clamp
	v_fma_f32 v37, -v5, v5, 1.0 clamp
	v_fma_f32 v38, -v6, v6, 1.0 clamp
	v_fma_f32 v39, -v7, v7, 1.0 clamp
	v_fma_f32 v40, -v8, v8, 1.0 clamp
	v_fma_f32 v41, -v9, v9, 1.0 clamp
	v_fma_f32 v42, -v10, v10, 1.0 clamp
	v_fma_f32 v43, -v11, v11, 1.0 clamp
	v_fma_f32 v44, -v12, v12, 1.0 clamp
	v_fma_f32 v45, -v13, v13, 1.0 clamp
	v_fma_f32 v46, -v14, v14, 1.0 clamp
	v_fma_f32 v47, -v15, v15, 1.0 clamp
	v_sqrt_f32_e32 v32, v32
	v_sqrt_f32_e32 v33, v33
	v_sqrt_f32_e32 v34, v34
	v_sqrt_f32_e32 v35, v35
	v_sqrt_f32_e32 v36, v36
	v_sqrt_f32_e32 v37, v37
	v_sqrt_f32_e32 v38, v38
	v_sqrt_f32_e32 v39, v39
	v_sqrt_f32_e32 v40, v40
	v_sqrt_f32_e32 v41, v41
	v_sqrt_f32_e32 v42, v42
	v_sqrt_f32_e32 v43, v43
	v_sqrt_f32_e32 v44, v44
	v_sqrt_f32_e32 v45, v45
	v_sqrt_f32_e32 v46, v46
	v_sqrt_f32_e32 v47, v47
	s_nop 0
	v_pk_mul_f32 v[16:17], v[16:17], v[32:33]
	v_pk_mul_f32 v[18:19], v[18:19], v[34:35]
	v_pk_mul_f32 v[20:21], v[20:21], v[36:37]
	v_pk_mul_f32 v[22:23], v[22:23], v[38:39]
	v_pk_mul_f32 v[24:25], v[24:25], v[40:41]
	v_pk_mul_f32 v[26:27], v[26:27], v[42:43]
	v_pk_mul_f32 v[28:29], v[28:29], v[44:45]
	v_pk_mul_f32 v[30:31], v[30:31], v[46:47]
	v_pk_mul_f32 v[16:17], v[16:17], v[48:49]
	v_pk_mul_f32 v[18:19], v[18:19], v[50:51]
	v_pk_mul_f32 v[20:21], v[20:21], v[52:53]
	v_pk_mul_f32 v[22:23], v[22:23], v[54:55]
	v_pk_mul_f32 v[24:25], v[24:25], v[56:57]
	v_pk_mul_f32 v[26:27], v[26:27], v[58:59]
	v_pk_mul_f32 v[28:29], v[28:29], v[60:61]
	v_pk_mul_f32 v[30:31], v[30:31], v[62:63]
	s_add_i32 s39, s15, 30
	s_lshl_b32 s39, s39, 11
	s_add_u32 s90, s0, 0x7b00000
	s_addc_u32 s91, s1, 0
	s_add_u32 s90, s90, s39
	s_addc_u32 s91, s91, 0
	v_lshlrev_b32_e32 v48, 16, v166
	v_and_b32_e32 v49, 0xffff0000, v166
	v_lshlrev_b32_e32 v50, 16, v167
	v_and_b32_e32 v51, 0xffff0000, v167
	v_lshlrev_b32_e32 v52, 16, v168
	v_and_b32_e32 v53, 0xffff0000, v168
	v_lshlrev_b32_e32 v54, 16, v169
	v_and_b32_e32 v55, 0xffff0000, v169
	v_lshlrev_b32_e32 v56, 16, v170
	v_and_b32_e32 v57, 0xffff0000, v170
	v_lshlrev_b32_e32 v58, 16, v171
	v_and_b32_e32 v59, 0xffff0000, v171
	v_lshlrev_b32_e32 v60, 16, v172
	v_and_b32_e32 v61, 0xffff0000, v172
	v_lshlrev_b32_e32 v62, 16, v173
	v_and_b32_e32 v63, 0xffff0000, v173
	v_fma_f32 v47, v15, v250, v31
	v_fma_f32 v46, v14, v47, v30
	v_fma_f32 v45, v13, v46, v29
	v_fma_f32 v44, v12, v45, v28
	v_fma_f32 v43, v11, v44, v27
	v_fma_f32 v42, v10, v43, v26
	v_fma_f32 v41, v9, v42, v25
	v_fma_f32 v40, v8, v41, v24
	v_fma_f32 v39, v7, v40, v23
	v_fma_f32 v38, v6, v39, v22
	v_fma_f32 v37, v5, v38, v21
	v_fma_f32 v36, v4, v37, v20
	v_fma_f32 v35, v3, v36, v19
	v_fma_f32 v34, v2, v35, v18
	v_fma_f32 v33, v1, v34, v17
	v_fma_f32 v32, v0, v33, v16
	v_mov_b32_e32 v250, v32
	v_pk_add_f32 v[32:33], v[48:49], v[32:33]
	v_pk_add_f32 v[34:35], v[50:51], v[34:35]
	v_pk_add_f32 v[36:37], v[52:53], v[36:37]
	v_pk_add_f32 v[38:39], v[54:55], v[38:39]
	v_pk_add_f32 v[40:41], v[56:57], v[40:41]
	v_pk_add_f32 v[42:43], v[58:59], v[42:43]
	v_pk_add_f32 v[44:45], v[60:61], v[44:45]
	v_pk_add_f32 v[46:47], v[62:63], v[46:47]
	v_pk_mul_f32 v[32:33], v[206:207], v[32:33]
	v_pk_mul_f32 v[34:35], v[208:209], v[34:35]
	v_pk_mul_f32 v[36:37], v[210:211], v[36:37]
	v_pk_mul_f32 v[38:39], v[212:213], v[38:39]
	v_pk_mul_f32 v[40:41], v[214:215], v[40:41]
	v_pk_mul_f32 v[42:43], v[216:217], v[42:43]
	v_pk_mul_f32 v[44:45], v[218:219], v[44:45]
	v_pk_mul_f32 v[46:47], v[222:223], v[46:47]
	v_cvt_pk_bf16_f32 v32, v32, v33
	v_cvt_pk_bf16_f32 v34, v34, v35
	v_cvt_pk_bf16_f32 v36, v36, v37
	v_cvt_pk_bf16_f32 v38, v38, v39
	v_cvt_pk_bf16_f32 v40, v40, v41
	v_cvt_pk_bf16_f32 v42, v42, v43
	v_cvt_pk_bf16_f32 v44, v44, v45
	v_cvt_pk_bf16_f32 v46, v46, v47
	global_store_short_d16_hi v234, v46, s[90:91] offset:2048
	global_store_short v234, v46, s[90:91]
	s_sub_u32 s90, s90, 0x1000
	s_subb_u32 s91, s91, 0
	global_store_short_d16_hi v234, v44, s[90:91] offset:2048
	global_store_short v234, v44, s[90:91]
	s_sub_u32 s90, s90, 0x1000
	s_subb_u32 s91, s91, 0
	global_store_short_d16_hi v234, v42, s[90:91] offset:2048
	global_store_short v234, v42, s[90:91]
	s_sub_u32 s90, s90, 0x1000
	s_subb_u32 s91, s91, 0
	global_store_short_d16_hi v234, v40, s[90:91] offset:2048
	global_store_short v234, v40, s[90:91]
	s_sub_u32 s90, s90, 0x1000
	s_subb_u32 s91, s91, 0
	global_store_short_d16_hi v234, v38, s[90:91] offset:2048
	global_store_short v234, v38, s[90:91]
	s_sub_u32 s90, s90, 0x1000
	s_subb_u32 s91, s91, 0
	global_store_short_d16_hi v234, v36, s[90:91] offset:2048
	global_store_short v234, v36, s[90:91]
	s_sub_u32 s90, s90, 0x1000
	s_subb_u32 s91, s91, 0
	global_store_short_d16_hi v234, v34, s[90:91] offset:2048
	global_store_short v234, v34, s[90:91]
	s_sub_u32 s90, s90, 0x1000
	s_subb_u32 s91, s91, 0
	global_store_short_d16_hi v234, v32, s[90:91] offset:2048
	global_store_short v234, v32, s[90:91]
	ds_read_b128 v[32:35], v236 offset:0
	ds_read_b128 v[36:39], v236 offset:64
	s_waitcnt lgkmcnt(0)
; #define LAS __attribute__((address_space(3)))
; #define WAVE_SYNC() asm volatile("s_waitcnt lgkmcnt(0)" ::: "memory")
; __device__ __forceinline__ float sigmoid_f(float x) { return rcpf_(1.f + __expf(-x)); }
; __device__ __forceinline__ float gelu_tanh_f(float x) { const float y = 0.7978845608028654f * (x + 0.044715f * x * x * x); return x * sigmoid_f(2.f * y); }
; __device__ __forceinline__ f32x4 mfma16(bf16x8 a, bf16x8 b, f32x4 c) { return __builtin_amdgcn_mfma_f32_16x16x32_bf16(a, b, c, 0, 0, 0); }
; template <bool FINAL, int D>
; __device__ __forceinline__ void rg_dir(PREF p, int l, int h, int ch, int sidx, int rowbase  , LAS bf16_t* sXc, LAS float* stg, int lane) {
;     ...
;         const bf16x8 A0 = *(const LAS bf16x8*)(sXc + (mt * 16 + (lane & 15)) * 72 + (lane >> 4) * 8), A1 = *(const LAS bf16x8*)(sXc + (mt * 16 + (lane & 15)) * 72 + 32 + (lane >> 4) * 8);
;         f32x4 ar[4], ai[4];
; #pragma unroll
;         for (int nt = 0; nt < 4; ++nt) { const f32x4 z = {0.f, 0.f, 0.f, 0.f};
;             ar[nt] = mfma16(A0, Br[nt][0], z); ar[nt] = mfma16(A1, Br[nt][1], ar[nt]); ai[nt] = mfma16(A0, Bi[nt][0], z); ai[nt] = mfma16(A1, Bi[nt][1], ai[nt]); }
;         WAVE_SYNC();
; #pragma unroll
;         for (int nt = 0; nt < 4; ++nt)
; #pragma unroll
;             for (int j = 0; j < 4; ++j) { const int o = ((lane >> 4) * 4 + j) * 64 + nt * 16 + (lane & 15); stg[o] = ar[nt][j]; stg[1024 + o] = ai[nt][j]; }
;         WAVE_SYNC();
;         float av[16], iv[16];
; #pragma unroll
;         for (int ti = 0; ti < 16; ++ti) { const int tk = D ? 15 - ti : ti;
;             const float zr = stg[tk * 64 + lane] + ba, zi = stg[1024 + tk * 64 + lane] + bi;
;             const float r = sigmoid_f(zr), ig = sigmoid_f(zi);
;             const float a = __builtin_amdgcn_exp2f(r * sp8);
;             const float xc = bf2f(sXc[(mt * 16 + tk) * 72 + lane]);
;             av[ti] = a; iv[ti] = __builtin_amdgcn_sqrtf(fmaxf(1.f - a * a, 0.f)) * ig * xc;
;             if (FINAL && D == 1) grv[ti] = gelu_tanh_f(grv[ti]);
	v_mfma_f32_16x16x32_bf16 v[0:3], v[32:35], v[80:83], 0
	v_mfma_f32_16x16x32_bf16 v[4:7], v[32:35], v[88:91], 0
	v_mfma_f32_16x16x32_bf16 v[8:11], v[32:35], v[96:99], 0
	v_mfma_f32_16x16x32_bf16 v[12:15], v[32:35], v[104:107], 0
	v_mfma_f32_16x16x32_bf16 v[16:19], v[32:35], v[112:115], 0
	v_mfma_f32_16x16x32_bf16 v[20:23], v[32:35], v[120:123], 0
	v_mfma_f32_16x16x32_bf16 v[24:27], v[32:35], v[128:131], 0
	v_mfma_f32_16x16x32_bf16 v[28:31], v[32:35], v[136:139], 0
	v_mfma_f32_16x16x32_bf16 v[0:3], v[36:39], v[84:87], v[0:3]
	v_mfma_f32_16x16x32_bf16 v[4:7], v[36:39], v[92:95], v[4:7]
	v_mfma_f32_16x16x32_bf16 v[8:11], v[36:39], v[100:103], v[8:11]
	v_mfma_f32_16x16x32_bf16 v[12:15], v[36:39], v[108:111], v[12:15]
	v_mfma_f32_16x16x32_bf16 v[16:19], v[36:39], v[116:119], v[16:19]
	v_mfma_f32_16x16x32_bf16 v[20:23], v[36:39], v[124:127], v[20:23]
	v_mfma_f32_16x16x32_bf16 v[24:27], v[36:39], v[132:135], v[24:27]
	v_mfma_f32_16x16x32_bf16 v[28:31], v[36:39], v[228:231], v[28:31]
	s_nop 3
	ds_write2_b32 v237, v0, v4 offset0:0 offset1:16
	ds_write2_b32 v237, v8, v12 offset0:32 offset1:48
	ds_write2_b32 v237, v1, v5 offset0:64 offset1:80
	ds_write2_b32 v237, v9, v13 offset0:96 offset1:112
	ds_write2_b32 v237, v2, v6 offset0:128 offset1:144
	ds_write2_b32 v237, v10, v14 offset0:160 offset1:176
	ds_write2_b32 v237, v3, v7 offset0:192 offset1:208
	ds_write2_b32 v237, v11, v15 offset0:224 offset1:240
	ds_write2_b32 v238, v16, v20 offset0:0 offset1:16
	ds_write2_b32 v238, v24, v28 offset0:32 offset1:48
	ds_write2_b32 v238, v17, v21 offset0:64 offset1:80
	ds_write2_b32 v238, v25, v29 offset0:96 offset1:112
	ds_write2_b32 v238, v18, v22 offset0:128 offset1:144
	ds_write2_b32 v238, v26, v30 offset0:160 offset1:176
	ds_write2_b32 v238, v19, v23 offset0:192 offset1:208
	ds_write2_b32 v238, v27, v31 offset0:224 offset1:240
	s_waitcnt lgkmcnt(0)
	ds_read2st64_b32 v[0:1], v239 offset0:36 offset1:37
	ds_read2st64_b32 v[2:3], v239 offset0:38 offset1:39
	ds_read2st64_b32 v[4:5], v239 offset0:40 offset1:41
	ds_read2st64_b32 v[6:7], v239 offset0:42 offset1:43
	ds_read2st64_b32 v[8:9], v239 offset0:44 offset1:45
	ds_read2st64_b32 v[10:11], v239 offset0:46 offset1:47
	ds_read2st64_b32 v[12:13], v239 offset0:48 offset1:49
	ds_read2st64_b32 v[14:15], v239 offset0:50 offset1:51
	ds_read2st64_b32 v[16:17], v239 offset0:52 offset1:53
	ds_read2st64_b32 v[18:19], v239 offset0:54 offset1:55
	ds_read2st64_b32 v[20:21], v239 offset0:56 offset1:57
	ds_read2st64_b32 v[22:23], v239 offset0:58 offset1:59
	ds_read2st64_b32 v[24:25], v239 offset0:60 offset1:61
	ds_read2st64_b32 v[26:27], v239 offset0:62 offset1:63
	ds_read2st64_b32 v[28:29], v239 offset0:64 offset1:65
	ds_read2st64_b32 v[30:31], v239 offset0:66 offset1:67
	ds_read_u16_d16_hi v48, v240 offset:0
	ds_read_u16_d16_hi v49, v240 offset:144
	ds_read_u16_d16_hi v50, v240 offset:288
	ds_read_u16_d16_hi v51, v240 offset:432
	ds_read_u16_d16_hi v52, v240 offset:576
	ds_read_u16_d16_hi v53, v240 offset:720
	ds_read_u16_d16_hi v54, v240 offset:864
	ds_read_u16_d16_hi v55, v240 offset:1008
	ds_read_u16_d16_hi v56, v240 offset:1152
	ds_read_u16_d16_hi v57, v240 offset:1296
	ds_read_u16_d16_hi v58, v240 offset:1440
	ds_read_u16_d16_hi v59, v240 offset:1584
	ds_read_u16_d16_hi v60, v240 offset:1728
	ds_read_u16_d16_hi v61, v240 offset:1872
	ds_read_u16_d16_hi v62, v240 offset:2016
	ds_read_u16_d16_hi v63, v240 offset:2160
	s_waitcnt vmcnt(16)
	v_lshlrev_b32_e32 v206, 16, v190
	v_lshlrev_b32_e32 v207, 16, v191
	v_lshlrev_b32_e32 v208, 16, v192
	v_lshlrev_b32_e32 v209, 16, v193
	v_lshlrev_b32_e32 v210, 16, v194
	v_lshlrev_b32_e32 v211, 16, v195
	v_lshlrev_b32_e32 v212, 16, v196
	v_lshlrev_b32_e32 v213, 16, v197
	v_lshlrev_b32_e32 v214, 16, v198
	v_lshlrev_b32_e32 v215, 16, v199
	v_lshlrev_b32_e32 v216, 16, v200
	v_lshlrev_b32_e32 v217, 16, v201
	v_lshlrev_b32_e32 v218, 16, v202
	v_lshlrev_b32_e32 v219, 16, v203
	v_lshlrev_b32_e32 v222, 16, v204
	v_lshlrev_b32_e32 v223, 16, v205
	v_pk_mul_f32 v[32:33], v[140:141], v[206:207]
	v_pk_mul_f32 v[34:35], v[140:141], v[208:209]
	v_pk_mul_f32 v[36:37], v[140:141], v[210:211]
	v_pk_mul_f32 v[38:39], v[140:141], v[212:213]
	v_pk_mul_f32 v[40:41], v[140:141], v[214:215]
	v_pk_mul_f32 v[42:43], v[140:141], v[216:217]
	v_pk_mul_f32 v[44:45], v[140:141], v[218:219]
	v_pk_mul_f32 v[46:47], v[140:141], v[222:223]
	v_pk_mul_f32 v[32:33], v[32:33], v[206:207]
	v_pk_mul_f32 v[34:35], v[34:35], v[208:209]
	v_pk_mul_f32 v[36:37], v[36:37], v[210:211]
	v_pk_mul_f32 v[38:39], v[38:39], v[212:213]
	v_pk_mul_f32 v[40:41], v[40:41], v[214:215]
	v_pk_mul_f32 v[42:43], v[42:43], v[216:217]
	v_pk_mul_f32 v[44:45], v[44:45], v[218:219]
	v_pk_mul_f32 v[46:47], v[46:47], v[222:223]
	v_fma_f32 v32, v32, v206, v206
	v_fma_f32 v33, v33, v207, v207
	v_fma_f32 v34, v34, v208, v208
	v_fma_f32 v35, v35, v209, v209
	v_fma_f32 v36, v36, v210, v210
	v_fma_f32 v37, v37, v211, v211
	v_fma_f32 v38, v38, v212, v212
	v_fma_f32 v39, v39, v213, v213
	v_fma_f32 v40, v40, v214, v214
	v_fma_f32 v41, v41, v215, v215
	v_fma_f32 v42, v42, v216, v216
	v_fma_f32 v43, v43, v217, v217
	v_fma_f32 v44, v44, v218, v218
	v_fma_f32 v45, v45, v219, v219
	v_fma_f32 v46, v46, v222, v222
	v_fma_f32 v47, v47, v223, v223
	s_mov_b32 s98, 0xc0135761
	v_pk_mul_f32 v[32:33], v[32:33], s[98:99] op_sel_hi:[1,0]
	v_pk_mul_f32 v[34:35], v[34:35], s[98:99] op_sel_hi:[1,0]
	v_pk_mul_f32 v[36:37], v[36:37], s[98:99] op_sel_hi:[1,0]
	v_pk_mul_f32 v[38:39], v[38:39], s[98:99] op_sel_hi:[1,0]
	v_pk_mul_f32 v[40:41], v[40:41], s[98:99] op_sel_hi:[1,0]
	v_pk_mul_f32 v[42:43], v[42:43], s[98:99] op_sel_hi:[1,0]
	v_pk_mul_f32 v[44:45], v[44:45], s[98:99] op_sel_hi:[1,0]
; __device__ __forceinline__ float sigmoid_f(float x) { return rcpf_(1.f + __expf(-x)); }
; __device__ __forceinline__ float gelu_tanh_f(float x) { const float y = 0.7978845608028654f * (x + 0.044715f * x * x * x); return x * sigmoid_f(2.f * y); }
; template <bool FINAL, int D>
; __device__ __forceinline__ void rg_dir(PREF p, int l, int h, int ch, int sidx, int rowbase  , LAS bf16_t* sXc, LAS float* stg, int lane) {
;     ...
;             const float zr = stg[tk * 64 + lane] + ba, zi = stg[1024 + tk * 64 + lane] + bi;
;             const float r = sigmoid_f(zr), ig = sigmoid_f(zi);
;             const float a = __builtin_amdgcn_exp2f(r * sp8);
;             const float xc = bf2f(sXc[(mt * 16 + tk) * 72 + lane]);
;             av[ti] = a; iv[ti] = __builtin_amdgcn_sqrtf(fmaxf(1.f - a * a, 0.f)) * ig * xc;
;             if (FINAL && D == 1) grv[ti] = gelu_tanh_f(grv[ti]);
	v_pk_mul_f32 v[46:47], v[46:47], s[98:99] op_sel_hi:[1,0]
	v_exp_f32_e32 v32, v32
	v_exp_f32_e32 v33, v33
	v_exp_f32_e32 v34, v34
	v_exp_f32_e32 v35, v35
	v_exp_f32_e32 v36, v36
	v_exp_f32_e32 v37, v37
	v_exp_f32_e32 v38, v38
	v_exp_f32_e32 v39, v39
	v_exp_f32_e32 v40, v40
	v_exp_f32_e32 v41, v41
	v_exp_f32_e32 v42, v42
	v_exp_f32_e32 v43, v43
	v_exp_f32_e32 v44, v44
	v_exp_f32_e32 v45, v45
	v_exp_f32_e32 v46, v46
	v_exp_f32_e32 v47, v47
	v_pk_add_f32 v[32:33], v[32:33], 1.0 op_sel_hi:[1,0]
	v_pk_add_f32 v[34:35], v[34:35], 1.0 op_sel_hi:[1,0]
	v_pk_add_f32 v[36:37], v[36:37], 1.0 op_sel_hi:[1,0]
	v_pk_add_f32 v[38:39], v[38:39], 1.0 op_sel_hi:[1,0]
	v_pk_add_f32 v[40:41], v[40:41], 1.0 op_sel_hi:[1,0]
	v_pk_add_f32 v[42:43], v[42:43], 1.0 op_sel_hi:[1,0]
	v_pk_add_f32 v[44:45], v[44:45], 1.0 op_sel_hi:[1,0]
	v_pk_add_f32 v[46:47], v[46:47], 1.0 op_sel_hi:[1,0]
	v_rcp_f32_e32 v32, v32
	v_rcp_f32_e32 v33, v33
	v_rcp_f32_e32 v34, v34
	v_rcp_f32_e32 v35, v35
	v_rcp_f32_e32 v36, v36
	v_rcp_f32_e32 v37, v37
	v_rcp_f32_e32 v38, v38
	v_rcp_f32_e32 v39, v39
	v_rcp_f32_e32 v40, v40
	v_rcp_f32_e32 v41, v41
	v_rcp_f32_e32 v42, v42
	v_rcp_f32_e32 v43, v43
	v_rcp_f32_e32 v44, v44
	v_rcp_f32_e32 v45, v45
	v_rcp_f32_e32 v46, v46
	v_rcp_f32_e32 v47, v47
	s_nop 0
	v_pk_mul_f32 v[206:207], v[32:33], v[206:207]
	v_pk_mul_f32 v[208:209], v[34:35], v[208:209]
	v_pk_mul_f32 v[210:211], v[36:37], v[210:211]
	v_pk_mul_f32 v[212:213], v[38:39], v[212:213]
	v_pk_mul_f32 v[214:215], v[40:41], v[214:215]
	v_pk_mul_f32 v[216:217], v[42:43], v[216:217]
	v_pk_mul_f32 v[218:219], v[44:45], v[218:219]
	v_pk_mul_f32 v[222:223], v[46:47], v[222:223]
	s_waitcnt lgkmcnt(0)
	v_pk_fma_f32 v[0:1], v[0:1], v[248:249], v[242:243]
	v_pk_fma_f32 v[2:3], v[2:3], v[248:249], v[242:243]
	v_pk_fma_f32 v[4:5], v[4:5], v[248:249], v[242:243]
	v_pk_fma_f32 v[6:7], v[6:7], v[248:249], v[242:243]
	v_pk_fma_f32 v[8:9], v[8:9], v[248:249], v[242:243]
	v_pk_fma_f32 v[10:11], v[10:11], v[248:249], v[242:243]
	v_pk_fma_f32 v[12:13], v[12:13], v[248:249], v[242:243]
	v_pk_fma_f32 v[14:15], v[14:15], v[248:249], v[242:243]
	v_pk_fma_f32 v[16:17], v[16:17], v[248:249], v[244:245]
	v_pk_fma_f32 v[18:19], v[18:19], v[248:249], v[244:245]
	v_pk_fma_f32 v[20:21], v[20:21], v[248:249], v[244:245]
	v_pk_fma_f32 v[22:23], v[22:23], v[248:249], v[244:245]
	v_pk_fma_f32 v[24:25], v[24:25], v[248:249], v[244:245]
	v_pk_fma_f32 v[26:27], v[26:27], v[248:249], v[244:245]
	v_pk_fma_f32 v[28:29], v[28:29], v[248:249], v[244:245]
	v_pk_fma_f32 v[30:31], v[30:31], v[248:249], v[244:245]
	v_exp_f32_e32 v0, v0
	v_exp_f32_e32 v1, v1
	v_exp_f32_e32 v2, v2
	v_exp_f32_e32 v3, v3
	v_exp_f32_e32 v4, v4
	v_exp_f32_e32 v5, v5
	v_exp_f32_e32 v6, v6
	v_exp_f32_e32 v7, v7
	v_exp_f32_e32 v8, v8
	v_exp_f32_e32 v9, v9
	v_exp_f32_e32 v10, v10
	v_exp_f32_e32 v11, v11
	v_exp_f32_e32 v12, v12
	v_exp_f32_e32 v13, v13
	v_exp_f32_e32 v14, v14
	v_exp_f32_e32 v15, v15
	v_exp_f32_e32 v16, v16
	v_exp_f32_e32 v17, v17
	v_exp_f32_e32 v18, v18
	v_exp_f32_e32 v19, v19
	v_exp_f32_e32 v20, v20
	v_exp_f32_e32 v21, v21
	v_exp_f32_e32 v22, v22
	v_exp_f32_e32 v23, v23
	v_exp_f32_e32 v24, v24
	v_exp_f32_e32 v25, v25
	v_exp_f32_e32 v26, v26
	v_exp_f32_e32 v27, v27
	v_exp_f32_e32 v28, v28
	v_exp_f32_e32 v29, v29
	v_exp_f32_e32 v30, v30
	v_exp_f32_e32 v31, v31
	v_pk_add_f32 v[0:1], v[0:1], 1.0 op_sel_hi:[1,0]
	v_pk_add_f32 v[2:3], v[2:3], 1.0 op_sel_hi:[1,0]
	v_pk_add_f32 v[4:5], v[4:5], 1.0 op_sel_hi:[1,0]
	v_pk_add_f32 v[6:7], v[6:7], 1.0 op_sel_hi:[1,0]
	v_pk_add_f32 v[8:9], v[8:9], 1.0 op_sel_hi:[1,0]
	v_pk_add_f32 v[10:11], v[10:11], 1.0 op_sel_hi:[1,0]
	v_pk_add_f32 v[12:13], v[12:13], 1.0 op_sel_hi:[1,0]
	v_pk_add_f32 v[14:15], v[14:15], 1.0 op_sel_hi:[1,0]
	v_pk_add_f32 v[16:17], v[16:17], 1.0 op_sel_hi:[1,0]
	v_pk_add_f32 v[18:19], v[18:19], 1.0 op_sel_hi:[1,0]
	v_pk_add_f32 v[20:21], v[20:21], 1.0 op_sel_hi:[1,0]
	v_pk_add_f32 v[22:23], v[22:23], 1.0 op_sel_hi:[1,0]
	v_pk_add_f32 v[24:25], v[24:25], 1.0 op_sel_hi:[1,0]
	v_pk_add_f32 v[26:27], v[26:27], 1.0 op_sel_hi:[1,0]
	v_pk_add_f32 v[28:29], v[28:29], 1.0 op_sel_hi:[1,0]
	v_pk_add_f32 v[30:31], v[30:31], 1.0 op_sel_hi:[1,0]
	v_rcp_f32_e32 v0, v0
	v_rcp_f32_e32 v1, v1
	v_rcp_f32_e32 v2, v2
	v_rcp_f32_e32 v3, v3
	v_rcp_f32_e32 v4, v4
	v_rcp_f32_e32 v5, v5
	v_rcp_f32_e32 v6, v6
	v_rcp_f32_e32 v7, v7
	v_rcp_f32_e32 v8, v8
	v_rcp_f32_e32 v9, v9
	v_rcp_f32_e32 v10, v10
	v_rcp_f32_e32 v11, v11
	v_rcp_f32_e32 v12, v12
	v_rcp_f32_e32 v13, v13
	v_rcp_f32_e32 v14, v14
	v_rcp_f32_e32 v15, v15
	v_rcp_f32_e32 v16, v16
	v_rcp_f32_e32 v17, v17
	v_rcp_f32_e32 v18, v18
	v_rcp_f32_e32 v19, v19
	v_rcp_f32_e32 v20, v20
	v_rcp_f32_e32 v21, v21
	v_rcp_f32_e32 v22, v22
	v_rcp_f32_e32 v23, v23
	v_rcp_f32_e32 v24, v24
	v_rcp_f32_e32 v25, v25
	v_rcp_f32_e32 v26, v26
	v_rcp_f32_e32 v27, v27
	v_rcp_f32_e32 v28, v28
	v_rcp_f32_e32 v29, v29
	v_rcp_f32_e32 v30, v30
	v_rcp_f32_e32 v31, v31
	v_pk_mul_f32 v[0:1], v[246:247], v[0:1]
	v_pk_mul_f32 v[2:3], v[246:247], v[2:3]
	v_pk_mul_f32 v[4:5], v[246:247], v[4:5]
	v_pk_mul_f32 v[6:7], v[246:247], v[6:7]
	v_pk_mul_f32 v[8:9], v[246:247], v[8:9]
	v_pk_mul_f32 v[10:11], v[246:247], v[10:11]
	v_pk_mul_f32 v[12:13], v[246:247], v[12:13]
	v_pk_mul_f32 v[14:15], v[246:247], v[14:15]
	v_exp_f32_e32 v0, v0
	v_exp_f32_e32 v1, v1
	v_exp_f32_e32 v2, v2
	v_exp_f32_e32 v3, v3
	v_exp_f32_e32 v4, v4
	v_exp_f32_e32 v5, v5
	v_exp_f32_e32 v6, v6
	v_exp_f32_e32 v7, v7
	v_exp_f32_e32 v8, v8
	v_exp_f32_e32 v9, v9
; __device__ __forceinline__ unsigned f2bf(float f) { unsigned r; asm("v_cvt_pk_bf16_f32 %0, %1, %1" : "=v"(r) : "v"(f)); return r & 0xffffu; }
; __device__ __forceinline__ float sigmoid_f(float x) { return rcpf_(1.f + __expf(-x)); }
; __device__ __forceinline__ float gelu_tanh_f(float x) { const float y = 0.7978845608028654f * (x + 0.044715f * x * x * x); return x * sigmoid_f(2.f * y); }
; template <bool FINAL, int D>
; __device__ __forceinline__ void rg_dir(PREF p, int l, int h, int ch, int sidx, int rowbase  , LAS bf16_t* sXc, LAS float* stg, int lane) {
;     ...
;             const float r = sigmoid_f(zr), ig = sigmoid_f(zi);
;             const float a = __builtin_amdgcn_exp2f(r * sp8);
;             const float xc = bf2f(sXc[(mt * 16 + tk) * 72 + lane]);
;             av[ti] = a; iv[ti] = __builtin_amdgcn_sqrtf(fmaxf(1.f - a * a, 0.f)) * ig * xc;
;             if (FINAL && D == 1) grv[ti] = gelu_tanh_f(grv[ti]);
;         }
; #pragma unroll
;         for (int ti = 0; ti < 16; ++ti) { const int tk = D ? 15 - ti : ti;
;             hc = av[ti] * hc + iv[ti]; Ap *= av[ti];
;             if (FINAL) { const size_t row = (size_t)(rowbase + mt * 16 + tk);
;                 if (D == 0) TMP[row * 512 + ch] = (bf16_t)f2bf(hc);
;                 else MIX[row * DM + ch] = (bf16_t)f2bf(grv[ti] * (hfv[ti] + hc)); }
; __global__ void __launch_bounds__(NTHREADS, 2) mega_fwd(Params p_arg) {
;     ...
;             for (int item = gw; item < nrg; item += NGW) rg_item<true>(p, l, item, lds + wave * 18432, lane);
	v_exp_f32_e32 v10, v10
	v_exp_f32_e32 v11, v11
	v_exp_f32_e32 v12, v12
	v_exp_f32_e32 v13, v13
	v_exp_f32_e32 v14, v14
	v_exp_f32_e32 v15, v15
	v_fma_f32 v32, -v0, v0, 1.0 clamp
	v_fma_f32 v33, -v1, v1, 1.0 clamp
	v_fma_f32 v34, -v2, v2, 1.0 clamp
	v_fma_f32 v35, -v3, v3, 1.0 clamp
	v_fma_f32 v36, -v4, v4, 1.0 clamp
	v_fma_f32 v37, -v5, v5, 1.0 clamp
	v_fma_f32 v38, -v6, v6, 1.0 clamp
	v_fma_f32 v39, -v7, v7, 1.0 clamp
	v_fma_f32 v40, -v8, v8, 1.0 clamp
	v_fma_f32 v41, -v9, v9, 1.0 clamp
	v_fma_f32 v42, -v10, v10, 1.0 clamp
	v_fma_f32 v43, -v11, v11, 1.0 clamp
	v_fma_f32 v44, -v12, v12, 1.0 clamp
	v_fma_f32 v45, -v13, v13, 1.0 clamp
	v_fma_f32 v46, -v14, v14, 1.0 clamp
	v_fma_f32 v47, -v15, v15, 1.0 clamp
	v_sqrt_f32_e32 v32, v32
	v_sqrt_f32_e32 v33, v33
	v_sqrt_f32_e32 v34, v34
	v_sqrt_f32_e32 v35, v35
	v_sqrt_f32_e32 v36, v36
	v_sqrt_f32_e32 v37, v37
	v_sqrt_f32_e32 v38, v38
	v_sqrt_f32_e32 v39, v39
	v_sqrt_f32_e32 v40, v40
	v_sqrt_f32_e32 v41, v41
	v_sqrt_f32_e32 v42, v42
	v_sqrt_f32_e32 v43, v43
	v_sqrt_f32_e32 v44, v44
	v_sqrt_f32_e32 v45, v45
	v_sqrt_f32_e32 v46, v46
	v_sqrt_f32_e32 v47, v47
	s_nop 0
	v_pk_mul_f32 v[16:17], v[16:17], v[32:33]
	v_pk_mul_f32 v[18:19], v[18:19], v[34:35]
	v_pk_mul_f32 v[20:21], v[20:21], v[36:37]
	v_pk_mul_f32 v[22:23], v[22:23], v[38:39]
	v_pk_mul_f32 v[24:25], v[24:25], v[40:41]
	v_pk_mul_f32 v[26:27], v[26:27], v[42:43]
	v_pk_mul_f32 v[28:29], v[28:29], v[44:45]
	v_pk_mul_f32 v[30:31], v[30:31], v[46:47]
	v_pk_mul_f32 v[16:17], v[16:17], v[48:49]
	v_pk_mul_f32 v[18:19], v[18:19], v[50:51]
	v_pk_mul_f32 v[20:21], v[20:21], v[52:53]
	v_pk_mul_f32 v[22:23], v[22:23], v[54:55]
	v_pk_mul_f32 v[24:25], v[24:25], v[56:57]
	v_pk_mul_f32 v[26:27], v[26:27], v[58:59]
	v_pk_mul_f32 v[28:29], v[28:29], v[60:61]
	v_pk_mul_f32 v[30:31], v[30:31], v[62:63]
	s_add_i32 s39, s15, 14
	s_lshl_b32 s39, s39, 11
	s_add_u32 s90, s0, 0x7b00000
	s_addc_u32 s91, s1, 0
	s_add_u32 s90, s90, s39
	s_addc_u32 s91, s91, 0
	v_lshlrev_b32_e32 v48, 16, v158
	v_and_b32_e32 v49, 0xffff0000, v158
	v_lshlrev_b32_e32 v50, 16, v159
	v_and_b32_e32 v51, 0xffff0000, v159
	v_lshlrev_b32_e32 v52, 16, v160
	v_and_b32_e32 v53, 0xffff0000, v160
	v_lshlrev_b32_e32 v54, 16, v161
	v_and_b32_e32 v55, 0xffff0000, v161
	v_lshlrev_b32_e32 v56, 16, v162
	v_and_b32_e32 v57, 0xffff0000, v162
	v_lshlrev_b32_e32 v58, 16, v163
	v_and_b32_e32 v59, 0xffff0000, v163
	v_lshlrev_b32_e32 v60, 16, v164
	v_and_b32_e32 v61, 0xffff0000, v164
	v_lshlrev_b32_e32 v62, 16, v165
	v_and_b32_e32 v63, 0xffff0000, v165
	v_fma_f32 v47, v15, v250, v31
	v_fma_f32 v46, v14, v47, v30
	v_fma_f32 v45, v13, v46, v29
	v_fma_f32 v44, v12, v45, v28
	v_fma_f32 v43, v11, v44, v27
	v_fma_f32 v42, v10, v43, v26
	v_fma_f32 v41, v9, v42, v25
	v_fma_f32 v40, v8, v41, v24
	v_fma_f32 v39, v7, v40, v23
	v_fma_f32 v38, v6, v39, v22
	v_fma_f32 v37, v5, v38, v21
	v_fma_f32 v36, v4, v37, v20
	v_fma_f32 v35, v3, v36, v19
	v_fma_f32 v34, v2, v35, v18
	v_fma_f32 v33, v1, v34, v17
	v_fma_f32 v32, v0, v33, v16
	v_mov_b32_e32 v250, v32
	v_pk_add_f32 v[32:33], v[48:49], v[32:33]
	v_pk_add_f32 v[34:35], v[50:51], v[34:35]
	v_pk_add_f32 v[36:37], v[52:53], v[36:37]
	v_pk_add_f32 v[38:39], v[54:55], v[38:39]
	v_pk_add_f32 v[40:41], v[56:57], v[40:41]
	v_pk_add_f32 v[42:43], v[58:59], v[42:43]
	v_pk_add_f32 v[44:45], v[60:61], v[44:45]
	v_pk_add_f32 v[46:47], v[62:63], v[46:47]
	v_pk_mul_f32 v[32:33], v[206:207], v[32:33]
	v_pk_mul_f32 v[34:35], v[208:209], v[34:35]
	v_pk_mul_f32 v[36:37], v[210:211], v[36:37]
	v_pk_mul_f32 v[38:39], v[212:213], v[38:39]
	v_pk_mul_f32 v[40:41], v[214:215], v[40:41]
	v_pk_mul_f32 v[42:43], v[216:217], v[42:43]
	v_pk_mul_f32 v[44:45], v[218:219], v[44:45]
	v_pk_mul_f32 v[46:47], v[222:223], v[46:47]
	v_cvt_pk_bf16_f32 v32, v32, v33
	v_cvt_pk_bf16_f32 v34, v34, v35
	v_cvt_pk_bf16_f32 v36, v36, v37
	v_cvt_pk_bf16_f32 v38, v38, v39
	v_cvt_pk_bf16_f32 v40, v40, v41
	v_cvt_pk_bf16_f32 v42, v42, v43
	v_cvt_pk_bf16_f32 v44, v44, v45
	v_cvt_pk_bf16_f32 v46, v46, v47
	global_store_short_d16_hi v234, v46, s[90:91] offset:2048
	global_store_short v234, v46, s[90:91]
	s_sub_u32 s90, s90, 0x1000
	s_subb_u32 s91, s91, 0
	global_store_short_d16_hi v234, v44, s[90:91] offset:2048
	global_store_short v234, v44, s[90:91]
	s_sub_u32 s90, s90, 0x1000
	s_subb_u32 s91, s91, 0
	global_store_short_d16_hi v234, v42, s[90:91] offset:2048
	global_store_short v234, v42, s[90:91]
	s_sub_u32 s90, s90, 0x1000
	s_subb_u32 s91, s91, 0
	global_store_short_d16_hi v234, v40, s[90:91] offset:2048
	global_store_short v234, v40, s[90:91]
	s_sub_u32 s90, s90, 0x1000
	s_subb_u32 s91, s91, 0
	global_store_short_d16_hi v234, v38, s[90:91] offset:2048
	global_store_short v234, v38, s[90:91]
	s_sub_u32 s90, s90, 0x1000
	s_subb_u32 s91, s91, 0
	global_store_short_d16_hi v234, v36, s[90:91] offset:2048
	global_store_short v234, v36, s[90:91]
	s_sub_u32 s90, s90, 0x1000
	s_subb_u32 s91, s91, 0
	global_store_short_d16_hi v234, v34, s[90:91] offset:2048
	global_store_short v234, v34, s[90:91]
	s_sub_u32 s90, s90, 0x1000
	s_subb_u32 s91, s91, 0
	global_store_short_d16_hi v234, v32, s[90:91] offset:2048
	global_store_short v234, v32, s[90:91]
	s_waitcnt lgkmcnt(0)
	v_readlane_b32 s84, v253, 29
	s_add_i32 s12, s12, s84
	s_cmpk_lt_i32 s12, 0x1000
	s_cbranch_scc1 .Lrg7_keep
	s_sub_i32 s0, s12, 0x1000
	s_lshr_b32 s1, s0, 5
	s_and_b32 s0, s0, 31
	s_and_b32 s12, s1, 7
	s_add_i32 s1, s1, 0x1000
	s_cmp_eq_u32 s0, s12
	s_cselect_b32 s12, s1, 0x2000
